# role-split software-pipelined k-loops for X, B1 and A units: waves 0-3 issue all LDS-DMA with SALU-only addressing, waves 4-7 MFMA only
# speedup vs baseline: 1.0450x; 1.0450x over previous
; template <int N> DI void wait_vm() { asm volatile("s_waitcnt vmcnt(%0)" ::"n"(N) : "memory"); }
;     ...
; #pragma unroll
;     for (int mt = 0; mt < MT; ++mt)
; #pragma unroll
;         for (int nt = 0; nt < NT; ++nt) acc[mt][nt] = (f32x4){0.f, 0.f, 0.f, 0.f};
;     const unsigned loff = (unsigned)(lrow * 64 + lcg * 16);
;     const int koff = (int)((blockIdx.x >> 3) + (blockIdx.x & 7) * 4) & (KT - 1);
;     auto issue_one = [&](int kt, int b, int i) {
;         const int row = lrow + 128 * i;
;         if ((NCH % 512 == 0) || (i < NCH / 512) || row < ROWS) {
;             const int kq = (kt + koff) & (KT - 1);
;             const char* ua = (const char*)A + (size_t)((DBG & 1) ? 0 : kq) * (BM * 64);
;             const char* ub = (const char*)Bt + (size_t)((DBG & 2) ? 0 : kq) * ((size_t)ldbk * 2);
;             const char* src;
;             if (BM % 128 == 0) src = (i < BM / 128) ? (ua + i * 8192 + loff) : (ub + (i * 128 - BM) * 64 + loff);
;             else if (i == 0) src = (lrow < BM) ? (ua + loff) : (ub + loff - BM * 64);
;             else src = ub + (i * 128 - BM) * 64 + loff;
;             __builtin_amdgcn_global_load_lds((const unsigned*)src, (unsigned*)(lds + b * BUF + i * 8192 + tid * 16), 16, 0, 0);
;         }
;     };
;     auto issue = [&](int kt, int b) {
; #pragma unroll
;         for (int i = 0; i < NIT; ++i) issue_one(kt, b, i);
;     ...
;     __syncthreads();
; #pragma unroll
;     for (int d = 0; d < D; ++d) issue(d, d);
;     int cb = 0, ib = D;
;     for (int kt = 0; kt < KT; ++kt) {
;         if (D > 1 && kt + D - 1 < KT) wait_vm<(D - 1) * NIT>(); else wait_vm<0>();
.LBB0_740:
	s_and_b64 vcc, exec, s[6:7]
	s_cbranch_vccz .LBB0_824
	v_mov_b32_e32 v137, v212
	v_mov_b32_e32 v4, v212
	s_lshl_b32 s0, s40, 5
	v_ashrrev_i32_e32 v5, 6, v4
	v_lshrrev_b32_e32 v0, 30, v5
	v_add_u32_e32 v0, v5, v0
	v_ashrrev_i32_e32 v6, 2, v0
	v_lshrrev_b32_e32 v0, 4, v4
	s_or_b32 s8, s0, s73
	v_sub_u32_e32 v0, 0, v0
	v_lshlrev_b32_e32 v2, 2, v4
	s_lshl_b32 s13, s8, 7
	s_lshl_b32 s0, s8, 18
	v_readlane_b32 s1, v243, 56
	v_and_b32_e32 v2, 48, v2
	v_xor_b32_e32 v0, v4, v0
	v_lshlrev_b32_e32 v8, 4, v4
	s_add_u32 s10, s1, s0
	v_readlane_b32 s0, v243, 40
	v_sub_u32_e32 v7, 0, v2
	v_and_b32_e32 v2, 0xffffffc0, v8
	v_lshlrev_b32_e32 v0, 4, v0
	s_addc_u32 s11, s0, 0
	v_and_or_b32 v0, v0, 48, v2
	v_lshl_add_u64 v[130:131], s[10:11], 0, v[0:1]
	v_readlane_b32 s10, v243, 25
	v_add_u32_e32 v134, 0, v8
	v_readlane_b32 s11, v243, 26
	v_readfirstlane_b32 s7, v134
	s_mov_b32 m0, s7
	v_lshl_add_u64 v[2:3], v[130:131], 0, s[10:11]
	s_barrier
	global_load_lds_dwordx4 v[2:3], off
	v_add_u32_e32 v2, 0x2000, v134
	v_readlane_b32 s10, v242, 7
	v_readfirstlane_b32 s7, v2
	s_mov_b32 m0, s7
	v_readlane_b32 s11, v242, 8
	v_add_u32_e32 v2, 0x4000, v134
	v_add_u32_e32 v9, 0xa000, v134
	v_readfirstlane_b32 s7, v2
	v_add_u32_e32 v2, 0x6000, v134
	s_add_i32 s12, 0, 0x10000
	global_load_lds_dwordx4 v0, s[10:11]
	v_readlane_b32 s10, v242, 3
	s_mov_b32 m0, s7
	v_readlane_b32 s11, v242, 4
	v_readfirstlane_b32 s7, v2
	v_add_u32_e32 v2, 0x8000, v134
	s_mov_b32 s1, 2
	s_mov_b32 s0, 4
	s_mov_b32 s6, 0
	global_load_lds_dwordx4 v0, s[10:11]
	v_readlane_b32 s10, v242, 5
	s_mov_b32 m0, s7
	v_readlane_b32 s11, v242, 6
	v_readfirstlane_b32 s7, v2
	v_lshl_add_u64 v[132:133], s[50:51], 0, v[0:1]
	s_nop 2
	global_load_lds_dwordx4 v0, s[10:11]
	v_readlane_b32 s10, v242, 9
	s_mov_b32 m0, s7
	v_readlane_b32 s11, v242, 10
	v_readfirstlane_b32 s7, v9
	s_nop 3
	global_load_lds_dwordx4 v0, s[10:11]
	v_readlane_b32 s10, v243, 5
	v_readlane_b32 s11, v243, 6
	s_mov_b32 m0, s7
	s_nop 0
	v_lshl_add_u64 v[2:3], v[130:131], 0, s[10:11]
	global_load_lds_dwordx4 v[2:3], off
	v_add_u32_e32 v2, 0xc000, v134
	v_readlane_b32 s10, v242, 15
	v_readfirstlane_b32 s7, v2
	s_mov_b32 m0, s7
	v_readlane_b32 s11, v242, 16
	v_add_u32_e32 v2, 0xe000, v134
	v_bitop3_b32 v3, v4, 48, v7 bitop3:0x48
	v_readfirstlane_b32 s7, v2
	v_add_u32_e32 v2, s12, v8
	v_add_u32_e32 v135, 0, v3
	global_load_lds_dwordx4 v0, s[10:11]
	v_readlane_b32 s10, v242, 11
	s_mov_b32 m0, s7
	v_readlane_b32 s11, v242, 12
	v_readfirstlane_b32 s7, v2
	v_lshlrev_b32_e32 v3, 6, v4
	v_and_b32_e32 v3, 0x3c0, v3
	v_lshl_or_b32 v136, v6, 12, v3
	s_nop 0
	global_load_lds_dwordx4 v0, s[10:11]
	s_mov_b32 m0, s7
	v_readlane_b32 s10, v242, 13
	v_readlane_b32 s7, v243, 31
	v_readlane_b32 s11, v242, 14
	s_nop 0
	v_add_u32_e32 v2, s7, v8
	s_nop 0
	v_readfirstlane_b32 s7, v2
	v_mul_i32_i24_e32 v2, 4, v6
	global_load_lds_dwordx4 v0, s[10:11]
	v_readlane_b32 s10, v242, 17
	s_mov_b32 m0, s7
	v_readlane_b32 s11, v242, 18
	v_sub_u32_e32 v2, v5, v2
	v_lshl_or_b32 v138, v2, 13, v3
	v_mov_b32_e32 v2, 0
	v_readlane_b32 s7, v243, 24
	v_mov_b32_e32 v3, v2
	global_load_lds_dwordx4 v0, s[10:11]
	v_mov_b32_e32 v4, v2
	v_mov_b32_e32 v5, v2
	v_mov_b32_e32 v6, v2
	v_mov_b32_e32 v7, v2
	v_mov_b32_e32 v8, v2
	v_mov_b32_e32 v9, v2
	v_mov_b32_e32 v10, v2
	v_mov_b32_e32 v11, v2
	v_mov_b32_e32 v12, v2
	v_mov_b32_e32 v13, v2
	v_mov_b32_e32 v14, v2
	v_mov_b32_e32 v15, v2
	v_mov_b32_e32 v16, v2
	v_mov_b32_e32 v17, v2
	v_mov_b32_e32 v18, v2
	v_mov_b32_e32 v19, v2
	v_mov_b32_e32 v20, v2
	v_mov_b32_e32 v21, v2
	v_mov_b32_e32 v22, v2
	v_mov_b32_e32 v23, v2
	v_mov_b32_e32 v24, v2
	v_mov_b32_e32 v25, v2
	v_mov_b32_e32 v26, v2
	v_mov_b32_e32 v27, v2
	v_mov_b32_e32 v28, v2
	v_mov_b32_e32 v29, v2
	v_mov_b32_e32 v30, v2
	v_mov_b32_e32 v31, v2
	v_mov_b32_e32 v32, v2
	v_mov_b32_e32 v33, v2
	v_mov_b32_e32 v34, v2
	v_mov_b32_e32 v35, v2
	v_mov_b32_e32 v36, v2
	v_mov_b32_e32 v37, v2
	v_mov_b32_e32 v38, v2
	v_mov_b32_e32 v39, v2
	v_mov_b32_e32 v40, v2
	v_mov_b32_e32 v41, v2
	v_mov_b32_e32 v42, v2
	v_mov_b32_e32 v43, v2
	v_mov_b32_e32 v44, v2
	v_mov_b32_e32 v45, v2
	v_mov_b32_e32 v46, v2
	v_mov_b32_e32 v47, v2
	v_mov_b32_e32 v48, v2
	v_mov_b32_e32 v49, v2
	v_mov_b32_e32 v50, v2
	v_mov_b32_e32 v51, v2
	v_mov_b32_e32 v52, v2
	v_mov_b32_e32 v53, v2
	v_mov_b32_e32 v54, v2
	v_mov_b32_e32 v55, v2
	v_mov_b32_e32 v56, v2
	v_mov_b32_e32 v57, v2
	v_mov_b32_e32 v58, v2
	v_mov_b32_e32 v59, v2
	v_mov_b32_e32 v60, v2
	v_mov_b32_e32 v61, v2
	v_mov_b32_e32 v62, v2
	v_mov_b32_e32 v63, v2
	v_mov_b32_e32 v64, v2
	v_mov_b32_e32 v65, v2
	v_mov_b32_e32 v66, v2
	v_mov_b32_e32 v67, v2
	v_mov_b32_e32 v68, v2
	v_mov_b32_e32 v69, v2
	v_mov_b32_e32 v70, v2
	v_mov_b32_e32 v71, v2
	v_mov_b32_e32 v72, v2
	v_mov_b32_e32 v73, v2
	v_mov_b32_e32 v74, v2
	v_mov_b32_e32 v75, v2
	v_mov_b32_e32 v76, v2
	v_mov_b32_e32 v77, v2
	v_mov_b32_e32 v78, v2
	v_mov_b32_e32 v79, v2
	v_mov_b32_e32 v80, v2
	v_mov_b32_e32 v81, v2
	v_mov_b32_e32 v82, v2
	v_mov_b32_e32 v83, v2
	v_mov_b32_e32 v84, v2
	v_mov_b32_e32 v85, v2
	v_mov_b32_e32 v86, v2
	v_mov_b32_e32 v87, v2
	v_mov_b32_e32 v88, v2
	v_mov_b32_e32 v89, v2
	v_mov_b32_e32 v90, v2
	v_mov_b32_e32 v91, v2
	v_mov_b32_e32 v92, v2
	v_mov_b32_e32 v93, v2
	v_mov_b32_e32 v94, v2
	v_mov_b32_e32 v95, v2
	v_mov_b32_e32 v96, v2
	v_mov_b32_e32 v97, v2
	v_mov_b32_e32 v98, v2
	v_mov_b32_e32 v99, v2
	v_mov_b32_e32 v100, v2
	v_mov_b32_e32 v101, v2
	v_mov_b32_e32 v102, v2
	v_mov_b32_e32 v103, v2
	v_mov_b32_e32 v104, v2
	v_mov_b32_e32 v105, v2
	v_mov_b32_e32 v106, v2
	v_mov_b32_e32 v107, v2
	v_mov_b32_e32 v108, v2
	v_mov_b32_e32 v109, v2
	v_mov_b32_e32 v110, v2
	v_mov_b32_e32 v111, v2
	v_mov_b32_e32 v112, v2
	v_mov_b32_e32 v113, v2
	v_mov_b32_e32 v114, v2
	v_mov_b32_e32 v115, v2
	s_waitcnt lgkmcnt(0)
	v_mov_b32_e32 v116, v2
	v_mov_b32_e32 v117, v2
	v_mov_b32_e32 v118, v2
	v_mov_b32_e32 v119, v2
	v_mov_b32_e32 v120, v2
	v_mov_b32_e32 v121, v2
	v_mov_b32_e32 v122, v2
	v_mov_b32_e32 v123, v2
	v_mov_b32_e32 v124, v2
	v_mov_b32_e32 v125, v2
	v_mov_b32_e32 v126, v2
	v_mov_b32_e32 v127, v2
	v_mov_b32_e32 v128, v2
	v_mov_b32_e32 v129, v2
	v_readfirstlane_b32 s9, v212
	s_nop 3
	s_cmp_lt_u32 s9, 0x100
	s_cbranch_scc0 .Lpx_c_entry
; DI f32x4 mfma16(bf16x8 a, bf16x8 b, f32x4 c) { return __builtin_amdgcn_mfma_f32_16x16x32_bf16(a, b, c, 0, 0, 0); }
; template <int N> DI void wait_vm() { asm volatile("s_waitcnt vmcnt(%0)" ::"n"(N) : "memory"); }
; DI void raw_barrier() { asm volatile("" ::: "memory"); __builtin_amdgcn_s_barrier(); asm volatile("" ::: "memory"); }
;     ...
;     auto compute = [&](int cb, bool do_issue, int ikt, int ib) {
;         const char* base = lds + cb * BUF;
;         bf16x8 af[MT], bfr[NT];
; #pragma unroll
;         for (int nt = 0; nt < NT; ++nt) {
;             const int br = BM + (nt / NTS) * (BN / NSEG) + wc * (NTS * 16) + (nt % NTS) * 16;
;             bfr[nt] = *(const bf16x8*)(base + (br + l15) * 64 + rsw);
;         }
; #pragma unroll
;         for (int mt = 0; mt < MT; ++mt) af[mt] = *(const bf16x8*)(base + (wr * WM + mt * 16 + l15) * 64 + rsw);
;         constexpr int TOT = MT * NT, PER = (TOT + NIT - 1) / NIT;
; #pragma unroll
;         for (int part = 0; part < NIT; ++part) {
; #pragma unroll
;             for (int q = 0; q < PER; ++q) {
;                 const int idx = part * PER + q;
;                 if (idx < TOT) {
;                     const int mt = idx / NT, nt = idx % NT;
;                     acc[mt][nt] = SWAP ? mfma16(bfr[nt], af[mt], acc[mt][nt]) : mfma16(af[mt], bfr[nt], acc[mt][nt]);
;                 }
;             }
;             __builtin_amdgcn_sched_barrier(0);
;             if (do_issue) issue_one(ikt, ib, part);
;             __builtin_amdgcn_sched_barrier(0);
;         }
;     };
;     __syncthreads();
; #pragma unroll
;     for (int d = 0; d < D; ++d) issue(d, d);
;     int cb = 0, ib = D;
;     for (int kt = 0; kt < KT; ++kt) {
;         if (D > 1 && kt + D - 1 < KT) wait_vm<(D - 1) * NIT>(); else wait_vm<0>();
;         raw_barrier();
;         compute(cb, kt + D < KT, kt + D, ib);
;         cb = (cb + 1 == NST) ? 0 : cb + 1;
;         ib = (ib + 1 == NST) ? 0 : ib + 1;
;     }
	s_lshl_b32 s7, s9, 5
	s_lshl_b32 s40, s9, 4
	v_add_u32_e32 v227, s40, v0
	v_readfirstlane_b32 s10, v130
	v_readfirstlane_b32 s11, v131
	v_readfirstlane_b32 s40, v0
	s_nop 3
	s_sub_u32 vcc_lo, s10, s40
	s_subb_u32 vcc_hi, s11, 0
	s_mul_i32 s10, s1, 0xa000
	s_add_u32 s10, s10, s7
	s_mov_b32 m0, s10
	s_add_i32 s40, s59, s0
	s_and_b32 s40, s40, 62
	s_lshl_b32 s10, s40, 12
	s_add_u32 s10, vcc_lo, s10
	s_addc_u32 s11, vcc_hi, 0
	s_mul_i32 s40, s40, 0x14000
	global_load_lds_dwordx4 v227, s[10:11]
	global_load_lds_dwordx4 v227, s[10:11] offset:1024
	s_add_u32 s10, s50, s40
	s_addc_u32 s11, s51, 0
	s_add_u32 m0, m0, 0x2000
	s_nop 0
	global_load_lds_dwordx4 v227, s[10:11]
	global_load_lds_dwordx4 v227, s[10:11] offset:1024
	s_add_u32 s10, s10, 0x2000
	s_addc_u32 s11, s11, 0
	s_add_u32 m0, m0, 0x2000
	s_nop 0
	global_load_lds_dwordx4 v227, s[10:11]
	global_load_lds_dwordx4 v227, s[10:11] offset:1024
	s_add_u32 s10, s10, 0x2000
	s_addc_u32 s11, s11, 0
	s_add_u32 m0, m0, 0x2000
	s_nop 0
	global_load_lds_dwordx4 v227, s[10:11]
	global_load_lds_dwordx4 v227, s[10:11] offset:1024
	s_add_u32 s10, s10, 0x2000
	s_addc_u32 s11, s11, 0
	s_add_u32 m0, m0, 0x2000
	s_nop 0
	global_load_lds_dwordx4 v227, s[10:11]
	global_load_lds_dwordx4 v227, s[10:11] offset:1024
	s_add_i32 s0, s0, 2
	s_mov_b32 s1, 0
	s_mov_b32 s6, 1
	s_waitcnt vmcnt(15)
	s_barrier
	v_add_u32_e32 v225, v135, v138
	v_add_u32_e32 v224, v135, v136
	ds_read_b128 v[144:147], v224
	ds_read_b128 v[152:155], v224 offset:1024
	ds_read_b128 v[180:183], v224 offset:2048
	ds_read_b128 v[140:143], v225 offset:8192
	ds_read_b128 v[148:151], v225 offset:9216
	ds_read_b128 v[156:159], v225 offset:10240
	ds_read_b128 v[160:163], v225 offset:11264
	ds_read_b128 v[164:167], v225 offset:12288
	ds_read_b128 v[168:171], v225 offset:13312
	ds_read_b128 v[172:175], v225 offset:14336
	ds_read_b128 v[176:179], v225 offset:15360
	ds_read_b128 v[184:187], v224 offset:3072
.Lpx_l_loop:
	s_mul_i32 s9, s6, 0xa000
	v_add_u32_e32 v226, s9, v135
	v_add_u32_e32 v225, v226, v138
	v_add_u32_e32 v224, v226, v136
	s_waitcnt lgkmcnt(8)
	v_mfma_f32_16x16x32_bf16 v[126:129], v[140:143], v[144:147], v[126:129]
	s_waitcnt lgkmcnt(7)
	v_mfma_f32_16x16x32_bf16 v[122:125], v[148:151], v[144:147], v[122:125]
	s_waitcnt lgkmcnt(6)
	v_mfma_f32_16x16x32_bf16 v[118:121], v[156:159], v[144:147], v[118:121]
	s_waitcnt lgkmcnt(5)
	v_mfma_f32_16x16x32_bf16 v[114:117], v[160:163], v[144:147], v[114:117]
	s_waitcnt lgkmcnt(4)
	v_mfma_f32_16x16x32_bf16 v[110:113], v[164:167], v[144:147], v[110:113]
	s_waitcnt lgkmcnt(3)
	v_mfma_f32_16x16x32_bf16 v[106:109], v[168:171], v[144:147], v[106:109]
	s_waitcnt lgkmcnt(2)
	v_mfma_f32_16x16x32_bf16 v[102:105], v[172:175], v[144:147], v[102:105]
	s_waitcnt lgkmcnt(1)
	v_mfma_f32_16x16x32_bf16 v[98:101], v[176:179], v[144:147], v[98:101]
	s_waitcnt vmcnt(10) lgkmcnt(0)
	s_barrier
	ds_read_b128 v[144:147], v224
	s_mul_i32 s10, s1, 0xa000
	s_add_u32 s10, s10, s7
	s_mov_b32 m0, s10
	s_add_i32 s40, s59, s0
	s_and_b32 s40, s40, 62
	s_lshl_b32 s10, s40, 12
	s_add_u32 s10, vcc_lo, s10
	s_addc_u32 s11, vcc_hi, 0
	s_mul_i32 s40, s40, 0x14000
	global_load_lds_dwordx4 v227, s[10:11]
	global_load_lds_dwordx4 v227, s[10:11] offset:1024
	v_mfma_f32_16x16x32_bf16 v[94:97], v[140:143], v[152:155], v[94:97]
	v_mfma_f32_16x16x32_bf16 v[90:93], v[148:151], v[152:155], v[90:93]
	v_mfma_f32_16x16x32_bf16 v[86:89], v[156:159], v[152:155], v[86:89]
	v_mfma_f32_16x16x32_bf16 v[82:85], v[160:163], v[152:155], v[82:85]
	v_mfma_f32_16x16x32_bf16 v[78:81], v[164:167], v[152:155], v[78:81]
	s_add_u32 s10, s50, s40
	s_addc_u32 s11, s51, 0
	s_add_u32 m0, m0, 0x2000
	s_nop 0
	global_load_lds_dwordx4 v227, s[10:11]
	global_load_lds_dwordx4 v227, s[10:11] offset:1024
	v_mfma_f32_16x16x32_bf16 v[74:77], v[168:171], v[152:155], v[74:77]
	v_mfma_f32_16x16x32_bf16 v[70:73], v[172:175], v[152:155], v[70:73]
	v_mfma_f32_16x16x32_bf16 v[66:69], v[176:179], v[152:155], v[66:69]
	ds_read_b128 v[152:155], v224 offset:1024
	v_mfma_f32_16x16x32_bf16 v[62:65], v[140:143], v[180:183], v[62:65]
	v_mfma_f32_16x16x32_bf16 v[58:61], v[148:151], v[180:183], v[58:61]
	s_add_u32 s10, s10, 0x2000
	s_addc_u32 s11, s11, 0
	s_add_u32 m0, m0, 0x2000
	s_nop 0
	global_load_lds_dwordx4 v227, s[10:11]
	global_load_lds_dwordx4 v227, s[10:11] offset:1024
	v_mfma_f32_16x16x32_bf16 v[54:57], v[156:159], v[180:183], v[54:57]
	v_mfma_f32_16x16x32_bf16 v[50:53], v[160:163], v[180:183], v[50:53]
	v_mfma_f32_16x16x32_bf16 v[46:49], v[164:167], v[180:183], v[46:49]
	v_mfma_f32_16x16x32_bf16 v[42:45], v[168:171], v[180:183], v[42:45]
	s_add_u32 s10, s10, 0x2000
	s_addc_u32 s11, s11, 0
	s_add_u32 m0, m0, 0x2000
	s_nop 0
	global_load_lds_dwordx4 v227, s[10:11]
	global_load_lds_dwordx4 v227, s[10:11] offset:1024
	v_mfma_f32_16x16x32_bf16 v[38:41], v[172:175], v[180:183], v[38:41]
	v_mfma_f32_16x16x32_bf16 v[34:37], v[176:179], v[180:183], v[34:37]
	ds_read_b128 v[180:183], v224 offset:2048
	v_mfma_f32_16x16x32_bf16 v[30:33], v[140:143], v[184:187], v[30:33]
	ds_read_b128 v[140:143], v225 offset:8192
	v_mfma_f32_16x16x32_bf16 v[26:29], v[148:151], v[184:187], v[26:29]
	ds_read_b128 v[148:151], v225 offset:9216
	v_mfma_f32_16x16x32_bf16 v[22:25], v[156:159], v[184:187], v[22:25]
	ds_read_b128 v[156:159], v225 offset:10240
	s_add_u32 s10, s10, 0x2000
	s_addc_u32 s11, s11, 0
	s_add_u32 m0, m0, 0x2000
	s_nop 0
	global_load_lds_dwordx4 v227, s[10:11]
	global_load_lds_dwordx4 v227, s[10:11] offset:1024
	v_mfma_f32_16x16x32_bf16 v[18:21], v[160:163], v[184:187], v[18:21]
	ds_read_b128 v[160:163], v225 offset:11264
	v_mfma_f32_16x16x32_bf16 v[14:17], v[164:167], v[184:187], v[14:17]
	ds_read_b128 v[164:167], v225 offset:12288
	v_mfma_f32_16x16x32_bf16 v[10:13], v[168:171], v[184:187], v[10:13]
	ds_read_b128 v[168:171], v225 offset:13312
	v_mfma_f32_16x16x32_bf16 v[6:9], v[172:175], v[184:187], v[6:9]
	ds_read_b128 v[172:175], v225 offset:14336
	v_mfma_f32_16x16x32_bf16 v[2:5], v[176:179], v[184:187], v[2:5]
	ds_read_b128 v[176:179], v225 offset:15360
	ds_read_b128 v[184:187], v224 offset:3072
	s_add_i32 s6, s6, 1
	s_cmp_lg_u32 s6, 3
	s_cselect_b32 s6, s6, 0
	s_add_i32 s1, s1, 1
	s_cmp_lg_u32 s1, 3
	s_cselect_b32 s1, s1, 0
	s_add_i32 s0, s0, 2
	s_cmp_lg_u32 s0, 64
	s_cbranch_scc1 .Lpx_l_loop
; DI f32x4 mfma16(bf16x8 a, bf16x8 b, f32x4 c) { return __builtin_amdgcn_mfma_f32_16x16x32_bf16(a, b, c, 0, 0, 0); }
; template <int N> DI void wait_vm() { asm volatile("s_waitcnt vmcnt(%0)" ::"n"(N) : "memory"); }
; DI void raw_barrier() { asm volatile("" ::: "memory"); __builtin_amdgcn_s_barrier(); asm volatile("" ::: "memory"); }
;     ...
;     auto compute = [&](int cb, bool do_issue, int ikt, int ib) {
;         const char* base = lds + cb * BUF;
;         bf16x8 af[MT], bfr[NT];
; #pragma unroll
;         for (int nt = 0; nt < NT; ++nt) {
;             const int br = BM + (nt / NTS) * (BN / NSEG) + wc * (NTS * 16) + (nt % NTS) * 16;
;             bfr[nt] = *(const bf16x8*)(base + (br + l15) * 64 + rsw);
;         }
; #pragma unroll
;         for (int mt = 0; mt < MT; ++mt) af[mt] = *(const bf16x8*)(base + (wr * WM + mt * 16 + l15) * 64 + rsw);
;         constexpr int TOT = MT * NT, PER = (TOT + NIT - 1) / NIT;
; #pragma unroll
;         for (int part = 0; part < NIT; ++part) {
; #pragma unroll
;             for (int q = 0; q < PER; ++q) {
;                 const int idx = part * PER + q;
;                 if (idx < TOT) {
;                     const int mt = idx / NT, nt = idx % NT;
;                     acc[mt][nt] = SWAP ? mfma16(bfr[nt], af[mt], acc[mt][nt]) : mfma16(af[mt], bfr[nt], acc[mt][nt]);
;                 }
;             }
;             __builtin_amdgcn_sched_barrier(0);
;             if (do_issue) issue_one(ikt, ib, part);
;             __builtin_amdgcn_sched_barrier(0);
;         }
;     };
;     __syncthreads();
; #pragma unroll
;     for (int d = 0; d < D; ++d) issue(d, d);
;     int cb = 0, ib = D;
;     for (int kt = 0; kt < KT; ++kt) {
;         if (D > 1 && kt + D - 1 < KT) wait_vm<(D - 1) * NIT>(); else wait_vm<0>();
;         raw_barrier();
;         compute(cb, kt + D < KT, kt + D, ib);
;         cb = (cb + 1 == NST) ? 0 : cb + 1;
;         ib = (ib + 1 == NST) ? 0 : ib + 1;
;     }
	s_waitcnt lgkmcnt(8)
	v_mfma_f32_16x16x32_bf16 v[126:129], v[140:143], v[144:147], v[126:129]
	s_waitcnt lgkmcnt(7)
	v_mfma_f32_16x16x32_bf16 v[122:125], v[148:151], v[144:147], v[122:125]
	s_waitcnt lgkmcnt(6)
	v_mfma_f32_16x16x32_bf16 v[118:121], v[156:159], v[144:147], v[118:121]
	s_waitcnt lgkmcnt(5)
	v_mfma_f32_16x16x32_bf16 v[114:117], v[160:163], v[144:147], v[114:117]
	s_waitcnt lgkmcnt(4)
	v_mfma_f32_16x16x32_bf16 v[110:113], v[164:167], v[144:147], v[110:113]
	s_waitcnt lgkmcnt(3)
	v_mfma_f32_16x16x32_bf16 v[106:109], v[168:171], v[144:147], v[106:109]
	s_waitcnt lgkmcnt(2)
	v_mfma_f32_16x16x32_bf16 v[102:105], v[172:175], v[144:147], v[102:105]
	s_waitcnt lgkmcnt(1)
	v_mfma_f32_16x16x32_bf16 v[98:101], v[176:179], v[144:147], v[98:101]
	s_waitcnt lgkmcnt(0)
	v_mfma_f32_16x16x32_bf16 v[94:97], v[140:143], v[152:155], v[94:97]
	v_mfma_f32_16x16x32_bf16 v[90:93], v[148:151], v[152:155], v[90:93]
	v_mfma_f32_16x16x32_bf16 v[86:89], v[156:159], v[152:155], v[86:89]
	v_mfma_f32_16x16x32_bf16 v[82:85], v[160:163], v[152:155], v[82:85]
	v_mfma_f32_16x16x32_bf16 v[78:81], v[164:167], v[152:155], v[78:81]
	v_mfma_f32_16x16x32_bf16 v[74:77], v[168:171], v[152:155], v[74:77]
	v_mfma_f32_16x16x32_bf16 v[70:73], v[172:175], v[152:155], v[70:73]
	v_mfma_f32_16x16x32_bf16 v[66:69], v[176:179], v[152:155], v[66:69]
	v_mfma_f32_16x16x32_bf16 v[62:65], v[140:143], v[180:183], v[62:65]
	v_mfma_f32_16x16x32_bf16 v[58:61], v[148:151], v[180:183], v[58:61]
	v_mfma_f32_16x16x32_bf16 v[54:57], v[156:159], v[180:183], v[54:57]
	v_mfma_f32_16x16x32_bf16 v[50:53], v[160:163], v[180:183], v[50:53]
	v_mfma_f32_16x16x32_bf16 v[46:49], v[164:167], v[180:183], v[46:49]
	v_mfma_f32_16x16x32_bf16 v[42:45], v[168:171], v[180:183], v[42:45]
	v_mfma_f32_16x16x32_bf16 v[38:41], v[172:175], v[180:183], v[38:41]
	v_mfma_f32_16x16x32_bf16 v[34:37], v[176:179], v[180:183], v[34:37]
	v_mfma_f32_16x16x32_bf16 v[30:33], v[140:143], v[184:187], v[30:33]
	v_mfma_f32_16x16x32_bf16 v[26:29], v[148:151], v[184:187], v[26:29]
	v_mfma_f32_16x16x32_bf16 v[22:25], v[156:159], v[184:187], v[22:25]
	v_mfma_f32_16x16x32_bf16 v[18:21], v[160:163], v[184:187], v[18:21]
	v_mfma_f32_16x16x32_bf16 v[14:17], v[164:167], v[184:187], v[14:17]
	v_mfma_f32_16x16x32_bf16 v[10:13], v[168:171], v[184:187], v[10:13]
	v_mfma_f32_16x16x32_bf16 v[6:9], v[172:175], v[184:187], v[6:9]
	v_mfma_f32_16x16x32_bf16 v[2:5], v[176:179], v[184:187], v[2:5]
	s_branch .Lpx_join
.Lpx_c_entry:
	s_add_i32 s0, s0, 2
	s_mov_b32 s6, 1
	s_waitcnt vmcnt(5)
	s_barrier
	v_add_u32_e32 v225, v135, v138
	v_add_u32_e32 v224, v135, v136
	ds_read_b128 v[144:147], v224
	ds_read_b128 v[152:155], v224 offset:1024
	ds_read_b128 v[180:183], v224 offset:2048
	ds_read_b128 v[140:143], v225 offset:8192
	ds_read_b128 v[148:151], v225 offset:9216
	ds_read_b128 v[156:159], v225 offset:10240
	ds_read_b128 v[160:163], v225 offset:11264
	ds_read_b128 v[164:167], v225 offset:12288
	ds_read_b128 v[168:171], v225 offset:13312
	ds_read_b128 v[172:175], v225 offset:14336
	ds_read_b128 v[176:179], v225 offset:15360
	ds_read_b128 v[184:187], v224 offset:3072
.Lpx_c_loop:
	s_mul_i32 s9, s6, 0xa000
	v_add_u32_e32 v226, s9, v135
	v_add_u32_e32 v225, v226, v138
	v_add_u32_e32 v224, v226, v136
	s_waitcnt lgkmcnt(8)
	v_mfma_f32_16x16x32_bf16 v[126:129], v[140:143], v[144:147], v[126:129]
	s_waitcnt lgkmcnt(7)
	v_mfma_f32_16x16x32_bf16 v[122:125], v[148:151], v[144:147], v[122:125]
	s_waitcnt lgkmcnt(6)
	v_mfma_f32_16x16x32_bf16 v[118:121], v[156:159], v[144:147], v[118:121]
	s_waitcnt lgkmcnt(5)
	v_mfma_f32_16x16x32_bf16 v[114:117], v[160:163], v[144:147], v[114:117]
	s_waitcnt lgkmcnt(4)
	v_mfma_f32_16x16x32_bf16 v[110:113], v[164:167], v[144:147], v[110:113]
	s_waitcnt lgkmcnt(3)
	v_mfma_f32_16x16x32_bf16 v[106:109], v[168:171], v[144:147], v[106:109]
	s_waitcnt lgkmcnt(2)
	v_mfma_f32_16x16x32_bf16 v[102:105], v[172:175], v[144:147], v[102:105]
	s_waitcnt lgkmcnt(1)
	v_mfma_f32_16x16x32_bf16 v[98:101], v[176:179], v[144:147], v[98:101]
	s_waitcnt vmcnt(0) lgkmcnt(0)
	s_barrier
	ds_read_b128 v[144:147], v224
	v_mfma_f32_16x16x32_bf16 v[94:97], v[140:143], v[152:155], v[94:97]
	v_mfma_f32_16x16x32_bf16 v[90:93], v[148:151], v[152:155], v[90:93]
	v_mfma_f32_16x16x32_bf16 v[86:89], v[156:159], v[152:155], v[86:89]
	v_mfma_f32_16x16x32_bf16 v[82:85], v[160:163], v[152:155], v[82:85]
	v_mfma_f32_16x16x32_bf16 v[78:81], v[164:167], v[152:155], v[78:81]
	v_mfma_f32_16x16x32_bf16 v[74:77], v[168:171], v[152:155], v[74:77]
	v_mfma_f32_16x16x32_bf16 v[70:73], v[172:175], v[152:155], v[70:73]
	v_mfma_f32_16x16x32_bf16 v[66:69], v[176:179], v[152:155], v[66:69]
	ds_read_b128 v[152:155], v224 offset:1024
	v_mfma_f32_16x16x32_bf16 v[62:65], v[140:143], v[180:183], v[62:65]
	v_mfma_f32_16x16x32_bf16 v[58:61], v[148:151], v[180:183], v[58:61]
	v_mfma_f32_16x16x32_bf16 v[54:57], v[156:159], v[180:183], v[54:57]
	v_mfma_f32_16x16x32_bf16 v[50:53], v[160:163], v[180:183], v[50:53]
	v_mfma_f32_16x16x32_bf16 v[46:49], v[164:167], v[180:183], v[46:49]
	v_mfma_f32_16x16x32_bf16 v[42:45], v[168:171], v[180:183], v[42:45]
	v_mfma_f32_16x16x32_bf16 v[38:41], v[172:175], v[180:183], v[38:41]
	v_mfma_f32_16x16x32_bf16 v[34:37], v[176:179], v[180:183], v[34:37]
	ds_read_b128 v[180:183], v224 offset:2048
	v_mfma_f32_16x16x32_bf16 v[30:33], v[140:143], v[184:187], v[30:33]
	ds_read_b128 v[140:143], v225 offset:8192
	v_mfma_f32_16x16x32_bf16 v[26:29], v[148:151], v[184:187], v[26:29]
	ds_read_b128 v[148:151], v225 offset:9216
	v_mfma_f32_16x16x32_bf16 v[22:25], v[156:159], v[184:187], v[22:25]
	ds_read_b128 v[156:159], v225 offset:10240
	v_mfma_f32_16x16x32_bf16 v[18:21], v[160:163], v[184:187], v[18:21]
	ds_read_b128 v[160:163], v225 offset:11264
	v_mfma_f32_16x16x32_bf16 v[14:17], v[164:167], v[184:187], v[14:17]
	ds_read_b128 v[164:167], v225 offset:12288
	v_mfma_f32_16x16x32_bf16 v[10:13], v[168:171], v[184:187], v[10:13]
	ds_read_b128 v[168:171], v225 offset:13312
	v_mfma_f32_16x16x32_bf16 v[6:9], v[172:175], v[184:187], v[6:9]
	ds_read_b128 v[172:175], v225 offset:14336
	v_mfma_f32_16x16x32_bf16 v[2:5], v[176:179], v[184:187], v[2:5]
	ds_read_b128 v[176:179], v225 offset:15360
	ds_read_b128 v[184:187], v224 offset:3072
	s_add_i32 s6, s6, 1
	s_cmp_lg_u32 s6, 3
	s_cselect_b32 s6, s6, 0
	s_add_i32 s0, s0, 2
	s_cmp_lg_u32 s0, 64
	s_cbranch_scc1 .Lpx_c_loop
; DI f32x4 mfma16(bf16x8 a, bf16x8 b, f32x4 c) { return __builtin_amdgcn_mfma_f32_16x16x32_bf16(a, b, c, 0, 0, 0); }
; template <int N> DI void wait_vm() { asm volatile("s_waitcnt vmcnt(%0)" ::"n"(N) : "memory"); }
; DI void raw_barrier() { asm volatile("" ::: "memory"); __builtin_amdgcn_s_barrier(); asm volatile("" ::: "memory"); }
;     ...
;     auto compute = [&](int cb, bool do_issue, int ikt, int ib) {
;         const char* base = lds + cb * BUF;
;         bf16x8 af[MT], bfr[NT];
; #pragma unroll
;         for (int nt = 0; nt < NT; ++nt) {
;             const int br = BM + (nt / NTS) * (BN / NSEG) + wc * (NTS * 16) + (nt % NTS) * 16;
;             bfr[nt] = *(const bf16x8*)(base + (br + l15) * 64 + rsw);
;         }
; #pragma unroll
;         for (int mt = 0; mt < MT; ++mt) af[mt] = *(const bf16x8*)(base + (wr * WM + mt * 16 + l15) * 64 + rsw);
;         constexpr int TOT = MT * NT, PER = (TOT + NIT - 1) / NIT;
; #pragma unroll
;         for (int part = 0; part < NIT; ++part) {
; #pragma unroll
;             for (int q = 0; q < PER; ++q) {
;                 const int idx = part * PER + q;
;                 if (idx < TOT) {
;                     const int mt = idx / NT, nt = idx % NT;
;                     acc[mt][nt] = SWAP ? mfma16(bfr[nt], af[mt], acc[mt][nt]) : mfma16(af[mt], bfr[nt], acc[mt][nt]);
;                 }
;             }
;             __builtin_amdgcn_sched_barrier(0);
;             if (do_issue) issue_one(ikt, ib, part);
;             __builtin_amdgcn_sched_barrier(0);
;         }
;     };
;     __syncthreads();
; #pragma unroll
;     for (int d = 0; d < D; ++d) issue(d, d);
;     int cb = 0, ib = D;
;     for (int kt = 0; kt < KT; ++kt) {
;         if (D > 1 && kt + D - 1 < KT) wait_vm<(D - 1) * NIT>(); else wait_vm<0>();
;         raw_barrier();
;         compute(cb, kt + D < KT, kt + D, ib);
;         cb = (cb + 1 == NST) ? 0 : cb + 1;
;         ib = (ib + 1 == NST) ? 0 : ib + 1;
;     }
	s_waitcnt lgkmcnt(8)
	v_mfma_f32_16x16x32_bf16 v[126:129], v[140:143], v[144:147], v[126:129]
	s_waitcnt lgkmcnt(7)
	v_mfma_f32_16x16x32_bf16 v[122:125], v[148:151], v[144:147], v[122:125]
	s_waitcnt lgkmcnt(6)
	v_mfma_f32_16x16x32_bf16 v[118:121], v[156:159], v[144:147], v[118:121]
	s_waitcnt lgkmcnt(5)
	v_mfma_f32_16x16x32_bf16 v[114:117], v[160:163], v[144:147], v[114:117]
	s_waitcnt lgkmcnt(4)
	v_mfma_f32_16x16x32_bf16 v[110:113], v[164:167], v[144:147], v[110:113]
	s_waitcnt lgkmcnt(3)
	v_mfma_f32_16x16x32_bf16 v[106:109], v[168:171], v[144:147], v[106:109]
	s_waitcnt lgkmcnt(2)
	v_mfma_f32_16x16x32_bf16 v[102:105], v[172:175], v[144:147], v[102:105]
	s_waitcnt lgkmcnt(1)
	v_mfma_f32_16x16x32_bf16 v[98:101], v[176:179], v[144:147], v[98:101]
	s_waitcnt lgkmcnt(0)
	v_mfma_f32_16x16x32_bf16 v[94:97], v[140:143], v[152:155], v[94:97]
	v_mfma_f32_16x16x32_bf16 v[90:93], v[148:151], v[152:155], v[90:93]
	v_mfma_f32_16x16x32_bf16 v[86:89], v[156:159], v[152:155], v[86:89]
	v_mfma_f32_16x16x32_bf16 v[82:85], v[160:163], v[152:155], v[82:85]
	v_mfma_f32_16x16x32_bf16 v[78:81], v[164:167], v[152:155], v[78:81]
	v_mfma_f32_16x16x32_bf16 v[74:77], v[168:171], v[152:155], v[74:77]
	v_mfma_f32_16x16x32_bf16 v[70:73], v[172:175], v[152:155], v[70:73]
	v_mfma_f32_16x16x32_bf16 v[66:69], v[176:179], v[152:155], v[66:69]
	v_mfma_f32_16x16x32_bf16 v[62:65], v[140:143], v[180:183], v[62:65]
	v_mfma_f32_16x16x32_bf16 v[58:61], v[148:151], v[180:183], v[58:61]
	v_mfma_f32_16x16x32_bf16 v[54:57], v[156:159], v[180:183], v[54:57]
	v_mfma_f32_16x16x32_bf16 v[50:53], v[160:163], v[180:183], v[50:53]
	v_mfma_f32_16x16x32_bf16 v[46:49], v[164:167], v[180:183], v[46:49]
	v_mfma_f32_16x16x32_bf16 v[42:45], v[168:171], v[180:183], v[42:45]
	v_mfma_f32_16x16x32_bf16 v[38:41], v[172:175], v[180:183], v[38:41]
	v_mfma_f32_16x16x32_bf16 v[34:37], v[176:179], v[180:183], v[34:37]
	v_mfma_f32_16x16x32_bf16 v[30:33], v[140:143], v[184:187], v[30:33]
	v_mfma_f32_16x16x32_bf16 v[26:29], v[148:151], v[184:187], v[26:29]
	v_mfma_f32_16x16x32_bf16 v[22:25], v[156:159], v[184:187], v[22:25]
	v_mfma_f32_16x16x32_bf16 v[18:21], v[160:163], v[184:187], v[18:21]
	v_mfma_f32_16x16x32_bf16 v[14:17], v[164:167], v[184:187], v[14:17]
	v_mfma_f32_16x16x32_bf16 v[10:13], v[168:171], v[184:187], v[10:13]
	v_mfma_f32_16x16x32_bf16 v[6:9], v[172:175], v[184:187], v[6:9]
	v_mfma_f32_16x16x32_bf16 v[2:5], v[176:179], v[184:187], v[2:5]
.Lpx_join:
	s_waitcnt vmcnt(5)
	s_barrier
	v_add_u32_e32 v0, v135, v138
	v_add_u32_e32 v134, v135, v136
	ds_read_b128 v[130:133], v0 offset:8192
	ds_read_b128 v[138:141], v134
	ds_read_b128 v[142:145], v0 offset:9216
	ds_read_b128 v[146:149], v134 offset:1024
	ds_read_b128 v[150:153], v0 offset:10240
	ds_read_b128 v[154:157], v0 offset:11264
	ds_read_b128 v[158:161], v0 offset:12288
	ds_read_b128 v[162:165], v0 offset:13312
	ds_read_b128 v[166:169], v0 offset:14336
	ds_read_b128 v[170:173], v0 offset:15360
	ds_read_b128 v[174:177], v134 offset:2048
	ds_read_b128 v[178:181], v134 offset:3072
	s_waitcnt lgkmcnt(0)
	v_mfma_f32_16x16x32_bf16 v[126:129], v[130:133], v[138:141], v[126:129]
	v_and_b32_e32 v135, 15, v137
	s_lshl_b32 s0, s13, 9
	v_mfma_f32_16x16x32_bf16 v[122:125], v[142:145], v[138:141], v[122:125]
	v_mfma_f32_16x16x32_bf16 v[118:121], v[150:153], v[138:141], v[118:121]
	v_mfma_f32_16x16x32_bf16 v[114:117], v[154:157], v[138:141], v[114:117]
	v_mfma_f32_16x16x32_bf16 v[110:113], v[158:161], v[138:141], v[110:113]
	v_mfma_f32_16x16x32_bf16 v[106:109], v[162:165], v[138:141], v[106:109]
	v_mfma_f32_16x16x32_bf16 v[102:105], v[166:169], v[138:141], v[102:105]
	v_mfma_f32_16x16x32_bf16 v[98:101], v[170:173], v[138:141], v[98:101]
	v_mfma_f32_16x16x32_bf16 v[94:97], v[130:133], v[146:149], v[94:97]
	v_mfma_f32_16x16x32_bf16 v[90:93], v[142:145], v[146:149], v[90:93]
	v_mfma_f32_16x16x32_bf16 v[86:89], v[150:153], v[146:149], v[86:89]
	v_mfma_f32_16x16x32_bf16 v[82:85], v[154:157], v[146:149], v[82:85]
	v_mfma_f32_16x16x32_bf16 v[78:81], v[158:161], v[146:149], v[78:81]
	v_mfma_f32_16x16x32_bf16 v[74:77], v[162:165], v[146:149], v[74:77]
	v_mfma_f32_16x16x32_bf16 v[70:73], v[166:169], v[146:149], v[70:73]
	v_mfma_f32_16x16x32_bf16 v[66:69], v[170:173], v[146:149], v[66:69]
	v_mfma_f32_16x16x32_bf16 v[62:65], v[130:133], v[174:177], v[62:65]
	v_mfma_f32_16x16x32_bf16 v[58:61], v[142:145], v[174:177], v[58:61]
	v_mfma_f32_16x16x32_bf16 v[54:57], v[150:153], v[174:177], v[54:57]
	v_mfma_f32_16x16x32_bf16 v[50:53], v[154:157], v[174:177], v[50:53]
	v_mfma_f32_16x16x32_bf16 v[46:49], v[158:161], v[174:177], v[46:49]
	v_mfma_f32_16x16x32_bf16 v[42:45], v[162:165], v[174:177], v[42:45]
	v_mfma_f32_16x16x32_bf16 v[38:41], v[166:169], v[174:177], v[38:41]
	v_mfma_f32_16x16x32_bf16 v[34:37], v[170:173], v[174:177], v[34:37]
	v_mfma_f32_16x16x32_bf16 v[30:33], v[130:133], v[178:181], v[30:33]
	v_mfma_f32_16x16x32_bf16 v[26:29], v[142:145], v[178:181], v[26:29]
	v_mfma_f32_16x16x32_bf16 v[22:25], v[150:153], v[178:181], v[22:25]
	v_mfma_f32_16x16x32_bf16 v[18:21], v[154:157], v[178:181], v[18:21]
	v_mfma_f32_16x16x32_bf16 v[14:17], v[158:161], v[178:181], v[14:17]
	v_mfma_f32_16x16x32_bf16 v[10:13], v[162:165], v[178:181], v[10:13]
	v_mfma_f32_16x16x32_bf16 v[6:9], v[166:169], v[178:181], v[6:9]
	v_mfma_f32_16x16x32_bf16 v[2:5], v[170:173], v[178:181], v[2:5]
	s_waitcnt vmcnt(0)
	s_barrier
; DI unsigned pk2(float lo, float hi) { const f32x2 v = {lo, hi}; const bf16x2_t b = __builtin_convertvector(v, bf16x2_t); return __builtin_bit_cast(unsigned, b); }
; DI float silu_f(float x) { return x * sigmoid_f(x); }
; DI f32x4 mfma16(bf16x8 a, bf16x8 b, f32x4 c) { return __builtin_amdgcn_mfma_f32_16x16x32_bf16(a, b, c, 0, 0, 0); }
;     ...
;     auto compute = [&](int cb, bool do_issue, int ikt, int ib) {
;         const char* base = lds + cb * BUF;
;         bf16x8 af[MT], bfr[NT];
; #pragma unroll
;         for (int nt = 0; nt < NT; ++nt) {
;             const int br = BM + (nt / NTS) * (BN / NSEG) + wc * (NTS * 16) + (nt % NTS) * 16;
;             bfr[nt] = *(const bf16x8*)(base + (br + l15) * 64 + rsw);
;         }
; #pragma unroll
;         for (int mt = 0; mt < MT; ++mt) af[mt] = *(const bf16x8*)(base + (wr * WM + mt * 16 + l15) * 64 + rsw);
;         constexpr int TOT = MT * NT, PER = (TOT + NIT - 1) / NIT;
; #pragma unroll
;         for (int part = 0; part < NIT; ++part) {
; #pragma unroll
;             for (int q = 0; q < PER; ++q) {
;                 const int idx = part * PER + q;
;                 if (idx < TOT) {
;                     const int mt = idx / NT, nt = idx % NT;
;                     acc[mt][nt] = SWAP ? mfma16(bfr[nt], af[mt], acc[mt][nt]) : mfma16(af[mt], bfr[nt], acc[mt][nt]);
; DI void unit_X(const Params& p, char* lds, int l, int chunk) {
;     ...
; #pragma unroll
;         for (int mt = 0; mt < 4; ++mt) {
;             const int tok = wr * 64 + mt * 16 + l15;
; #pragma unroll
;             for (int nt = 0; nt < 8; ++nt) {
;                 const f32x4 v = acc[mt][nt];
;                 if (wc < 2) {
;                     const int col = wc * 128 + nt * 16 + quad * 4;
;                     const float qs = 0.125f * 1.44269504089f;
;                     *(u32x2*)(Qs + tok * 528 + col * 2) = (u32x2){pk2(v[0] * qs, v[1] * qs), pk2(v[2] * qs, v[3] * qs)};
;                 } else {
;                     const int col = (wc - 2) * 128 + nt * 16 + quad * 4;
;                     *(u32x2*)(gx + (size_t)tok * 256 + col) = (u32x2){pk2(silu_f(v[0]), silu_f(v[1])), pk2(silu_f(v[2]), silu_f(v[3]))};
;                 }
;             }
;         }
	ds_read_b128 v[130:133], v0 offset:49152
	ds_read_b128 v[140:143], v0 offset:50176
	ds_read_b128 v[144:147], v134 offset:40960
	ds_read_b128 v[148:151], v134 offset:41984
	ds_read_b128 v[152:155], v0 offset:51200
	ds_read_b128 v[156:159], v0 offset:52224
	ds_read_b128 v[160:163], v0 offset:53248
	ds_read_b128 v[164:167], v0 offset:54272
	ds_read_b128 v[168:171], v0 offset:55296
	ds_read_b128 v[172:175], v0 offset:56320
	ds_read_b128 v[176:179], v134 offset:43008
	ds_read_b128 v[180:183], v134 offset:44032
	s_waitcnt lgkmcnt(0)
	v_mfma_f32_16x16x32_bf16 v[126:129], v[130:133], v[144:147], v[126:129]
	v_readlane_b32 s1, v243, 8
	s_add_u32 s10, s1, s0
	v_readlane_b32 s0, v243, 9
	v_mfma_f32_16x16x32_bf16 v[122:125], v[140:143], v[144:147], v[122:125]
	v_bfe_u32 v138, v137, 6, 2
	v_bfe_u32 v136, v137, 4, 2
	s_addc_u32 s11, s0, 0
	v_mfma_f32_16x16x32_bf16 v[118:121], v[152:155], v[144:147], v[118:121]
	v_mfma_f32_16x16x32_bf16 v[114:117], v[156:159], v[144:147], v[114:117]
	v_mfma_f32_16x16x32_bf16 v[110:113], v[160:163], v[144:147], v[110:113]
	v_mfma_f32_16x16x32_bf16 v[106:109], v[164:167], v[144:147], v[106:109]
	v_mfma_f32_16x16x32_bf16 v[102:105], v[168:171], v[144:147], v[102:105]
	v_mfma_f32_16x16x32_bf16 v[98:101], v[172:175], v[144:147], v[98:101]
	v_mfma_f32_16x16x32_bf16 v[94:97], v[130:133], v[148:151], v[94:97]
	v_mfma_f32_16x16x32_bf16 v[90:93], v[140:143], v[148:151], v[90:93]
	v_mfma_f32_16x16x32_bf16 v[86:89], v[152:155], v[148:151], v[86:89]
	v_mfma_f32_16x16x32_bf16 v[82:85], v[156:159], v[148:151], v[82:85]
	v_mfma_f32_16x16x32_bf16 v[78:81], v[160:163], v[148:151], v[78:81]
	v_mfma_f32_16x16x32_bf16 v[74:77], v[164:167], v[148:151], v[74:77]
	v_mfma_f32_16x16x32_bf16 v[70:73], v[168:171], v[148:151], v[70:73]
	v_mfma_f32_16x16x32_bf16 v[66:69], v[172:175], v[148:151], v[66:69]
	v_mfma_f32_16x16x32_bf16 v[62:65], v[130:133], v[176:179], v[62:65]
	v_mfma_f32_16x16x32_bf16 v[58:61], v[140:143], v[176:179], v[58:61]
	v_mfma_f32_16x16x32_bf16 v[54:57], v[152:155], v[176:179], v[54:57]
	v_mfma_f32_16x16x32_bf16 v[50:53], v[156:159], v[176:179], v[50:53]
	v_mfma_f32_16x16x32_bf16 v[46:49], v[160:163], v[176:179], v[46:49]
	v_mfma_f32_16x16x32_bf16 v[42:45], v[164:167], v[176:179], v[42:45]
	v_mfma_f32_16x16x32_bf16 v[38:41], v[168:171], v[176:179], v[38:41]
	v_mfma_f32_16x16x32_bf16 v[34:37], v[172:175], v[176:179], v[34:37]
	v_mfma_f32_16x16x32_bf16 v[30:33], v[130:133], v[180:183], v[30:33]
	v_mfma_f32_16x16x32_bf16 v[26:29], v[140:143], v[180:183], v[26:29]
	v_mfma_f32_16x16x32_bf16 v[22:25], v[152:155], v[180:183], v[22:25]
	v_mfma_f32_16x16x32_bf16 v[18:21], v[156:159], v[180:183], v[18:21]
	v_mfma_f32_16x16x32_bf16 v[14:17], v[160:163], v[180:183], v[14:17]
	v_mfma_f32_16x16x32_bf16 v[10:13], v[164:167], v[180:183], v[10:13]
	v_mfma_f32_16x16x32_bf16 v[6:9], v[168:171], v[180:183], v[6:9]
	v_mfma_f32_16x16x32_bf16 v[2:5], v[172:175], v[180:183], v[2:5]
	v_ashrrev_i32_e32 v0, 2, v137
	s_movk_i32 s0, 0xffc0
	v_and_or_b32 v130, v0, s0, v135
	v_ashrrev_i32_e32 v131, 31, v130
	v_lshlrev_b32_e32 v0, 7, v138
	v_lshlrev_b32_e32 v134, 2, v136
	v_lshlrev_b64 v[132:133], 9, v[130:131]
	v_cmp_lt_u32_e32 vcc, 1, v138
	v_lshl_add_u64 v[132:133], s[10:11], 0, v[132:133]
	v_add_lshl_u32 v0, v0, v134, 1
	s_waitcnt vmcnt(0)
	s_barrier
	s_and_saveexec_b64 s[0:1], vcc
	s_xor_b64 s[6:7], exec, s[0:1]
	s_cbranch_execz .LBB0_745
	v_mul_f32_e32 v131, 0xbfb8aa3b, v126
	v_exp_f32_e32 v131, v131
	s_nop 0
	v_add_f32_e32 v131, 1.0, v131
	v_rcp_f32_e32 v140, v131
	v_mul_f32_e32 v131, 0xbfb8aa3b, v127
	v_exp_f32_e32 v131, v131
	s_nop 0
	v_add_f32_e32 v131, 1.0, v131
	v_rcp_f32_e32 v141, v131
	s_nop 0
	v_pk_mul_f32 v[126:127], v[126:127], v[140:141]
	s_nop 0
	v_cvt_pk_bf16_f32 v126, v126, v127
	v_mul_f32_e32 v127, 0xbfb8aa3b, v128
	v_exp_f32_e32 v127, v127
	s_nop 0
	v_add_f32_e32 v127, 1.0, v127
	v_rcp_f32_e32 v140, v127
	v_mul_f32_e32 v127, 0xbfb8aa3b, v129
	v_exp_f32_e32 v127, v127
	s_nop 0
	v_add_f32_e32 v127, 1.0, v127
	v_rcp_f32_e32 v141, v127
	s_nop 0
	v_pk_mul_f32 v[128:129], v[128:129], v[140:141]
	s_nop 0
	v_cvt_pk_bf16_f32 v127, v128, v129
	v_lshl_add_u64 v[128:129], v[132:133], 0, v[0:1]
	global_store_dwordx2 v[128:129], v[126:127], off offset:-512

;     ...
; #pragma unroll
;     for (int mt = 0; mt < MT; ++mt)
; #pragma unroll
;         for (int nt = 0; nt < NT; ++nt) acc[mt][nt] = (f32x4){0.f, 0.f, 0.f, 0.f};
;     const unsigned loff = (unsigned)(lrow * 64 + lcg * 16);
;     const int koff = (int)((blockIdx.x >> 3) + (blockIdx.x & 7) * 4) & (KT - 1);
;     auto issue_one = [&](int kt, int b, int i) {
;         const int row = lrow + 128 * i;
;         if ((NCH % 512 == 0) || (i < NCH / 512) || row < ROWS) {
;             const int kq = (kt + koff) & (KT - 1);
;             const char* ua = (const char*)A + (size_t)((DBG & 1) ? 0 : kq) * (BM * 64);
;             const char* ub = (const char*)Bt + (size_t)((DBG & 2) ? 0 : kq) * ((size_t)ldbk * 2);
;             const char* src;
;             if (BM % 128 == 0) src = (i < BM / 128) ? (ua + i * 8192 + loff) : (ub + (i * 128 - BM) * 64 + loff);
;             else if (i == 0) src = (lrow < BM) ? (ua + loff) : (ub + loff - BM * 64);
;             else src = ub + (i * 128 - BM) * 64 + loff;
;             __builtin_amdgcn_global_load_lds((const unsigned*)src, (unsigned*)(lds + b * BUF + i * 8192 + tid * 16), 16, 0, 0);
;         }
;     };
;     auto issue = [&](int kt, int b) {
; #pragma unroll
;         for (int i = 0; i < NIT; ++i) issue_one(kt, b, i);
; DI void unit_A(const Params& p, char* lds, int l, int chunk, int h) {
;     ...
;     __syncthreads();
;     {
;         const bf16_t* W = WS_PTR(const bf16_t, OFF_WSP) + (size_t)(l * 4 + h) * 16384;
; #pragma unroll
;         for (int i = 0; i < 4; ++i) {
;             const int piece = wid + 8 * i, row = piece * 4 + (lane >> 4), lc = (lane & 15) ^ (row & 15);
;             __builtin_amdgcn_global_load_lds((const unsigned*)(W + row * 128 + lc * 8), (unsigned*)(WL + piece * 1024 + lane * 16), 16, 0, 0);
;         }
;     }
;     gemm_main<128, 384, 2, 4, 3, false, 3>(xb + (size_t)chunk * 128 * 1024, WS_PTR(const bf16_t, OFF_WIN) + (size_t)l * 2560 * 1024 + (size_t)h * 384 * 32, 2560 * 32, lds, acc);
.LBB0_825:
	s_andn2_b64 vcc, exec, s[6:7]
	s_cbranch_vccnz .LBB0_858
	s_ashr_i32 s1, s79, 8
	v_readlane_b32 s6, v242, 23
	s_add_i32 s6, s1, s6
	s_ashr_i32 s7, s6, 31
	s_and_b32 s0, s2, 0xff
	s_lshl_b64 s[8:9], s[6:7], 15
	v_readlane_b32 s7, v244, 40
	v_mov_b32_e32 v191, v212
	s_add_u32 s8, s7, s8
	v_readlane_b32 s7, v244, 41
	s_addc_u32 s9, s7, s9
	v_and_b32_e32 v0, 63, v191
	v_ashrrev_i32_e32 v4, 6, v191
	s_add_i32 s10, 0, 0x18000
	v_bfe_u32 v190, v191, 4, 2
	v_lshl_add_u32 v5, v0, 4, s10
	v_lshlrev_b32_e32 v0, 2, v4
	v_or_b32_e32 v2, v0, v190
	v_bitop3_b32 v0, v0, v191, v190 bitop3:0x36
	v_lshlrev_b32_e32 v2, 7, v2
	v_ashrrev_i32_e32 v3, 31, v2
	v_lshlrev_b32_e32 v0, 4, v0
	v_lshl_add_u64 v[2:3], v[2:3], 1, s[8:9]
	v_and_b32_e32 v0, 0xf0, v0
	v_lshl_add_u64 v[2:3], v[2:3], 0, v[0:1]
	v_lshl_add_u32 v0, v4, 10, v5
	v_add_u32_e32 v6, 8, v4
	v_readfirstlane_b32 s12, v0
	s_mov_b32 m0, s12
	v_lshlrev_b32_e32 v0, 2, v6
	s_barrier
	global_load_lds_dwordx4 v[2:3], off
	v_or_b32_e32 v2, v0, v190
	v_bitop3_b32 v0, v0, v191, v190 bitop3:0x36
	v_lshlrev_b32_e32 v2, 7, v2
	v_ashrrev_i32_e32 v3, 31, v2
	v_lshlrev_b32_e32 v0, 4, v0
	v_lshl_add_u64 v[2:3], v[2:3], 1, s[8:9]
	v_and_b32_e32 v0, 0xf0, v0
	v_lshl_add_u64 v[2:3], v[2:3], 0, v[0:1]
	v_lshl_add_u32 v0, v6, 10, v5
	v_add_u32_e32 v6, 16, v4
	v_readfirstlane_b32 s12, v0
	s_mov_b32 m0, s12
	v_lshlrev_b32_e32 v0, 2, v6
	global_load_lds_dwordx4 v[2:3], off
	v_or_b32_e32 v2, v0, v190
	v_bitop3_b32 v0, v0, v191, v190 bitop3:0x36
	v_lshlrev_b32_e32 v2, 7, v2
	v_ashrrev_i32_e32 v3, 31, v2
	v_lshlrev_b32_e32 v0, 4, v0
	v_lshl_add_u64 v[2:3], v[2:3], 1, s[8:9]
	v_and_b32_e32 v0, 0xf0, v0
	v_lshl_add_u64 v[2:3], v[2:3], 0, v[0:1]
	v_lshl_add_u32 v0, v6, 10, v5
	v_add_u32_e32 v4, 24, v4
	v_readfirstlane_b32 s12, v0
	s_mov_b32 m0, s12
	v_lshlrev_b32_e32 v0, 2, v4
	global_load_lds_dwordx4 v[2:3], off
	v_or_b32_e32 v2, v0, v190
	v_bitop3_b32 v0, v0, v191, v190 bitop3:0x36
	v_lshlrev_b32_e32 v2, 7, v2
	v_ashrrev_i32_e32 v3, 31, v2
	v_lshlrev_b32_e32 v0, 4, v0
	v_lshl_add_u64 v[2:3], v[2:3], 1, s[8:9]
	v_and_b32_e32 v0, 0xf0, v0
	v_lshl_add_u64 v[2:3], v[2:3], 0, v[0:1]
	v_lshl_add_u32 v0, v4, 10, v5
	v_mov_b32_e32 v6, v212
	v_readfirstlane_b32 s8, v0
	s_mov_b32 m0, s8
	s_lshl_b32 s8, s0, 18
	global_load_lds_dwordx4 v[2:3], off
	v_readlane_b32 s9, v243, 56
	v_ashrrev_i32_e32 v7, 6, v6
	v_lshrrev_b32_e32 v0, 30, v7
	v_add_u32_e32 v0, v7, v0
	v_ashrrev_i32_e32 v8, 2, v0
	v_lshrrev_b32_e32 v0, 4, v6
	v_sub_u32_e32 v0, 0, v0
	v_lshlrev_b32_e32 v2, 2, v6
	v_and_b32_e32 v2, 48, v2
	v_xor_b32_e32 v0, v6, v0
	v_lshlrev_b32_e32 v4, 4, v6
	s_add_u32 s14, s9, s8
	v_readlane_b32 s8, v243, 40
	v_sub_u32_e32 v9, 0, v2
	v_and_b32_e32 v2, 0xffffffc0, v4
	v_lshlrev_b32_e32 v0, 4, v0
	s_addc_u32 s15, s8, 0
	s_mul_i32 s8, s1, 0x6000
	v_readlane_b32 s12, v242, 24
	v_and_or_b32 v0, v0, 48, v2
	v_add_u32_e32 v102, 0, v4
	s_mul_hi_i32 s9, s1, 0x6000
	s_add_u32 s8, s12, s8
	v_readlane_b32 s12, v242, 25
	v_lshl_add_u64 v[98:99], s[14:15], 0, v[0:1]
	v_readlane_b32 s14, v243, 25
	v_readfirstlane_b32 s13, v102
	s_addc_u32 s9, s12, s9
	v_readlane_b32 s15, v243, 26
	s_mov_b32 m0, s13
	v_readlane_b32 s13, v243, 4
	v_lshl_add_u64 v[2:3], v[98:99], 0, s[14:15]
	s_add_u32 s14, s8, s13
	v_add_u32_e32 v4, 0x2000, v102
	s_addc_u32 s15, s9, 0
	v_readfirstlane_b32 s13, v4
	v_add_u32_e32 v10, 0x4000, v102
	s_waitcnt vmcnt(0) lgkmcnt(0)
	s_barrier
	global_load_lds_dwordx4 v[2:3], off
	v_lshl_add_u64 v[2:3], s[14:15], 0, v[0:1]
	s_mov_b32 m0, s13
	v_readfirstlane_b32 s13, v10
	global_load_lds_dwordx4 v0, s[14:15]
	v_lshl_add_u64 v[4:5], v[2:3], 0, s[76:77]
	s_mov_b32 m0, s13
	v_lshl_add_u64 v[2:3], v[2:3], 0, s[80:81]
	global_load_lds_dwordx4 v[4:5], off
	v_add_u32_e32 v4, 0x6000, v102
	v_readlane_b32 s14, v243, 5
	v_readfirstlane_b32 s13, v4
	v_add_u32_e32 v4, 0x8000, v102
	s_mov_b32 m0, s13
	v_readfirstlane_b32 s13, v4
	global_load_lds_dwordx4 v[2:3], off
	v_readlane_b32 s15, v243, 6
	s_mov_b32 m0, s13
	v_readlane_b32 s13, v243, 7
	v_lshl_add_u64 v[2:3], v[98:99], 0, s[14:15]
	s_add_u32 s14, s8, s13
	v_add_u32_e32 v4, 0xa000, v102
	s_addc_u32 s15, s9, 0
	v_readfirstlane_b32 s13, v4
	v_add_u32_e32 v10, 0xc000, v102
	global_load_lds_dwordx4 v[2:3], off
	v_lshl_add_u64 v[2:3], s[14:15], 0, v[0:1]
	s_mov_b32 m0, s13
	v_readfirstlane_b32 s13, v10
	global_load_lds_dwordx4 v0, s[14:15]
	v_lshl_add_u64 v[4:5], v[2:3], 0, s[76:77]
	s_mov_b32 m0, s13
	v_lshl_add_u64 v[2:3], v[2:3], 0, s[80:81]
	global_load_lds_dwordx4 v[4:5], off
	v_add_u32_e32 v4, 0xe000, v102
	s_mov_b32 s7, 4
	v_readfirstlane_b32 s13, v4
	s_mov_b32 m0, s13
	s_mov_b32 s11, 2
	global_load_lds_dwordx4 v[2:3], off
	v_bitop3_b32 v3, v6, 48, v9 bitop3:0x48
	v_mul_i32_i24_e32 v2, 4, v8
	v_add_u32_e32 v103, 0, v3
	v_lshlrev_b32_e32 v3, 6, v6
	v_sub_u32_e32 v2, v7, v2
	v_and_b32_e32 v3, 0x3c0, v3
	v_lshl_or_b32 v104, v2, 11, v3
	v_mov_b32_e32 v2, 0
	s_mov_b32 s12, 0
	v_lshl_or_b32 v105, v8, 12, v3
	v_lshl_add_u64 v[100:101], s[8:9], 0, v[0:1]
	v_readlane_b32 s13, v243, 24
	v_mov_b32_e32 v3, v2
	v_mov_b32_e32 v4, v2
	v_mov_b32_e32 v5, v2
	v_mov_b32_e32 v6, v2
	v_mov_b32_e32 v7, v2
	v_mov_b32_e32 v8, v2
	v_mov_b32_e32 v9, v2
	v_mov_b32_e32 v10, v2
	v_mov_b32_e32 v11, v2
	v_mov_b32_e32 v12, v2
	v_mov_b32_e32 v13, v2
	v_mov_b32_e32 v14, v2
	v_mov_b32_e32 v15, v2
	v_mov_b32_e32 v16, v2
	v_mov_b32_e32 v17, v2
	v_mov_b32_e32 v18, v2
	v_mov_b32_e32 v19, v2
	v_mov_b32_e32 v20, v2
	v_mov_b32_e32 v21, v2
	v_mov_b32_e32 v22, v2
	v_mov_b32_e32 v23, v2
	v_mov_b32_e32 v24, v2
	v_mov_b32_e32 v25, v2
	v_mov_b32_e32 v26, v2
	v_mov_b32_e32 v27, v2
	v_mov_b32_e32 v28, v2
	v_mov_b32_e32 v29, v2
	v_mov_b32_e32 v30, v2
; DI f32x4 mfma16(bf16x8 a, bf16x8 b, f32x4 c) { return __builtin_amdgcn_mfma_f32_16x16x32_bf16(a, b, c, 0, 0, 0); }
; template <int N> DI void wait_vm() { asm volatile("s_waitcnt vmcnt(%0)" ::"n"(N) : "memory"); }
; DI void raw_barrier() { asm volatile("" ::: "memory"); __builtin_amdgcn_s_barrier(); asm volatile("" ::: "memory"); }
;     ...
;     auto compute = [&](int cb, bool do_issue, int ikt, int ib) {
;         const char* base = lds + cb * BUF;
;         bf16x8 af[MT], bfr[NT];
; #pragma unroll
;         for (int nt = 0; nt < NT; ++nt) {
;             const int br = BM + (nt / NTS) * (BN / NSEG) + wc * (NTS * 16) + (nt % NTS) * 16;
;             bfr[nt] = *(const bf16x8*)(base + (br + l15) * 64 + rsw);
;         }
; #pragma unroll
;         for (int mt = 0; mt < MT; ++mt) af[mt] = *(const bf16x8*)(base + (wr * WM + mt * 16 + l15) * 64 + rsw);
;         constexpr int TOT = MT * NT, PER = (TOT + NIT - 1) / NIT;
; #pragma unroll
;         for (int part = 0; part < NIT; ++part) {
; #pragma unroll
;             for (int q = 0; q < PER; ++q) {
;                 const int idx = part * PER + q;
;                 if (idx < TOT) {
;                     const int mt = idx / NT, nt = idx % NT;
;                     acc[mt][nt] = SWAP ? mfma16(bfr[nt], af[mt], acc[mt][nt]) : mfma16(af[mt], bfr[nt], acc[mt][nt]);
;                 }
;             }
;             __builtin_amdgcn_sched_barrier(0);
;             if (do_issue) issue_one(ikt, ib, part);
;             __builtin_amdgcn_sched_barrier(0);
;         }
;     };
;     __syncthreads();
; #pragma unroll
;     for (int d = 0; d < D; ++d) issue(d, d);
;     int cb = 0, ib = D;
;     for (int kt = 0; kt < KT; ++kt) {
;         if (D > 1 && kt + D - 1 < KT) wait_vm<(D - 1) * NIT>(); else wait_vm<0>();
;         raw_barrier();
;         compute(cb, kt + D < KT, kt + D, ib);
;         cb = (cb + 1 == NST) ? 0 : cb + 1;
;         ib = (ib + 1 == NST) ? 0 : ib + 1;
;     }
	v_mov_b32_e32 v31, v2
	v_mov_b32_e32 v32, v2
	v_mov_b32_e32 v33, v2
	v_mov_b32_e32 v34, v2
	v_mov_b32_e32 v35, v2
	v_mov_b32_e32 v36, v2
	v_mov_b32_e32 v37, v2
	v_mov_b32_e32 v38, v2
	v_mov_b32_e32 v39, v2
	v_mov_b32_e32 v40, v2
	v_mov_b32_e32 v41, v2
	v_mov_b32_e32 v42, v2
	v_mov_b32_e32 v43, v2
	v_mov_b32_e32 v44, v2
	v_mov_b32_e32 v45, v2
	v_mov_b32_e32 v46, v2
	v_mov_b32_e32 v47, v2
	v_mov_b32_e32 v48, v2
	v_mov_b32_e32 v49, v2
	v_mov_b32_e32 v50, v2
	v_mov_b32_e32 v51, v2
	v_mov_b32_e32 v52, v2
	v_mov_b32_e32 v53, v2
	v_mov_b32_e32 v54, v2
	v_mov_b32_e32 v55, v2
	v_mov_b32_e32 v56, v2
	v_mov_b32_e32 v57, v2
	v_mov_b32_e32 v58, v2
	v_mov_b32_e32 v59, v2
	v_mov_b32_e32 v60, v2
	v_mov_b32_e32 v61, v2
	v_mov_b32_e32 v62, v2
	v_mov_b32_e32 v63, v2
	v_mov_b32_e32 v64, v2
	v_mov_b32_e32 v65, v2
	v_mov_b32_e32 v66, v2
	v_mov_b32_e32 v67, v2
	v_mov_b32_e32 v68, v2
	v_mov_b32_e32 v69, v2
	v_mov_b32_e32 v70, v2
	v_mov_b32_e32 v71, v2
	v_mov_b32_e32 v72, v2
	v_mov_b32_e32 v73, v2
	v_mov_b32_e32 v74, v2
	v_mov_b32_e32 v75, v2
	v_mov_b32_e32 v76, v2
	v_mov_b32_e32 v77, v2
	v_mov_b32_e32 v78, v2
	v_mov_b32_e32 v79, v2
	v_mov_b32_e32 v80, v2
	v_mov_b32_e32 v81, v2
	v_mov_b32_e32 v82, v2
	v_mov_b32_e32 v83, v2
	v_mov_b32_e32 v84, v2
	v_mov_b32_e32 v85, v2
	v_mov_b32_e32 v86, v2
	v_mov_b32_e32 v87, v2
	v_mov_b32_e32 v88, v2
	v_mov_b32_e32 v89, v2
	v_mov_b32_e32 v90, v2
	v_mov_b32_e32 v91, v2
	v_mov_b32_e32 v92, v2
	v_mov_b32_e32 v93, v2
	v_mov_b32_e32 v94, v2
	v_mov_b32_e32 v95, v2
	v_mov_b32_e32 v96, v2
	v_mov_b32_e32 v97, v2
	v_readfirstlane_b32 s40, v212
	s_nop 3
	s_cmp_lt_u32 s40, 0x100
	s_cbranch_scc0 .Lpa_c_entry
	s_lshl_b32 s13, s40, 5
	s_lshl_b32 s40, s40, 4
	v_add_u32_e32 v227, s40, v0
	v_readfirstlane_b32 s14, v98
	v_readfirstlane_b32 s15, v99
	v_readfirstlane_b32 s40, v0
	s_nop 3
	s_sub_u32 vcc_lo, s14, s40
	s_subb_u32 vcc_hi, s15, 0
	s_mul_i32 s14, s11, 0x8000
	s_add_u32 s14, s14, s13
	s_mov_b32 m0, s14
	s_add_i32 s40, s59, s7
	s_and_b32 s40, s40, 62
	s_lshl_b32 s14, s40, 12
	s_add_u32 s14, vcc_lo, s14
	s_addc_u32 s15, vcc_hi, 0
	s_mul_i32 s40, s40, 0x14000
	global_load_lds_dwordx4 v227, s[14:15]
	global_load_lds_dwordx4 v227, s[14:15] offset:1024
	s_add_u32 s14, s8, s40
	s_addc_u32 s15, s9, 0
	s_add_u32 m0, m0, 0x2000
	s_nop 0
	global_load_lds_dwordx4 v227, s[14:15]
	global_load_lds_dwordx4 v227, s[14:15] offset:1024
	s_add_u32 s14, s14, 0x2000
	s_addc_u32 s15, s15, 0
	s_add_u32 m0, m0, 0x2000
	s_nop 0
	global_load_lds_dwordx4 v227, s[14:15]
	global_load_lds_dwordx4 v227, s[14:15] offset:1024
	s_add_u32 s14, s14, 0x2000
	s_addc_u32 s15, s15, 0
	s_add_u32 m0, m0, 0x2000
	s_nop 0
	global_load_lds_dwordx4 v227, s[14:15]
	global_load_lds_dwordx4 v227, s[14:15] offset:1024
	s_add_i32 s7, s7, 2
	s_mov_b32 s11, 0
	s_mov_b32 s12, 1
	s_waitcnt vmcnt(12)
	s_barrier
	v_add_u32_e32 v225, v103, v104
	v_add_u32_e32 v224, v103, v105
	ds_read_b128 v[106:109], v224
	ds_read_b128 v[118:121], v224 offset:1024
	ds_read_b128 v[138:141], v224 offset:2048
	ds_read_b128 v[110:113], v225 offset:8192
	ds_read_b128 v[114:117], v225 offset:9216
	ds_read_b128 v[122:125], v225 offset:16384
	ds_read_b128 v[126:129], v225 offset:17408
	ds_read_b128 v[130:133], v225 offset:24576
	ds_read_b128 v[134:137], v225 offset:25600
	ds_read_b128 v[142:145], v224 offset:3072
.Lpa_l_loop:
	s_mul_i32 s40, s12, 0x8000
	v_add_u32_e32 v226, s40, v103
	v_add_u32_e32 v225, v226, v104
	v_add_u32_e32 v224, v226, v105
	s_waitcnt lgkmcnt(6)
	v_mfma_f32_16x16x32_bf16 v[94:97], v[106:109], v[110:113], v[94:97]
	s_waitcnt lgkmcnt(5)
	v_mfma_f32_16x16x32_bf16 v[90:93], v[106:109], v[114:117], v[90:93]
	s_waitcnt lgkmcnt(4)
	v_mfma_f32_16x16x32_bf16 v[86:89], v[106:109], v[122:125], v[86:89]
	s_waitcnt lgkmcnt(3)
	v_mfma_f32_16x16x32_bf16 v[82:85], v[106:109], v[126:129], v[82:85]
	s_waitcnt lgkmcnt(2)
	v_mfma_f32_16x16x32_bf16 v[78:81], v[106:109], v[130:133], v[78:81]
	s_waitcnt lgkmcnt(1)
	v_mfma_f32_16x16x32_bf16 v[74:77], v[106:109], v[134:137], v[74:77]
	s_waitcnt vmcnt(8) lgkmcnt(0)
	s_barrier
	ds_read_b128 v[106:109], v224
	s_mul_i32 s14, s11, 0x8000
	s_add_u32 s14, s14, s13
	s_mov_b32 m0, s14
	s_add_i32 s40, s59, s7
	s_and_b32 s40, s40, 62
	s_lshl_b32 s14, s40, 12
	s_add_u32 s14, vcc_lo, s14
	s_addc_u32 s15, vcc_hi, 0
	s_mul_i32 s40, s40, 0x14000
	global_load_lds_dwordx4 v227, s[14:15]
	global_load_lds_dwordx4 v227, s[14:15] offset:1024
	v_mfma_f32_16x16x32_bf16 v[70:73], v[118:121], v[110:113], v[70:73]
	v_mfma_f32_16x16x32_bf16 v[66:69], v[118:121], v[114:117], v[66:69]
	v_mfma_f32_16x16x32_bf16 v[62:65], v[118:121], v[122:125], v[62:65]
	v_mfma_f32_16x16x32_bf16 v[58:61], v[118:121], v[126:129], v[58:61]
	s_add_u32 s14, s8, s40
	s_addc_u32 s15, s9, 0
	s_add_u32 m0, m0, 0x2000
	s_nop 0
	global_load_lds_dwordx4 v227, s[14:15]
	global_load_lds_dwordx4 v227, s[14:15] offset:1024
	v_mfma_f32_16x16x32_bf16 v[54:57], v[118:121], v[130:133], v[54:57]
	v_mfma_f32_16x16x32_bf16 v[50:53], v[118:121], v[134:137], v[50:53]
	ds_read_b128 v[118:121], v224 offset:1024
	v_mfma_f32_16x16x32_bf16 v[46:49], v[138:141], v[110:113], v[46:49]
	v_mfma_f32_16x16x32_bf16 v[42:45], v[138:141], v[114:117], v[42:45]
	v_mfma_f32_16x16x32_bf16 v[38:41], v[138:141], v[122:125], v[38:41]
	s_add_u32 s14, s14, 0x2000
	s_addc_u32 s15, s15, 0
	s_add_u32 m0, m0, 0x2000
	s_nop 0
	global_load_lds_dwordx4 v227, s[14:15]
	global_load_lds_dwordx4 v227, s[14:15] offset:1024
	v_mfma_f32_16x16x32_bf16 v[34:37], v[138:141], v[126:129], v[34:37]
	v_mfma_f32_16x16x32_bf16 v[30:33], v[138:141], v[130:133], v[30:33]
	v_mfma_f32_16x16x32_bf16 v[26:29], v[138:141], v[134:137], v[26:29]
	ds_read_b128 v[138:141], v224 offset:2048
	v_mfma_f32_16x16x32_bf16 v[22:25], v[142:145], v[110:113], v[22:25]
	ds_read_b128 v[110:113], v225 offset:8192
	v_mfma_f32_16x16x32_bf16 v[18:21], v[142:145], v[114:117], v[18:21]
	ds_read_b128 v[114:117], v225 offset:9216
	s_add_u32 s14, s14, 0x2000
	s_addc_u32 s15, s15, 0
	s_add_u32 m0, m0, 0x2000
	s_nop 0
	global_load_lds_dwordx4 v227, s[14:15]
	global_load_lds_dwordx4 v227, s[14:15] offset:1024
	v_mfma_f32_16x16x32_bf16 v[14:17], v[142:145], v[122:125], v[14:17]
	ds_read_b128 v[122:125], v225 offset:16384
	v_mfma_f32_16x16x32_bf16 v[10:13], v[142:145], v[126:129], v[10:13]
	ds_read_b128 v[126:129], v225 offset:17408
	v_mfma_f32_16x16x32_bf16 v[6:9], v[142:145], v[130:133], v[6:9]
	ds_read_b128 v[130:133], v225 offset:24576
	v_mfma_f32_16x16x32_bf16 v[2:5], v[142:145], v[134:137], v[2:5]
	ds_read_b128 v[134:137], v225 offset:25600
	ds_read_b128 v[142:145], v224 offset:3072
	s_add_i32 s12, s12, 1
	s_cmp_lg_u32 s12, 3
	s_cselect_b32 s12, s12, 0
	s_add_i32 s11, s11, 1
	s_cmp_lg_u32 s11, 3
	s_cselect_b32 s11, s11, 0
	s_add_i32 s7, s7, 2
	s_cmp_lg_u32 s7, 64
	s_cbranch_scc1 .Lpa_l_loop
; DI f32x4 mfma16(bf16x8 a, bf16x8 b, f32x4 c) { return __builtin_amdgcn_mfma_f32_16x16x32_bf16(a, b, c, 0, 0, 0); }
; template <int N> DI void wait_vm() { asm volatile("s_waitcnt vmcnt(%0)" ::"n"(N) : "memory"); }
; DI void raw_barrier() { asm volatile("" ::: "memory"); __builtin_amdgcn_s_barrier(); asm volatile("" ::: "memory"); }
;     ...
;     auto compute = [&](int cb, bool do_issue, int ikt, int ib) {
;         const char* base = lds + cb * BUF;
;         bf16x8 af[MT], bfr[NT];
; #pragma unroll
;         for (int nt = 0; nt < NT; ++nt) {
;             const int br = BM + (nt / NTS) * (BN / NSEG) + wc * (NTS * 16) + (nt % NTS) * 16;
;             bfr[nt] = *(const bf16x8*)(base + (br + l15) * 64 + rsw);
;         }
; #pragma unroll
;         for (int mt = 0; mt < MT; ++mt) af[mt] = *(const bf16x8*)(base + (wr * WM + mt * 16 + l15) * 64 + rsw);
;         constexpr int TOT = MT * NT, PER = (TOT + NIT - 1) / NIT;
; #pragma unroll
;         for (int part = 0; part < NIT; ++part) {
; #pragma unroll
;             for (int q = 0; q < PER; ++q) {
;                 const int idx = part * PER + q;
;                 if (idx < TOT) {
;                     const int mt = idx / NT, nt = idx % NT;
;                     acc[mt][nt] = SWAP ? mfma16(bfr[nt], af[mt], acc[mt][nt]) : mfma16(af[mt], bfr[nt], acc[mt][nt]);
;                 }
;             }
;             __builtin_amdgcn_sched_barrier(0);
;             if (do_issue) issue_one(ikt, ib, part);
;             __builtin_amdgcn_sched_barrier(0);
;         }
;     };
;     __syncthreads();
; #pragma unroll
;     for (int d = 0; d < D; ++d) issue(d, d);
;     int cb = 0, ib = D;
;     for (int kt = 0; kt < KT; ++kt) {
;         if (D > 1 && kt + D - 1 < KT) wait_vm<(D - 1) * NIT>(); else wait_vm<0>();
;         raw_barrier();
;         compute(cb, kt + D < KT, kt + D, ib);
;         cb = (cb + 1 == NST) ? 0 : cb + 1;
;         ib = (ib + 1 == NST) ? 0 : ib + 1;
;     }
	s_waitcnt lgkmcnt(6)
	v_mfma_f32_16x16x32_bf16 v[94:97], v[106:109], v[110:113], v[94:97]
	s_waitcnt lgkmcnt(5)
	v_mfma_f32_16x16x32_bf16 v[90:93], v[106:109], v[114:117], v[90:93]
	s_waitcnt lgkmcnt(4)
	v_mfma_f32_16x16x32_bf16 v[86:89], v[106:109], v[122:125], v[86:89]
	s_waitcnt lgkmcnt(3)
	v_mfma_f32_16x16x32_bf16 v[82:85], v[106:109], v[126:129], v[82:85]
	s_waitcnt lgkmcnt(2)
	v_mfma_f32_16x16x32_bf16 v[78:81], v[106:109], v[130:133], v[78:81]
	s_waitcnt lgkmcnt(1)
	v_mfma_f32_16x16x32_bf16 v[74:77], v[106:109], v[134:137], v[74:77]
	s_waitcnt lgkmcnt(0)
	v_mfma_f32_16x16x32_bf16 v[70:73], v[118:121], v[110:113], v[70:73]
	v_mfma_f32_16x16x32_bf16 v[66:69], v[118:121], v[114:117], v[66:69]
	v_mfma_f32_16x16x32_bf16 v[62:65], v[118:121], v[122:125], v[62:65]
	v_mfma_f32_16x16x32_bf16 v[58:61], v[118:121], v[126:129], v[58:61]
	v_mfma_f32_16x16x32_bf16 v[54:57], v[118:121], v[130:133], v[54:57]
	v_mfma_f32_16x16x32_bf16 v[50:53], v[118:121], v[134:137], v[50:53]
	v_mfma_f32_16x16x32_bf16 v[46:49], v[138:141], v[110:113], v[46:49]
	v_mfma_f32_16x16x32_bf16 v[42:45], v[138:141], v[114:117], v[42:45]
	v_mfma_f32_16x16x32_bf16 v[38:41], v[138:141], v[122:125], v[38:41]
	v_mfma_f32_16x16x32_bf16 v[34:37], v[138:141], v[126:129], v[34:37]
	v_mfma_f32_16x16x32_bf16 v[30:33], v[138:141], v[130:133], v[30:33]
	v_mfma_f32_16x16x32_bf16 v[26:29], v[138:141], v[134:137], v[26:29]
	v_mfma_f32_16x16x32_bf16 v[22:25], v[142:145], v[110:113], v[22:25]
	v_mfma_f32_16x16x32_bf16 v[18:21], v[142:145], v[114:117], v[18:21]
	v_mfma_f32_16x16x32_bf16 v[14:17], v[142:145], v[122:125], v[14:17]
	v_mfma_f32_16x16x32_bf16 v[10:13], v[142:145], v[126:129], v[10:13]
	v_mfma_f32_16x16x32_bf16 v[6:9], v[142:145], v[130:133], v[6:9]
	v_mfma_f32_16x16x32_bf16 v[2:5], v[142:145], v[134:137], v[2:5]
	s_branch .Lpa_join
.Lpa_c_entry:
	s_add_i32 s7, s7, 2
	s_mov_b32 s12, 1
	s_waitcnt vmcnt(4)
	s_barrier
	v_add_u32_e32 v225, v103, v104
	v_add_u32_e32 v224, v103, v105
	ds_read_b128 v[106:109], v224
	ds_read_b128 v[118:121], v224 offset:1024
	ds_read_b128 v[138:141], v224 offset:2048
	ds_read_b128 v[110:113], v225 offset:8192
	ds_read_b128 v[114:117], v225 offset:9216
	ds_read_b128 v[122:125], v225 offset:16384
	ds_read_b128 v[126:129], v225 offset:17408
	ds_read_b128 v[130:133], v225 offset:24576
	ds_read_b128 v[134:137], v225 offset:25600
	ds_read_b128 v[142:145], v224 offset:3072
.Lpa_c_loop:
	s_mul_i32 s40, s12, 0x8000
	v_add_u32_e32 v226, s40, v103
	v_add_u32_e32 v225, v226, v104
	v_add_u32_e32 v224, v226, v105
	s_waitcnt lgkmcnt(6)
	v_mfma_f32_16x16x32_bf16 v[94:97], v[106:109], v[110:113], v[94:97]
	s_waitcnt lgkmcnt(5)
	v_mfma_f32_16x16x32_bf16 v[90:93], v[106:109], v[114:117], v[90:93]
	s_waitcnt lgkmcnt(4)
	v_mfma_f32_16x16x32_bf16 v[86:89], v[106:109], v[122:125], v[86:89]
	s_waitcnt lgkmcnt(3)
	v_mfma_f32_16x16x32_bf16 v[82:85], v[106:109], v[126:129], v[82:85]
	s_waitcnt lgkmcnt(2)
	v_mfma_f32_16x16x32_bf16 v[78:81], v[106:109], v[130:133], v[78:81]
	s_waitcnt lgkmcnt(1)
	v_mfma_f32_16x16x32_bf16 v[74:77], v[106:109], v[134:137], v[74:77]
	s_waitcnt vmcnt(0) lgkmcnt(0)
	s_barrier
	ds_read_b128 v[106:109], v224
	v_mfma_f32_16x16x32_bf16 v[70:73], v[118:121], v[110:113], v[70:73]
	v_mfma_f32_16x16x32_bf16 v[66:69], v[118:121], v[114:117], v[66:69]
	v_mfma_f32_16x16x32_bf16 v[62:65], v[118:121], v[122:125], v[62:65]
	v_mfma_f32_16x16x32_bf16 v[58:61], v[118:121], v[126:129], v[58:61]
	v_mfma_f32_16x16x32_bf16 v[54:57], v[118:121], v[130:133], v[54:57]
	v_mfma_f32_16x16x32_bf16 v[50:53], v[118:121], v[134:137], v[50:53]
	ds_read_b128 v[118:121], v224 offset:1024
	v_mfma_f32_16x16x32_bf16 v[46:49], v[138:141], v[110:113], v[46:49]
	v_mfma_f32_16x16x32_bf16 v[42:45], v[138:141], v[114:117], v[42:45]
	v_mfma_f32_16x16x32_bf16 v[38:41], v[138:141], v[122:125], v[38:41]
	v_mfma_f32_16x16x32_bf16 v[34:37], v[138:141], v[126:129], v[34:37]
	v_mfma_f32_16x16x32_bf16 v[30:33], v[138:141], v[130:133], v[30:33]
	v_mfma_f32_16x16x32_bf16 v[26:29], v[138:141], v[134:137], v[26:29]
	ds_read_b128 v[138:141], v224 offset:2048
	v_mfma_f32_16x16x32_bf16 v[22:25], v[142:145], v[110:113], v[22:25]
	ds_read_b128 v[110:113], v225 offset:8192
	v_mfma_f32_16x16x32_bf16 v[18:21], v[142:145], v[114:117], v[18:21]
	ds_read_b128 v[114:117], v225 offset:9216
	v_mfma_f32_16x16x32_bf16 v[14:17], v[142:145], v[122:125], v[14:17]
	ds_read_b128 v[122:125], v225 offset:16384
	v_mfma_f32_16x16x32_bf16 v[10:13], v[142:145], v[126:129], v[10:13]
	ds_read_b128 v[126:129], v225 offset:17408
	v_mfma_f32_16x16x32_bf16 v[6:9], v[142:145], v[130:133], v[6:9]
	ds_read_b128 v[130:133], v225 offset:24576
	v_mfma_f32_16x16x32_bf16 v[2:5], v[142:145], v[134:137], v[2:5]
	ds_read_b128 v[134:137], v225 offset:25600
	ds_read_b128 v[142:145], v224 offset:3072
	s_add_i32 s12, s12, 1
	s_cmp_lg_u32 s12, 3
	s_cselect_b32 s12, s12, 0
	s_add_i32 s7, s7, 2
	s_cmp_lg_u32 s7, 64
	s_cbranch_scc1 .Lpa_c_loop
	s_waitcnt lgkmcnt(6)
	v_mfma_f32_16x16x32_bf16 v[94:97], v[106:109], v[110:113], v[94:97]
	s_waitcnt lgkmcnt(5)
	v_mfma_f32_16x16x32_bf16 v[90:93], v[106:109], v[114:117], v[90:93]
	s_waitcnt lgkmcnt(4)
	v_mfma_f32_16x16x32_bf16 v[86:89], v[106:109], v[122:125], v[86:89]
	s_waitcnt lgkmcnt(3)
	v_mfma_f32_16x16x32_bf16 v[82:85], v[106:109], v[126:129], v[82:85]
	s_waitcnt lgkmcnt(2)
	v_mfma_f32_16x16x32_bf16 v[78:81], v[106:109], v[130:133], v[78:81]
	s_waitcnt lgkmcnt(1)
	v_mfma_f32_16x16x32_bf16 v[74:77], v[106:109], v[134:137], v[74:77]
	s_waitcnt lgkmcnt(0)
	v_mfma_f32_16x16x32_bf16 v[70:73], v[118:121], v[110:113], v[70:73]
	v_mfma_f32_16x16x32_bf16 v[66:69], v[118:121], v[114:117], v[66:69]
	v_mfma_f32_16x16x32_bf16 v[62:65], v[118:121], v[122:125], v[62:65]
	v_mfma_f32_16x16x32_bf16 v[58:61], v[118:121], v[126:129], v[58:61]
	v_mfma_f32_16x16x32_bf16 v[54:57], v[118:121], v[130:133], v[54:57]
	v_mfma_f32_16x16x32_bf16 v[50:53], v[118:121], v[134:137], v[50:53]
	v_mfma_f32_16x16x32_bf16 v[46:49], v[138:141], v[110:113], v[46:49]
	v_mfma_f32_16x16x32_bf16 v[42:45], v[138:141], v[114:117], v[42:45]
	v_mfma_f32_16x16x32_bf16 v[38:41], v[138:141], v[122:125], v[38:41]
	v_mfma_f32_16x16x32_bf16 v[34:37], v[138:141], v[126:129], v[34:37]
	v_mfma_f32_16x16x32_bf16 v[30:33], v[138:141], v[130:133], v[30:33]
	v_mfma_f32_16x16x32_bf16 v[26:29], v[138:141], v[134:137], v[26:29]
	v_mfma_f32_16x16x32_bf16 v[22:25], v[142:145], v[110:113], v[22:25]
	v_mfma_f32_16x16x32_bf16 v[18:21], v[142:145], v[114:117], v[18:21]
	v_mfma_f32_16x16x32_bf16 v[14:17], v[142:145], v[122:125], v[14:17]
	v_mfma_f32_16x16x32_bf16 v[10:13], v[142:145], v[126:129], v[10:13]
	v_mfma_f32_16x16x32_bf16 v[6:9], v[142:145], v[130:133], v[6:9]
	v_mfma_f32_16x16x32_bf16 v[2:5], v[142:145], v[134:137], v[2:5]
; DI f32x4 mfma16(bf16x8 a, bf16x8 b, f32x4 c) { return __builtin_amdgcn_mfma_f32_16x16x32_bf16(a, b, c, 0, 0, 0); }
; template <int N> DI void wait_vm() { asm volatile("s_waitcnt vmcnt(%0)" ::"n"(N) : "memory"); }
;     ...
;     auto compute = [&](int cb, bool do_issue, int ikt, int ib) {
;         const char* base = lds + cb * BUF;
;         bf16x8 af[MT], bfr[NT];
; #pragma unroll
;         for (int nt = 0; nt < NT; ++nt) {
;             const int br = BM + (nt / NTS) * (BN / NSEG) + wc * (NTS * 16) + (nt % NTS) * 16;
;             bfr[nt] = *(const bf16x8*)(base + (br + l15) * 64 + rsw);
;         }
; #pragma unroll
;         for (int mt = 0; mt < MT; ++mt) af[mt] = *(const bf16x8*)(base + (wr * WM + mt * 16 + l15) * 64 + rsw);
;         constexpr int TOT = MT * NT, PER = (TOT + NIT - 1) / NIT;
; #pragma unroll
;         for (int part = 0; part < NIT; ++part) {
; #pragma unroll
;             for (int q = 0; q < PER; ++q) {
;                 const int idx = part * PER + q;
;                 if (idx < TOT) {
;                     const int mt = idx / NT, nt = idx % NT;
;                     acc[mt][nt] = SWAP ? mfma16(bfr[nt], af[mt], acc[mt][nt]) : mfma16(af[mt], bfr[nt], acc[mt][nt]);
;                 }
;             }
;             __builtin_amdgcn_sched_barrier(0);
;             if (do_issue) issue_one(ikt, ib, part);
;             __builtin_amdgcn_sched_barrier(0);
;         }
;     };
;     __syncthreads();
; #pragma unroll
;     for (int d = 0; d < D; ++d) issue(d, d);
;     int cb = 0, ib = D;
;     for (int kt = 0; kt < KT; ++kt) {
;         if (D > 1 && kt + D - 1 < KT) wait_vm<(D - 1) * NIT>(); else wait_vm<0>();
;         raw_barrier();
;         compute(cb, kt + D < KT, kt + D, ib);
;         cb = (cb + 1 == NST) ? 0 : cb + 1;
;         ib = (ib + 1 == NST) ? 0 : ib + 1;
;     }
; DI void unit_A(const Params& p, char* lds, int l, int chunk, int h) {
;     ...
;     float* stat = (float*)lds;
;     char* Vt = lds + 4096;
;     float lgv[2], lbv[2];
; #pragma unroll
;     for (int n2 = 0; n2 < 2; ++n2) { const int d = wc * 32 + n2 * 16 + l15; lgv[n2] = p.gm_ln_g[(l * 4 + h) * 128 + d]; lbv[n2] = p.gm_ln_b[(l * 4 + h) * 128 + d]; }
;     f32x4 bsv[4];
; #pragma unroll
;     for (int mt = 0; mt < 4; ++mt) bsv[mt] = *(const f32x4*)(p.gm_b_s + (l * 4 + h) * 128 + wr * 64 + mt * 16 + quad * 4);
.Lpa_join:
	s_waitcnt vmcnt(4)
	s_barrier
	v_add_u32_e32 v0, v103, v105
	ds_read_b128 v[98:101], v0
	v_add_u32_e32 v182, v103, v104
	ds_read_b128 v[102:105], v182 offset:8192
	ds_read_b128 v[106:109], v182 offset:9216
	ds_read_b128 v[110:113], v0 offset:1024
	ds_read_b128 v[114:117], v182 offset:16384
	ds_read_b128 v[118:121], v182 offset:17408
	v_bfe_u32 v192, v191, 6, 2
	v_ashrrev_i32_e32 v193, 8, v191
	s_waitcnt lgkmcnt(0)
	v_mfma_f32_16x16x32_bf16 v[122:125], v[98:101], v[118:121], v[82:85]
	s_nop 2
	ds_read_b128 v[82:85], v182 offset:24576
	ds_read_b128 v[126:129], v182 offset:25600
	s_waitcnt lgkmcnt(0)
	v_mfma_f32_16x16x32_bf16 v[130:133], v[98:101], v[82:85], v[78:81]
	s_nop 2
	ds_read_b128 v[78:81], v0 offset:2048
	ds_read_b128 v[134:137], v0 offset:3072
	v_mfma_f32_16x16x32_bf16 v[94:97], v[98:101], v[102:105], v[94:97]
	v_mfma_f32_16x16x32_bf16 v[90:93], v[98:101], v[106:109], v[90:93]
	v_mfma_f32_16x16x32_bf16 v[86:89], v[98:101], v[114:117], v[86:89]
	v_mfma_f32_16x16x32_bf16 v[98:101], v[98:101], v[126:129], v[74:77]
	v_mfma_f32_16x16x32_bf16 v[138:141], v[110:113], v[102:105], v[70:73]
	v_mfma_f32_16x16x32_bf16 v[142:145], v[110:113], v[106:109], v[66:69]
	v_mfma_f32_16x16x32_bf16 v[146:149], v[110:113], v[114:117], v[62:65]
	v_mfma_f32_16x16x32_bf16 v[150:153], v[110:113], v[118:121], v[58:61]
	v_mfma_f32_16x16x32_bf16 v[54:57], v[110:113], v[82:85], v[54:57]
	v_mfma_f32_16x16x32_bf16 v[110:113], v[110:113], v[126:129], v[50:53]
	s_waitcnt lgkmcnt(0)
	v_mfma_f32_16x16x32_bf16 v[154:157], v[78:81], v[102:105], v[46:49]
	v_mfma_f32_16x16x32_bf16 v[158:161], v[78:81], v[106:109], v[42:45]
	v_mfma_f32_16x16x32_bf16 v[162:165], v[78:81], v[114:117], v[38:41]
	v_mfma_f32_16x16x32_bf16 v[34:37], v[78:81], v[118:121], v[34:37]
	v_mfma_f32_16x16x32_bf16 v[166:169], v[78:81], v[82:85], v[30:33]
	v_mfma_f32_16x16x32_bf16 v[76:79], v[78:81], v[126:129], v[26:29]
	v_mfma_f32_16x16x32_bf16 v[102:105], v[134:137], v[102:105], v[22:25]
	v_mfma_f32_16x16x32_bf16 v[106:109], v[134:137], v[106:109], v[18:21]
	v_mfma_f32_16x16x32_bf16 v[14:17], v[134:137], v[114:117], v[14:17]
	v_mfma_f32_16x16x32_bf16 v[114:117], v[134:137], v[118:121], v[10:13]
	v_mfma_f32_16x16x32_bf16 v[118:121], v[134:137], v[82:85], v[6:9]
	v_mfma_f32_16x16x32_bf16 v[2:5], v[134:137], v[126:129], v[2:5]
	s_waitcnt vmcnt(0)
	s_barrier
	s_nop 0
	ds_read_b128 v[6:9], v0 offset:32768
	ds_read_b128 v[10:13], v182 offset:40960
	ds_read_b128 v[126:129], v182 offset:41984
	ds_read_b128 v[18:21], v0 offset:33792
	ds_read_b128 v[134:137], v182 offset:49152
	ds_read_b128 v[170:173], v182 offset:50176
	s_waitcnt lgkmcnt(0)
	v_mfma_f32_16x16x32_bf16 v[174:177], v[6:9], v[134:137], v[86:89]
	v_and_b32_e32 v194, 15, v191
	v_mfma_f32_16x16x32_bf16 v[178:181], v[6:9], v[170:173], v[122:125]
	s_nop 0
	ds_read_b128 v[84:87], v182 offset:57344
	s_nop 0
	ds_read_b128 v[122:125], v182 offset:58368
	s_waitcnt lgkmcnt(0)
	v_mfma_f32_16x16x32_bf16 v[72:75], v[6:9], v[84:87], v[130:133]
	ds_read_b128 v[22:25], v0 offset:34816
	s_nop 1
	ds_read_b128 v[130:133], v0 offset:35840
	v_mfma_f32_16x16x32_bf16 v[80:83], v[6:9], v[10:13], v[94:97]
	v_mfma_f32_16x16x32_bf16 v[68:71], v[6:9], v[126:129], v[90:93]
	v_mfma_f32_16x16x32_bf16 v[64:67], v[6:9], v[122:125], v[98:101]
	v_mfma_f32_16x16x32_bf16 v[60:63], v[18:21], v[10:13], v[138:141]
	v_mfma_f32_16x16x32_bf16 v[48:51], v[18:21], v[126:129], v[142:145]
	v_mfma_f32_16x16x32_bf16 v[182:185], v[18:21], v[134:137], v[146:149]
	v_mfma_f32_16x16x32_bf16 v[186:189], v[18:21], v[170:173], v[150:153]
	v_mfma_f32_16x16x32_bf16 v[52:55], v[18:21], v[84:87], v[54:57]
	v_mfma_f32_16x16x32_bf16 v[44:47], v[18:21], v[122:125], v[110:113]
	s_waitcnt lgkmcnt(0)
	v_mfma_f32_16x16x32_bf16 v[40:43], v[22:25], v[10:13], v[154:157]
	v_mfma_f32_16x16x32_bf16 v[28:31], v[22:25], v[126:129], v[158:161]
	v_mfma_f32_16x16x32_bf16 v[96:99], v[22:25], v[134:137], v[162:165]
	v_mfma_f32_16x16x32_bf16 v[92:95], v[22:25], v[170:173], v[34:37]
	v_mfma_f32_16x16x32_bf16 v[32:35], v[22:25], v[84:87], v[166:169]
	v_mfma_f32_16x16x32_bf16 v[24:27], v[22:25], v[122:125], v[76:79]
	v_mfma_f32_16x16x32_bf16 v[20:23], v[130:133], v[10:13], v[102:105]
	v_mfma_f32_16x16x32_bf16 v[8:11], v[130:133], v[126:129], v[106:109]
	v_mfma_f32_16x16x32_bf16 v[88:91], v[130:133], v[134:137], v[14:17]
	v_mfma_f32_16x16x32_bf16 v[76:79], v[130:133], v[170:173], v[114:117]
	v_mfma_f32_16x16x32_bf16 v[12:15], v[130:133], v[84:87], v[118:121]
	v_mfma_f32_16x16x32_bf16 v[4:7], v[130:133], v[122:125], v[2:5]
	s_lshl_b32 s6, s6, 7
	s_nop 1
	v_lshl_or_b32 v3, v192, 5, v194
	v_or_b32_e32 v16, s6, v3
	s_ashr_i32 s7, s6, 31
	v_ashrrev_i32_e32 v17, 31, v16
	s_lshl_b64 s[6:7], s[6:7], 2
	v_lshlrev_b64 v[16:17], 2, v[16:17]
	s_add_u32 s6, s60, s6
	v_lshlrev_b32_e32 v124, 6, v193
	v_lshl_add_u64 v[18:19], s[62:63], 0, v[16:17]
	v_lshl_add_u64 v[16:17], s[64:65], 0, v[16:17]
	s_addc_u32 s7, s61, s7
	v_ashrrev_i32_e32 v125, 31, v124
	s_waitcnt vmcnt(0)
	s_barrier
; DI float gelu_f(float x) {
;     const float t = x * (-2.30220819f + -0.102943240f * (x * x));
;     return x * __builtin_amdgcn_rcpf(1.f + __builtin_amdgcn_exp2f(t));
; }
; DI void unit_A(const Params& p, char* lds, int l, int chunk, int h) {
;     ...
;     for (int n2 = 0; n2 < 2; ++n2) { const int d = wc * 32 + n2 * 16 + l15; lgv[n2] = p.gm_ln_g[(l * 4 + h) * 128 + d]; lbv[n2] = p.gm_ln_b[(l * 4 + h) * 128 + d]; }
;     f32x4 bsv[4];
; #pragma unroll
;     for (int mt = 0; mt < 4; ++mt) bsv[mt] = *(const f32x4*)(p.gm_b_s + (l * 4 + h) * 128 + wr * 64 + mt * 16 + quad * 4);
;     {
;         float sv[4][4], ssv[4][4];
; #pragma unroll
;         for (int mt = 0; mt < 4; ++mt)
; #pragma unroll
;             for (int i = 0; i < 4; ++i) {
;                 float s = 0.f, ss = 0.f;
; #pragma unroll
;                 for (int n2 = 0; n2 < 2; ++n2) { const float v = gelu_f(acc[mt][2 + n2][i]); acc[mt][2 + n2][i] = v; s += v; ss += v * v; }
;                 sv[mt][i] = s; ssv[mt][i] = ss;
;             }
	global_load_dword v102, v[18:19], off
	global_load_dword v2, v[18:19], off offset:64
	global_load_dword v104, v[16:17], off
	global_load_dword v100, v[16:17], off offset:64
	v_lshl_add_u64 v[16:17], v[124:125], 2, s[6:7]
	v_lshlrev_b32_e32 v0, 4, v190
	v_lshl_add_u64 v[16:17], v[16:17], 0, v[0:1]
	v_mul_f32_e32 v0, v174, v174
	v_fmamk_f32 v0, v0, 0xbdd2d3e8, v213
	v_mul_f32_e32 v103, v178, v178
	v_mul_f32_e32 v0, v174, v0
	v_fmamk_f32 v103, v103, 0xbdd2d3e8, v213
	v_mul_f32_e32 v105, v175, v175
	v_exp_f32_e32 v0, v0
	v_mul_f32_e32 v103, v178, v103
	v_fmamk_f32 v105, v105, 0xbdd2d3e8, v213
	v_exp_f32_e32 v103, v103
	v_mul_f32_e32 v105, v175, v105
	v_exp_f32_e32 v105, v105
	v_add_f32_e32 v0, 1.0, v0
	v_rcp_f32_e32 v106, v0
	v_add_f32_e32 v0, 1.0, v103
	v_rcp_f32_e32 v108, v0
	v_add_f32_e32 v0, 1.0, v105
	v_rcp_f32_e32 v107, v0
	v_mul_f32_e32 v0, v179, v179
	v_fmamk_f32 v0, v0, 0xbdd2d3e8, v213
	v_mul_f32_e32 v0, v179, v0
	v_exp_f32_e32 v0, v0
	v_mul_f32_e32 v103, v180, v180
	v_fmamk_f32 v103, v103, 0xbdd2d3e8, v213
	v_mul_f32_e32 v105, v177, v177
	v_add_f32_e32 v0, 1.0, v0
	v_rcp_f32_e32 v109, v0
	v_mul_f32_e32 v0, v176, v176
	v_fmamk_f32 v0, v0, 0xbdd2d3e8, v213
	v_mul_f32_e32 v0, v176, v0
	v_exp_f32_e32 v0, v0
	v_mul_f32_e32 v103, v180, v103
	v_fmamk_f32 v105, v105, 0xbdd2d3e8, v213
	v_exp_f32_e32 v103, v103
	v_mul_f32_e32 v105, v177, v105
	v_exp_f32_e32 v105, v105
	v_add_f32_e32 v0, 1.0, v0
	v_pk_mul_f32 v[116:117], v[174:175], v[106:107]
	v_rcp_f32_e32 v106, v0
	v_add_f32_e32 v0, 1.0, v103
	v_pk_mul_f32 v[114:115], v[178:179], v[108:109]
	v_rcp_f32_e32 v108, v0
	v_add_f32_e32 v0, 1.0, v105
	v_rcp_f32_e32 v107, v0
	v_mul_f32_e32 v0, v181, v181
	v_fmamk_f32 v0, v0, 0xbdd2d3e8, v213
	v_mul_f32_e32 v0, v181, v0
	v_exp_f32_e32 v0, v0
	v_mul_f32_e32 v103, v186, v186
	v_fmamk_f32 v103, v103, 0xbdd2d3e8, v213
	v_mul_f32_e32 v105, v183, v183
	v_add_f32_e32 v0, 1.0, v0
	v_rcp_f32_e32 v109, v0
	v_mul_f32_e32 v0, v182, v182
	v_fmamk_f32 v0, v0, 0xbdd2d3e8, v213
	v_mul_f32_e32 v0, v182, v0
	v_exp_f32_e32 v0, v0
	v_mul_f32_e32 v103, v186, v103
	v_fmamk_f32 v105, v105, 0xbdd2d3e8, v213
	v_exp_f32_e32 v103, v103
	v_mul_f32_e32 v105, v183, v105
	v_exp_f32_e32 v105, v105
	v_add_f32_e32 v0, 1.0, v0
	v_pk_mul_f32 v[118:119], v[176:177], v[106:107]
	v_rcp_f32_e32 v106, v0
	v_add_f32_e32 v0, 1.0, v103
	v_rcp_f32_e32 v110, v0
	v_add_f32_e32 v0, 1.0, v105
	v_rcp_f32_e32 v107, v0
	v_mul_f32_e32 v0, v187, v187
	v_fmamk_f32 v0, v0, 0xbdd2d3e8, v213
	v_mul_f32_e32 v0, v187, v0
	v_exp_f32_e32 v0, v0
	v_mul_f32_e32 v103, v188, v188
	v_fmamk_f32 v103, v103, 0xbdd2d3e8, v213
	v_mul_f32_e32 v105, v185, v185
	v_add_f32_e32 v0, 1.0, v0
	v_rcp_f32_e32 v111, v0
	v_mul_f32_e32 v0, v184, v184
	v_fmamk_f32 v0, v0, 0xbdd2d3e8, v213
	v_mul_f32_e32 v0, v184, v0
	v_exp_f32_e32 v0, v0
	v_mul_f32_e32 v103, v188, v103
	v_fmamk_f32 v105, v105, 0xbdd2d3e8, v213
	v_exp_f32_e32 v103, v103
	v_mul_f32_e32 v105, v185, v105
	v_exp_f32_e32 v105, v105
	v_add_f32_e32 v0, 1.0, v0
	v_pk_mul_f32 v[120:121], v[180:181], v[108:109]
	v_pk_mul_f32 v[108:109], v[182:183], v[106:107]
	v_pk_mul_f32 v[106:107], v[186:187], v[110:111]
	v_rcp_f32_e32 v110, v0
	v_add_f32_e32 v0, 1.0, v103
	v_rcp_f32_e32 v112, v0
	v_add_f32_e32 v0, 1.0, v105
	v_rcp_f32_e32 v111, v0
	v_mul_f32_e32 v0, v189, v189
	v_fmamk_f32 v0, v0, 0xbdd2d3e8, v213
	v_mul_f32_e32 v0, v189, v0
	v_exp_f32_e32 v0, v0
	v_mul_f32_e32 v103, v92, v92
	v_fmamk_f32 v103, v103, 0xbdd2d3e8, v213
	v_mul_f32_e32 v105, v97, v97
	v_add_f32_e32 v0, 1.0, v0
	v_rcp_f32_e32 v113, v0
	v_mul_f32_e32 v0, v96, v96
	v_fmamk_f32 v0, v0, 0xbdd2d3e8, v213
	v_mul_f32_e32 v0, v96, v0
	v_exp_f32_e32 v0, v0
	v_mul_f32_e32 v103, v92, v103
	v_fmamk_f32 v105, v105, 0xbdd2d3e8, v213
	global_load_dwordx4 v[84:87], v[16:17], off
	global_load_dwordx4 v[56:59], v[16:17], off offset:64
	global_load_dwordx4 v[36:39], v[16:17], off offset:128
	s_nop 0
	global_load_dwordx4 v[16:19], v[16:17], off offset:192
	v_exp_f32_e32 v103, v103
	v_mul_f32_e32 v105, v97, v105
	v_exp_f32_e32 v105, v105
	v_add_f32_e32 v0, 1.0, v0
	v_rcp_f32_e32 v126, v0
	v_add_f32_e32 v0, 1.0, v103
	v_rcp_f32_e32 v160, v0
	v_add_f32_e32 v0, 1.0, v105
	v_rcp_f32_e32 v127, v0
	v_mul_f32_e32 v0, v93, v93
	v_fmamk_f32 v0, v0, 0xbdd2d3e8, v213
	v_mul_f32_e32 v0, v93, v0
	v_exp_f32_e32 v0, v0
	v_mul_f32_e32 v103, v94, v94
	v_fmamk_f32 v103, v103, 0xbdd2d3e8, v213
	v_mul_f32_e32 v105, v99, v99
	v_add_f32_e32 v0, 1.0, v0
	v_rcp_f32_e32 v161, v0
	v_mul_f32_e32 v0, v98, v98
	v_fmamk_f32 v0, v0, 0xbdd2d3e8, v213
	v_mul_f32_e32 v0, v98, v0
	v_exp_f32_e32 v0, v0
	v_mul_f32_e32 v103, v94, v103
	v_fmamk_f32 v105, v105, 0xbdd2d3e8, v213
	v_exp_f32_e32 v103, v103
	v_mul_f32_e32 v105, v99, v105
	v_exp_f32_e32 v105, v105
	v_add_f32_e32 v0, 1.0, v0
	v_pk_mul_f32 v[96:97], v[96:97], v[126:127]
	v_rcp_f32_e32 v126, v0
	v_add_f32_e32 v0, 1.0, v103
	v_pk_mul_f32 v[92:93], v[92:93], v[160:161]
	v_rcp_f32_e32 v160, v0
	v_add_f32_e32 v0, 1.0, v105
	v_rcp_f32_e32 v127, v0
	v_mul_f32_e32 v0, v95, v95
	v_fmamk_f32 v0, v0, 0xbdd2d3e8, v213
	v_mul_f32_e32 v0, v95, v0
	v_exp_f32_e32 v0, v0
	v_mul_f32_e32 v103, v76, v76
	v_fmamk_f32 v103, v103, 0xbdd2d3e8, v213
	v_mul_f32_e32 v105, v89, v89
	v_add_f32_e32 v0, 1.0, v0
	v_rcp_f32_e32 v161, v0
	v_mul_f32_e32 v0, v88, v88
	v_fmamk_f32 v0, v0, 0xbdd2d3e8, v213
	v_mul_f32_e32 v0, v88, v0
	v_exp_f32_e32 v0, v0
	v_mul_f32_e32 v103, v76, v103
	v_fmamk_f32 v105, v105, 0xbdd2d3e8, v213
	v_exp_f32_e32 v103, v103
	v_mul_f32_e32 v105, v89, v105
	v_exp_f32_e32 v105, v105
	v_add_f32_e32 v0, 1.0, v0
	v_pk_mul_f32 v[98:99], v[98:99], v[126:127]
	v_rcp_f32_e32 v126, v0
	v_add_f32_e32 v0, 1.0, v103
; template <int CTRL> DI float dpp_f(float v) { return __builtin_bit_cast(float, __builtin_amdgcn_update_dpp(0, __builtin_bit_cast(int, v), CTRL, 0xF, 0xF, true)); }
; DI float row16_sum(float v) {
;     v += dpp_f<0xB1>(v);
;     v += dpp_f<0x4E>(v);
;     v += dpp_f<0x141>(v);
;     v += dpp_f<0x140>(v);
;     return v;
; }
; DI void unit_A(const Params& p, char* lds, int l, int chunk, int h) {
;     ...
;         for (int mt = 0; mt < 4; ++mt)
; #pragma unroll
;             for (int i = 0; i < 4; ++i) {
;                 float s = 0.f, ss = 0.f;
; #pragma unroll
;                 for (int n2 = 0; n2 < 2; ++n2) { const float v = gelu_f(acc[mt][2 + n2][i]); acc[mt][2 + n2][i] = v; s += v; ss += v * v; }
;                 sv[mt][i] = s; ssv[mt][i] = ss;
;             }
; #pragma unroll
;         for (int mt = 0; mt < 4; ++mt)
; #pragma unroll
;             for (int i = 0; i < 4; ++i) { sv[mt][i] = row16_sum(sv[mt][i]); ssv[mt][i] = row16_sum(ssv[mt][i]); }
	v_pk_mul_f32 v[94:95], v[94:95], v[160:161]
	v_rcp_f32_e32 v160, v0
	v_add_f32_e32 v0, 1.0, v105
	v_rcp_f32_e32 v127, v0
	v_mul_f32_e32 v0, v77, v77
	v_fmamk_f32 v0, v0, 0xbdd2d3e8, v213
	v_mul_f32_e32 v0, v77, v0
	v_exp_f32_e32 v0, v0
	v_mul_f32_e32 v103, v91, v91
	v_fmamk_f32 v103, v103, 0xbdd2d3e8, v213
	v_mul_f32_e32 v103, v91, v103
	v_add_f32_e32 v0, 1.0, v0
	v_rcp_f32_e32 v161, v0
	v_mul_f32_e32 v0, v90, v90
	v_fmamk_f32 v0, v0, 0xbdd2d3e8, v213
	v_mul_f32_e32 v0, v90, v0
	v_exp_f32_e32 v0, v0
	v_exp_f32_e32 v103, v103
	v_pk_mul_f32 v[88:89], v[88:89], v[126:127]
	v_pk_mul_f32 v[128:129], v[116:117], v[116:117]
	v_add_f32_e32 v0, 1.0, v0
	v_rcp_f32_e32 v126, v0
	v_mul_f32_e32 v0, v78, v78
	v_add_f32_e32 v103, 1.0, v103
	v_fmamk_f32 v0, v0, 0xbdd2d3e8, v213
	v_rcp_f32_e32 v127, v103
	v_mul_f32_e32 v103, v79, v79
	v_mul_f32_e32 v0, v78, v0
	v_fmamk_f32 v103, v103, 0xbdd2d3e8, v213
	v_exp_f32_e32 v0, v0
	v_mul_f32_e32 v103, v79, v103
	v_exp_f32_e32 v103, v103
	v_pk_mul_f32 v[132:133], v[114:115], v[114:115]
	v_add_f32_e32 v0, 1.0, v0
	v_add_f32_e32 v130, 0, v117
	v_pk_mul_f32 v[136:137], v[118:119], v[118:119]
	v_pk_mul_f32 v[140:141], v[120:121], v[120:121]
	v_rcp_f32_e32 v170, v0
	v_pk_mul_f32 v[90:91], v[90:91], v[126:127]
	v_add_f32_e32 v0, 1.0, v103
	v_mov_b32_e32 v127, v132
	v_mov_b32_e32 v131, v129
	v_mov_b32_e32 v132, v115
	v_add_f32_e32 v138, 0, v119
	v_pk_mul_f32 v[144:145], v[108:109], v[108:109]
	v_pk_mul_f32 v[148:149], v[106:107], v[106:107]
	v_pk_mul_f32 v[110:111], v[184:185], v[110:111]
	v_pk_mul_f32 v[112:113], v[188:189], v[112:113]
	v_rcp_f32_e32 v171, v0
	v_mov_b32_e32 v123, v128
	v_pk_add_f32 v[128:129], v[130:131], v[132:133]
	v_mov_b32_e32 v133, v140
	v_mov_b32_e32 v139, v137
	v_mov_b32_e32 v140, v121
	v_add_f32_e32 v146, 0, v109
	v_pk_mul_f32 v[152:153], v[110:111], v[110:111]
	v_pk_mul_f32 v[156:157], v[112:113], v[112:113]
	v_mov_b32_e32 v135, v136
	v_pk_add_f32 v[136:137], v[138:139], v[140:141]
	v_mov_b32_e32 v141, v148
	v_mov_b32_e32 v147, v145
	v_mov_b32_e32 v148, v107
	v_add_f32_e32 v154, 0, v111
	v_pk_mul_f32 v[168:169], v[96:97], v[96:97]
	v_pk_mul_f32 v[182:183], v[92:93], v[92:93]
	v_mov_b32_e32 v143, v144
	v_pk_add_f32 v[144:145], v[146:147], v[148:149]
	v_mov_b32_e32 v149, v156
	v_mov_b32_e32 v155, v153
	v_mov_b32_e32 v156, v113
	v_add_f32_e32 v178, 0, v97
	v_pk_mul_f32 v[164:165], v[98:99], v[98:99]
	v_pk_mul_f32 v[180:181], v[94:95], v[94:95]
	v_pk_mul_f32 v[76:77], v[76:77], v[160:161]
	v_mov_b32_e32 v151, v152
	v_pk_add_f32 v[152:153], v[154:155], v[156:157]
	v_mov_b32_e32 v157, v182
	v_mov_b32_e32 v179, v169
	v_mov_b32_e32 v182, v93
	v_add_f32_e32 v176, 0, v99
	v_pk_mul_f32 v[162:163], v[88:89], v[88:89]
	v_pk_mul_f32 v[174:175], v[76:77], v[76:77]
	v_pk_mul_f32 v[78:79], v[78:79], v[170:171]
	v_mov_b32_e32 v159, v168
	v_pk_add_f32 v[168:169], v[178:179], v[182:183]
	v_mov_b32_e32 v183, v180
	v_mov_b32_e32 v177, v165
	v_mov_b32_e32 v180, v95
	v_add_f32_e32 v172, 0, v89
	v_pk_mul_f32 v[166:167], v[90:91], v[90:91]
	v_pk_mul_f32 v[170:171], v[78:79], v[78:79]
	v_mov_b32_e32 v189, v164
	v_pk_add_f32 v[164:165], v[176:177], v[180:181]
	v_mov_b32_e32 v181, v174
	v_mov_b32_e32 v173, v163
	v_mov_b32_e32 v174, v77
	v_add_f32_e32 v122, 0, v116
	v_add_f32_e32 v134, 0, v118
	v_add_f32_e32 v142, 0, v108
	v_add_f32_e32 v150, 0, v110
	v_add_f32_e32 v158, 0, v96
	v_add_f32_e32 v188, 0, v98
	v_add_f32_e32 v184, 0, v88
	v_add_f32_e32 v186, 0, v90
	v_add_f32_e32 v160, 0, v91
	v_mov_b32_e32 v126, v114
	v_mov_b32_e32 v132, v120
	v_mov_b32_e32 v140, v106
	v_mov_b32_e32 v148, v112
	v_mov_b32_e32 v156, v92
	v_mov_b32_e32 v182, v94
	v_mov_b32_e32 v185, v162
	v_mov_b32_e32 v180, v76
	v_pk_add_f32 v[162:163], v[172:173], v[174:175]
	v_mov_b32_e32 v187, v166
	v_mov_b32_e32 v174, v78
	v_mov_b32_e32 v175, v170
	v_mov_b32_e32 v161, v167
	v_mov_b32_e32 v170, v79
	v_pk_add_f32 v[122:123], v[122:123], v[126:127]
	v_pk_add_f32 v[132:133], v[134:135], v[132:133]
	v_pk_add_f32 v[140:141], v[142:143], v[140:141]
	v_pk_add_f32 v[148:149], v[150:151], v[148:149]
	v_pk_add_f32 v[156:157], v[158:159], v[156:157]
	v_pk_add_f32 v[182:183], v[188:189], v[182:183]
	v_pk_add_f32 v[180:181], v[184:185], v[180:181]
	v_pk_add_f32 v[174:175], v[186:187], v[174:175]
	v_pk_add_f32 v[160:161], v[160:161], v[170:171]
	v_mov_b32_dpp v126, v122 quad_perm:[1,0,3,2] row_mask:0xf bank_mask:0xf bound_ctrl:1
	v_mov_b32_dpp v127, v123 quad_perm:[1,0,3,2] row_mask:0xf bank_mask:0xf bound_ctrl:1
	v_mov_b32_dpp v130, v128 quad_perm:[1,0,3,2] row_mask:0xf bank_mask:0xf bound_ctrl:1
	v_mov_b32_dpp v131, v129 quad_perm:[1,0,3,2] row_mask:0xf bank_mask:0xf bound_ctrl:1
	v_mov_b32_dpp v134, v132 quad_perm:[1,0,3,2] row_mask:0xf bank_mask:0xf bound_ctrl:1
	v_mov_b32_dpp v135, v133 quad_perm:[1,0,3,2] row_mask:0xf bank_mask:0xf bound_ctrl:1
	v_mov_b32_dpp v138, v136 quad_perm:[1,0,3,2] row_mask:0xf bank_mask:0xf bound_ctrl:1
	v_mov_b32_dpp v139, v137 quad_perm:[1,0,3,2] row_mask:0xf bank_mask:0xf bound_ctrl:1
	v_mov_b32_dpp v142, v140 quad_perm:[1,0,3,2] row_mask:0xf bank_mask:0xf bound_ctrl:1
	v_mov_b32_dpp v143, v141 quad_perm:[1,0,3,2] row_mask:0xf bank_mask:0xf bound_ctrl:1
	v_mov_b32_dpp v146, v144 quad_perm:[1,0,3,2] row_mask:0xf bank_mask:0xf bound_ctrl:1
	v_mov_b32_dpp v147, v145 quad_perm:[1,0,3,2] row_mask:0xf bank_mask:0xf bound_ctrl:1
	v_mov_b32_dpp v150, v148 quad_perm:[1,0,3,2] row_mask:0xf bank_mask:0xf bound_ctrl:1
	v_mov_b32_dpp v151, v149 quad_perm:[1,0,3,2] row_mask:0xf bank_mask:0xf bound_ctrl:1
	v_mov_b32_dpp v154, v152 quad_perm:[1,0,3,2] row_mask:0xf bank_mask:0xf bound_ctrl:1
	v_mov_b32_dpp v155, v153 quad_perm:[1,0,3,2] row_mask:0xf bank_mask:0xf bound_ctrl:1
; template <int CTRL> DI float dpp_f(float v) { return __builtin_bit_cast(float, __builtin_amdgcn_update_dpp(0, __builtin_bit_cast(int, v), CTRL, 0xF, 0xF, true)); }
; DI float row16_sum(float v) {
;     v += dpp_f<0xB1>(v);
;     v += dpp_f<0x4E>(v);
;     v += dpp_f<0x141>(v);
;     v += dpp_f<0x140>(v);
;     return v;
; }
; DI void unit_A(const Params& p, char* lds, int l, int chunk, int h) {
;     ...
;         for (int mt = 0; mt < 4; ++mt)
; #pragma unroll
;             for (int i = 0; i < 4; ++i) { sv[mt][i] = row16_sum(sv[mt][i]); ssv[mt][i] = row16_sum(ssv[mt][i]); }
	v_mov_b32_dpp v158, v156 quad_perm:[1,0,3,2] row_mask:0xf bank_mask:0xf bound_ctrl:1
	v_mov_b32_dpp v159, v157 quad_perm:[1,0,3,2] row_mask:0xf bank_mask:0xf bound_ctrl:1
	v_mov_b32_dpp v178, v168 quad_perm:[1,0,3,2] row_mask:0xf bank_mask:0xf bound_ctrl:1
	v_mov_b32_dpp v179, v169 quad_perm:[1,0,3,2] row_mask:0xf bank_mask:0xf bound_ctrl:1
	v_mov_b32_dpp v188, v182 quad_perm:[1,0,3,2] row_mask:0xf bank_mask:0xf bound_ctrl:1
	v_mov_b32_dpp v189, v183 quad_perm:[1,0,3,2] row_mask:0xf bank_mask:0xf bound_ctrl:1
	v_mov_b32_dpp v176, v164 quad_perm:[1,0,3,2] row_mask:0xf bank_mask:0xf bound_ctrl:1
	v_mov_b32_dpp v177, v165 quad_perm:[1,0,3,2] row_mask:0xf bank_mask:0xf bound_ctrl:1
	v_mov_b32_dpp v184, v180 quad_perm:[1,0,3,2] row_mask:0xf bank_mask:0xf bound_ctrl:1
	v_mov_b32_dpp v185, v181 quad_perm:[1,0,3,2] row_mask:0xf bank_mask:0xf bound_ctrl:1
	v_mov_b32_dpp v172, v162 quad_perm:[1,0,3,2] row_mask:0xf bank_mask:0xf bound_ctrl:1
	v_mov_b32_dpp v173, v163 quad_perm:[1,0,3,2] row_mask:0xf bank_mask:0xf bound_ctrl:1
	v_mov_b32_dpp v186, v174 quad_perm:[1,0,3,2] row_mask:0xf bank_mask:0xf bound_ctrl:1
	v_mov_b32_dpp v187, v175 quad_perm:[1,0,3,2] row_mask:0xf bank_mask:0xf bound_ctrl:1
	v_mov_b32_dpp v166, v160 quad_perm:[1,0,3,2] row_mask:0xf bank_mask:0xf bound_ctrl:1
	v_mov_b32_dpp v167, v161 quad_perm:[1,0,3,2] row_mask:0xf bank_mask:0xf bound_ctrl:1
	v_pk_add_f32 v[122:123], v[122:123], v[126:127]
	v_pk_add_f32 v[128:129], v[128:129], v[130:131]
	v_pk_add_f32 v[132:133], v[132:133], v[134:135]
	v_pk_add_f32 v[136:137], v[136:137], v[138:139]
	v_pk_add_f32 v[140:141], v[140:141], v[142:143]
	v_pk_add_f32 v[144:145], v[144:145], v[146:147]
	v_pk_add_f32 v[148:149], v[148:149], v[150:151]
	v_pk_add_f32 v[152:153], v[152:153], v[154:155]
	v_pk_add_f32 v[156:157], v[156:157], v[158:159]
	v_pk_add_f32 v[168:169], v[168:169], v[178:179]
	v_pk_add_f32 v[182:183], v[182:183], v[188:189]
	v_pk_add_f32 v[164:165], v[164:165], v[176:177]
	v_pk_add_f32 v[180:181], v[180:181], v[184:185]
	v_pk_add_f32 v[162:163], v[162:163], v[172:173]
	v_pk_add_f32 v[174:175], v[174:175], v[186:187]
	v_pk_add_f32 v[160:161], v[160:161], v[166:167]
	v_mov_b32_dpp v126, v122 quad_perm:[2,3,0,1] row_mask:0xf bank_mask:0xf bound_ctrl:1
	v_mov_b32_dpp v127, v123 quad_perm:[2,3,0,1] row_mask:0xf bank_mask:0xf bound_ctrl:1
	v_mov_b32_dpp v130, v128 quad_perm:[2,3,0,1] row_mask:0xf bank_mask:0xf bound_ctrl:1
	v_mov_b32_dpp v131, v129 quad_perm:[2,3,0,1] row_mask:0xf bank_mask:0xf bound_ctrl:1
	v_mov_b32_dpp v134, v132 quad_perm:[2,3,0,1] row_mask:0xf bank_mask:0xf bound_ctrl:1
	v_mov_b32_dpp v135, v133 quad_perm:[2,3,0,1] row_mask:0xf bank_mask:0xf bound_ctrl:1
	v_mov_b32_dpp v138, v136 quad_perm:[2,3,0,1] row_mask:0xf bank_mask:0xf bound_ctrl:1
	v_mov_b32_dpp v139, v137 quad_perm:[2,3,0,1] row_mask:0xf bank_mask:0xf bound_ctrl:1
	v_mov_b32_dpp v142, v140 quad_perm:[2,3,0,1] row_mask:0xf bank_mask:0xf bound_ctrl:1
	v_mov_b32_dpp v143, v141 quad_perm:[2,3,0,1] row_mask:0xf bank_mask:0xf bound_ctrl:1
	v_mov_b32_dpp v146, v144 quad_perm:[2,3,0,1] row_mask:0xf bank_mask:0xf bound_ctrl:1
	v_mov_b32_dpp v147, v145 quad_perm:[2,3,0,1] row_mask:0xf bank_mask:0xf bound_ctrl:1
	v_mov_b32_dpp v150, v148 quad_perm:[2,3,0,1] row_mask:0xf bank_mask:0xf bound_ctrl:1
	v_mov_b32_dpp v151, v149 quad_perm:[2,3,0,1] row_mask:0xf bank_mask:0xf bound_ctrl:1
	v_mov_b32_dpp v154, v152 quad_perm:[2,3,0,1] row_mask:0xf bank_mask:0xf bound_ctrl:1
	v_mov_b32_dpp v155, v153 quad_perm:[2,3,0,1] row_mask:0xf bank_mask:0xf bound_ctrl:1
	v_mov_b32_dpp v158, v156 quad_perm:[2,3,0,1] row_mask:0xf bank_mask:0xf bound_ctrl:1
	v_mov_b32_dpp v159, v157 quad_perm:[2,3,0,1] row_mask:0xf bank_mask:0xf bound_ctrl:1
	v_mov_b32_dpp v178, v168 quad_perm:[2,3,0,1] row_mask:0xf bank_mask:0xf bound_ctrl:1
	v_mov_b32_dpp v179, v169 quad_perm:[2,3,0,1] row_mask:0xf bank_mask:0xf bound_ctrl:1
	v_mov_b32_dpp v188, v182 quad_perm:[2,3,0,1] row_mask:0xf bank_mask:0xf bound_ctrl:1
	v_mov_b32_dpp v189, v183 quad_perm:[2,3,0,1] row_mask:0xf bank_mask:0xf bound_ctrl:1
	v_mov_b32_dpp v176, v164 quad_perm:[2,3,0,1] row_mask:0xf bank_mask:0xf bound_ctrl:1
	v_mov_b32_dpp v177, v165 quad_perm:[2,3,0,1] row_mask:0xf bank_mask:0xf bound_ctrl:1
	v_mov_b32_dpp v184, v180 quad_perm:[2,3,0,1] row_mask:0xf bank_mask:0xf bound_ctrl:1
	v_mov_b32_dpp v185, v181 quad_perm:[2,3,0,1] row_mask:0xf bank_mask:0xf bound_ctrl:1
	v_mov_b32_dpp v172, v162 quad_perm:[2,3,0,1] row_mask:0xf bank_mask:0xf bound_ctrl:1
	v_mov_b32_dpp v173, v163 quad_perm:[2,3,0,1] row_mask:0xf bank_mask:0xf bound_ctrl:1
	v_mov_b32_dpp v186, v174 quad_perm:[2,3,0,1] row_mask:0xf bank_mask:0xf bound_ctrl:1
	v_mov_b32_dpp v187, v175 quad_perm:[2,3,0,1] row_mask:0xf bank_mask:0xf bound_ctrl:1
	v_mov_b32_dpp v166, v160 quad_perm:[2,3,0,1] row_mask:0xf bank_mask:0xf bound_ctrl:1
	v_mov_b32_dpp v167, v161 quad_perm:[2,3,0,1] row_mask:0xf bank_mask:0xf bound_ctrl:1
	v_pk_add_f32 v[122:123], v[122:123], v[126:127]
	v_pk_add_f32 v[128:129], v[128:129], v[130:131]
	v_pk_add_f32 v[132:133], v[132:133], v[134:135]
	v_pk_add_f32 v[136:137], v[136:137], v[138:139]
	v_pk_add_f32 v[140:141], v[140:141], v[142:143]
	v_pk_add_f32 v[144:145], v[144:145], v[146:147]
	v_pk_add_f32 v[148:149], v[148:149], v[150:151]
	v_pk_add_f32 v[152:153], v[152:153], v[154:155]
	v_pk_add_f32 v[156:157], v[156:157], v[158:159]
	v_pk_add_f32 v[168:169], v[168:169], v[178:179]
	v_pk_add_f32 v[182:183], v[182:183], v[188:189]
	v_pk_add_f32 v[164:165], v[164:165], v[176:177]
	v_pk_add_f32 v[180:181], v[180:181], v[184:185]
	v_pk_add_f32 v[162:163], v[162:163], v[172:173]
	v_pk_add_f32 v[174:175], v[174:175], v[186:187]
; template <int CTRL> DI float dpp_f(float v) { return __builtin_bit_cast(float, __builtin_amdgcn_update_dpp(0, __builtin_bit_cast(int, v), CTRL, 0xF, 0xF, true)); }
; DI float row16_sum(float v) {
;     v += dpp_f<0xB1>(v);
;     v += dpp_f<0x4E>(v);
;     v += dpp_f<0x141>(v);
;     v += dpp_f<0x140>(v);
;     return v;
; }
; DI void unit_A(const Params& p, char* lds, int l, int chunk, int h) {
;     ...
;         for (int mt = 0; mt < 4; ++mt)
; #pragma unroll
;             for (int i = 0; i < 4; ++i) { sv[mt][i] = row16_sum(sv[mt][i]); ssv[mt][i] = row16_sum(ssv[mt][i]); }
;         if (l15 == 0) {
; #pragma unroll
;             for (int mt = 0; mt < 4; ++mt)
; #pragma unroll
;                 for (int i = 0; i < 4; ++i) { const int row = wr * 64 + mt * 16 + quad * 4 + i; *(f32x2*)&stat[(row * 4 + wc) * 2] = (f32x2){sv[mt][i], ssv[mt][i]}; }
;         }
	v_pk_add_f32 v[160:161], v[160:161], v[166:167]
	v_lshlrev_b32_e32 v101, 2, v190
	v_mov_b32_dpp v126, v122 row_half_mirror row_mask:0xf bank_mask:0xf bound_ctrl:1
	v_mov_b32_dpp v127, v123 row_half_mirror row_mask:0xf bank_mask:0xf bound_ctrl:1
	v_mov_b32_dpp v130, v128 row_half_mirror row_mask:0xf bank_mask:0xf bound_ctrl:1
	v_mov_b32_dpp v131, v129 row_half_mirror row_mask:0xf bank_mask:0xf bound_ctrl:1
	v_mov_b32_dpp v134, v132 row_half_mirror row_mask:0xf bank_mask:0xf bound_ctrl:1
	v_mov_b32_dpp v135, v133 row_half_mirror row_mask:0xf bank_mask:0xf bound_ctrl:1
	v_mov_b32_dpp v138, v136 row_half_mirror row_mask:0xf bank_mask:0xf bound_ctrl:1
	v_mov_b32_dpp v139, v137 row_half_mirror row_mask:0xf bank_mask:0xf bound_ctrl:1
	v_mov_b32_dpp v142, v140 row_half_mirror row_mask:0xf bank_mask:0xf bound_ctrl:1
	v_mov_b32_dpp v143, v141 row_half_mirror row_mask:0xf bank_mask:0xf bound_ctrl:1
	v_mov_b32_dpp v146, v144 row_half_mirror row_mask:0xf bank_mask:0xf bound_ctrl:1
	v_mov_b32_dpp v147, v145 row_half_mirror row_mask:0xf bank_mask:0xf bound_ctrl:1
	v_mov_b32_dpp v150, v148 row_half_mirror row_mask:0xf bank_mask:0xf bound_ctrl:1
	v_mov_b32_dpp v151, v149 row_half_mirror row_mask:0xf bank_mask:0xf bound_ctrl:1
	v_mov_b32_dpp v154, v152 row_half_mirror row_mask:0xf bank_mask:0xf bound_ctrl:1
	v_mov_b32_dpp v155, v153 row_half_mirror row_mask:0xf bank_mask:0xf bound_ctrl:1
	v_mov_b32_dpp v158, v156 row_half_mirror row_mask:0xf bank_mask:0xf bound_ctrl:1
	v_mov_b32_dpp v159, v157 row_half_mirror row_mask:0xf bank_mask:0xf bound_ctrl:1
	v_mov_b32_dpp v178, v168 row_half_mirror row_mask:0xf bank_mask:0xf bound_ctrl:1
	v_mov_b32_dpp v179, v169 row_half_mirror row_mask:0xf bank_mask:0xf bound_ctrl:1
	v_mov_b32_dpp v188, v182 row_half_mirror row_mask:0xf bank_mask:0xf bound_ctrl:1
	v_mov_b32_dpp v189, v183 row_half_mirror row_mask:0xf bank_mask:0xf bound_ctrl:1
	v_mov_b32_dpp v176, v164 row_half_mirror row_mask:0xf bank_mask:0xf bound_ctrl:1
	v_mov_b32_dpp v177, v165 row_half_mirror row_mask:0xf bank_mask:0xf bound_ctrl:1
	v_mov_b32_dpp v184, v180 row_half_mirror row_mask:0xf bank_mask:0xf bound_ctrl:1
	v_mov_b32_dpp v185, v181 row_half_mirror row_mask:0xf bank_mask:0xf bound_ctrl:1
	v_mov_b32_dpp v172, v162 row_half_mirror row_mask:0xf bank_mask:0xf bound_ctrl:1
	v_mov_b32_dpp v173, v163 row_half_mirror row_mask:0xf bank_mask:0xf bound_ctrl:1
	v_mov_b32_dpp v186, v174 row_half_mirror row_mask:0xf bank_mask:0xf bound_ctrl:1
	v_mov_b32_dpp v187, v175 row_half_mirror row_mask:0xf bank_mask:0xf bound_ctrl:1
	v_mov_b32_dpp v166, v160 row_half_mirror row_mask:0xf bank_mask:0xf bound_ctrl:1
	v_mov_b32_dpp v167, v161 row_half_mirror row_mask:0xf bank_mask:0xf bound_ctrl:1
	v_pk_add_f32 v[122:123], v[122:123], v[126:127]
	v_pk_add_f32 v[128:129], v[128:129], v[130:131]
	v_pk_add_f32 v[132:133], v[132:133], v[134:135]
	v_pk_add_f32 v[136:137], v[136:137], v[138:139]
	v_pk_add_f32 v[140:141], v[140:141], v[142:143]
	v_pk_add_f32 v[144:145], v[144:145], v[146:147]
	v_pk_add_f32 v[148:149], v[148:149], v[150:151]
	v_pk_add_f32 v[152:153], v[152:153], v[154:155]
	v_pk_add_f32 v[156:157], v[156:157], v[158:159]
	v_pk_add_f32 v[168:169], v[168:169], v[178:179]
	v_pk_add_f32 v[182:183], v[182:183], v[188:189]
	v_pk_add_f32 v[164:165], v[164:165], v[176:177]
	v_pk_add_f32 v[180:181], v[180:181], v[184:185]
	v_pk_add_f32 v[162:163], v[162:163], v[172:173]
	v_pk_add_f32 v[174:175], v[174:175], v[186:187]
	v_pk_add_f32 v[160:161], v[160:161], v[166:167]
	v_or_b32_e32 v204, v101, v124
	v_mov_b32_dpp v126, v122 row_mirror row_mask:0xf bank_mask:0xf bound_ctrl:1
	v_mov_b32_dpp v127, v123 row_mirror row_mask:0xf bank_mask:0xf bound_ctrl:1
	v_mov_b32_dpp v130, v128 row_mirror row_mask:0xf bank_mask:0xf bound_ctrl:1
	v_mov_b32_dpp v131, v129 row_mirror row_mask:0xf bank_mask:0xf bound_ctrl:1
	v_mov_b32_dpp v134, v132 row_mirror row_mask:0xf bank_mask:0xf bound_ctrl:1
	v_mov_b32_dpp v135, v133 row_mirror row_mask:0xf bank_mask:0xf bound_ctrl:1
	v_mov_b32_dpp v138, v136 row_mirror row_mask:0xf bank_mask:0xf bound_ctrl:1
	v_mov_b32_dpp v139, v137 row_mirror row_mask:0xf bank_mask:0xf bound_ctrl:1
	v_mov_b32_dpp v142, v140 row_mirror row_mask:0xf bank_mask:0xf bound_ctrl:1
	v_mov_b32_dpp v143, v141 row_mirror row_mask:0xf bank_mask:0xf bound_ctrl:1
	v_mov_b32_dpp v146, v144 row_mirror row_mask:0xf bank_mask:0xf bound_ctrl:1
	v_mov_b32_dpp v147, v145 row_mirror row_mask:0xf bank_mask:0xf bound_ctrl:1
	v_mov_b32_dpp v150, v148 row_mirror row_mask:0xf bank_mask:0xf bound_ctrl:1
	v_mov_b32_dpp v151, v149 row_mirror row_mask:0xf bank_mask:0xf bound_ctrl:1
	v_mov_b32_dpp v154, v152 row_mirror row_mask:0xf bank_mask:0xf bound_ctrl:1
	v_mov_b32_dpp v155, v153 row_mirror row_mask:0xf bank_mask:0xf bound_ctrl:1
	v_mov_b32_dpp v158, v156 row_mirror row_mask:0xf bank_mask:0xf bound_ctrl:1
	v_mov_b32_dpp v159, v157 row_mirror row_mask:0xf bank_mask:0xf bound_ctrl:1
	v_mov_b32_dpp v178, v168 row_mirror row_mask:0xf bank_mask:0xf bound_ctrl:1
	v_mov_b32_dpp v179, v169 row_mirror row_mask:0xf bank_mask:0xf bound_ctrl:1
	v_mov_b32_dpp v188, v182 row_mirror row_mask:0xf bank_mask:0xf bound_ctrl:1
	v_mov_b32_dpp v189, v183 row_mirror row_mask:0xf bank_mask:0xf bound_ctrl:1
	v_mov_b32_dpp v176, v164 row_mirror row_mask:0xf bank_mask:0xf bound_ctrl:1
	v_mov_b32_dpp v177, v165 row_mirror row_mask:0xf bank_mask:0xf bound_ctrl:1
	v_mov_b32_dpp v184, v180 row_mirror row_mask:0xf bank_mask:0xf bound_ctrl:1
	v_mov_b32_dpp v185, v181 row_mirror row_mask:0xf bank_mask:0xf bound_ctrl:1
	v_mov_b32_dpp v172, v162 row_mirror row_mask:0xf bank_mask:0xf bound_ctrl:1
	v_mov_b32_dpp v173, v163 row_mirror row_mask:0xf bank_mask:0xf bound_ctrl:1
	v_mov_b32_dpp v186, v174 row_mirror row_mask:0xf bank_mask:0xf bound_ctrl:1
	v_mov_b32_dpp v187, v175 row_mirror row_mask:0xf bank_mask:0xf bound_ctrl:1
	v_mov_b32_dpp v166, v160 row_mirror row_mask:0xf bank_mask:0xf bound_ctrl:1
	v_mov_b32_dpp v167, v161 row_mirror row_mask:0xf bank_mask:0xf bound_ctrl:1
	v_cmp_ne_u32_e32 vcc, 0, v194
	v_lshlrev_b32_e32 v200, 5, v204
	s_and_saveexec_b64 s[6:7], vcc
	s_xor_b64 s[6:7], exec, s[6:7]
	s_cbranch_execz .LBB0_830
	v_lshlrev_b32_e32 v200, 5, v204
	v_or_b32_e32 v202, 32, v200
	v_or_b32_e32 v203, 64, v200
	v_or_b32_e32 v201, 0x60, v200
	v_or_b32_e32 v198, 0x200, v200
	v_or_b32_e32 v197, 0x220, v200
	v_or_b32_e32 v199, 0x240, v200
	v_or_b32_e32 v196, 0x260, v200
	v_or_b32_e32 v171, 0x400, v200
	v_or_b32_e32 v170, 0x420, v200
	v_or_b32_e32 v195, 0x440, v200
	v_or_b32_e32 v125, 0x460, v200
	v_or_b32_e32 v103, 0x600, v200
	v_or_b32_e32 v101, 0x620, v200
	v_or_b32_e32 v105, 0x640, v200
	v_or_b32_e32 v0, 0x660, v200

;     ...
; #pragma unroll
;     for (int mt = 0; mt < MT; ++mt)
; #pragma unroll
;         for (int nt = 0; nt < NT; ++nt) acc[mt][nt] = (f32x4){0.f, 0.f, 0.f, 0.f};
;     const unsigned loff = (unsigned)(lrow * 64 + lcg * 16);
;     const int koff = (int)((blockIdx.x >> 3) + (blockIdx.x & 7) * 4) & (KT - 1);
;     auto issue_one = [&](int kt, int b, int i) {
;         const int row = lrow + 128 * i;
;         if ((NCH % 512 == 0) || (i < NCH / 512) || row < ROWS) {
;             const int kq = (kt + koff) & (KT - 1);
;             const char* ua = (const char*)A + (size_t)((DBG & 1) ? 0 : kq) * (BM * 64);
;             const char* ub = (const char*)Bt + (size_t)((DBG & 2) ? 0 : kq) * ((size_t)ldbk * 2);
;             const char* src;
;             if (BM % 128 == 0) src = (i < BM / 128) ? (ua + i * 8192 + loff) : (ub + (i * 128 - BM) * 64 + loff);
;             else if (i == 0) src = (lrow < BM) ? (ua + loff) : (ub + loff - BM * 64);
;             else src = ub + (i * 128 - BM) * 64 + loff;
;             __builtin_amdgcn_global_load_lds((const unsigned*)src, (unsigned*)(lds + b * BUF + i * 8192 + tid * 16), 16, 0, 0);
;         }
;     };
;     auto issue = [&](int kt, int b) {
; #pragma unroll
;         for (int i = 0; i < NIT; ++i) issue_one(kt, b, i);
;     ...
;     __syncthreads();
; #pragma unroll
;     for (int d = 0; d < D; ++d) issue(d, d);
.LBB0_892:
	s_andn2_b64 vcc, exec, s[6:7]
	s_cbranch_vccnz .LBB0_662
	v_mov_b32_e32 v135, v212
	v_mov_b32_e32 v4, v212
	s_ashr_i32 s3, s2, 31
	v_ashrrev_i32_e32 v5, 6, v4
	v_lshrrev_b32_e32 v0, 30, v5
	v_add_u32_e32 v0, v5, v0
	v_ashrrev_i32_e32 v6, 2, v0
	v_lshrrev_b32_e32 v0, 4, v4
	v_sub_u32_e32 v0, 0, v0
	v_lshlrev_b32_e32 v2, 2, v4
	s_lshl_b64 s[0:1], s[2:3], 18
	v_readlane_b32 s6, v243, 56
	v_and_b32_e32 v2, 48, v2
	v_xor_b32_e32 v0, v4, v0
	v_lshlrev_b32_e32 v8, 4, v4
	s_add_u32 s8, s6, s0
	v_readlane_b32 s0, v243, 40
	v_sub_u32_e32 v7, 0, v2
	v_and_b32_e32 v2, 0xffffffc0, v8
	v_lshlrev_b32_e32 v0, 4, v0
	s_addc_u32 s9, s0, s1
	v_and_or_b32 v0, v0, 48, v2
	v_lshl_add_u64 v[130:131], s[8:9], 0, v[0:1]
	v_readlane_b32 s8, v243, 25
	v_add_u32_e32 v134, 0, v8
	v_readlane_b32 s9, v243, 26
	v_readfirstlane_b32 s7, v134
	s_mov_b32 m0, s7
	v_lshl_add_u64 v[2:3], v[130:131], 0, s[8:9]
	s_waitcnt lgkmcnt(0)
	s_barrier
	global_load_lds_dwordx4 v[2:3], off
	v_add_u32_e32 v2, 0x2000, v134
	v_readlane_b32 s8, v243, 42
	v_readfirstlane_b32 s7, v2
	s_mov_b32 m0, s7
	v_readlane_b32 s9, v243, 43
	v_add_u32_e32 v2, 0x4000, v134
	v_add_u32_e32 v9, 0xa000, v134
	v_readfirstlane_b32 s7, v2
	v_add_u32_e32 v2, 0x6000, v134
	s_mov_b32 s1, 2
	global_load_lds_dwordx4 v0, s[8:9]
	v_readlane_b32 s8, v243, 44
	s_mov_b32 m0, s7
	v_readlane_b32 s9, v243, 45
	v_readfirstlane_b32 s7, v2
	v_add_u32_e32 v2, 0x8000, v134
	s_mov_b32 s0, 4
	s_mov_b32 s6, 0
	v_lshl_add_u64 v[132:133], s[48:49], 0, v[0:1]
	global_load_lds_dwordx4 v0, s[8:9]
	v_readlane_b32 s8, v243, 46
	s_mov_b32 m0, s7
	v_readlane_b32 s9, v243, 47
	v_readfirstlane_b32 s7, v2
	s_nop 3
	global_load_lds_dwordx4 v0, s[8:9]
	v_readlane_b32 s8, v243, 48
	s_mov_b32 m0, s7
	v_readlane_b32 s9, v243, 49
	v_readfirstlane_b32 s7, v9
	s_nop 3
	global_load_lds_dwordx4 v0, s[8:9]
	v_readlane_b32 s8, v243, 5
	v_readlane_b32 s9, v243, 6
	s_mov_b32 m0, s7
	s_nop 0
	v_lshl_add_u64 v[2:3], v[130:131], 0, s[8:9]
	global_load_lds_dwordx4 v[2:3], off
	v_add_u32_e32 v2, 0xc000, v134
	v_readlane_b32 s8, v243, 50
	v_readfirstlane_b32 s7, v2
	v_add_u32_e32 v2, 0xe000, v134
	s_mov_b32 m0, s7
	v_readlane_b32 s9, v243, 51
	v_readfirstlane_b32 s7, v2
	v_bitop3_b32 v3, v4, 48, v7 bitop3:0x48
	v_add_u32_e32 v136, 0, v3
	v_lshlrev_b32_e32 v3, 6, v4
	v_and_b32_e32 v3, 0x3c0, v3
	global_load_lds_dwordx4 v0, s[8:9]
	s_mov_b32 m0, s7
	s_add_i32 s7, 0, 0x10000
	v_readlane_b32 s8, v243, 52
	v_add_u32_e32 v2, s7, v8
	v_readlane_b32 s9, v243, 53
	v_readfirstlane_b32 s7, v2
	v_lshl_or_b32 v137, v6, 12, v3
	s_nop 2
	global_load_lds_dwordx4 v0, s[8:9]
	s_mov_b32 m0, s7
	v_readlane_b32 s8, v243, 58
	v_readlane_b32 s7, v243, 31
	v_readlane_b32 s9, v243, 59
	s_nop 0
	v_add_u32_e32 v2, s7, v8
	s_nop 0
	v_readfirstlane_b32 s7, v2
	v_mul_i32_i24_e32 v2, 4, v6
	global_load_lds_dwordx4 v0, s[8:9]
	v_readlane_b32 s8, v243, 54
	s_mov_b32 m0, s7
	v_readlane_b32 s9, v243, 55
	v_sub_u32_e32 v2, v5, v2
	v_lshl_or_b32 v138, v2, 13, v3
	v_mov_b32_e32 v2, 0
	v_readlane_b32 s7, v243, 24
	v_mov_b32_e32 v3, v2
	global_load_lds_dwordx4 v0, s[8:9]
	v_mov_b32_e32 v4, v2
	v_mov_b32_e32 v5, v2
	v_mov_b32_e32 v6, v2
	v_mov_b32_e32 v7, v2
	v_mov_b32_e32 v8, v2
	v_mov_b32_e32 v9, v2
	v_mov_b32_e32 v10, v2
	v_mov_b32_e32 v11, v2
	v_mov_b32_e32 v12, v2
	v_mov_b32_e32 v13, v2
	v_mov_b32_e32 v14, v2
	v_mov_b32_e32 v15, v2
	v_mov_b32_e32 v16, v2
	v_mov_b32_e32 v17, v2
	v_mov_b32_e32 v18, v2
	v_mov_b32_e32 v19, v2
	v_mov_b32_e32 v20, v2
	v_mov_b32_e32 v21, v2
	v_mov_b32_e32 v22, v2
	v_mov_b32_e32 v23, v2
	v_mov_b32_e32 v24, v2
	v_mov_b32_e32 v25, v2
	v_mov_b32_e32 v26, v2
	v_mov_b32_e32 v27, v2
	v_mov_b32_e32 v28, v2
	v_mov_b32_e32 v29, v2
	v_mov_b32_e32 v30, v2
	v_mov_b32_e32 v31, v2
	v_mov_b32_e32 v32, v2
	v_mov_b32_e32 v33, v2
	v_mov_b32_e32 v34, v2
	v_mov_b32_e32 v35, v2
	v_mov_b32_e32 v36, v2
	v_mov_b32_e32 v37, v2
	v_mov_b32_e32 v38, v2
	v_mov_b32_e32 v39, v2
	v_mov_b32_e32 v40, v2
	v_mov_b32_e32 v41, v2
	v_mov_b32_e32 v42, v2
	v_mov_b32_e32 v43, v2
	v_mov_b32_e32 v44, v2
	v_mov_b32_e32 v45, v2
	v_mov_b32_e32 v46, v2
	v_mov_b32_e32 v47, v2
	v_mov_b32_e32 v48, v2
	v_mov_b32_e32 v49, v2
	v_mov_b32_e32 v50, v2
	v_mov_b32_e32 v51, v2
	v_mov_b32_e32 v52, v2
	v_mov_b32_e32 v53, v2
	v_mov_b32_e32 v54, v2
	v_mov_b32_e32 v55, v2
	v_mov_b32_e32 v56, v2
	v_mov_b32_e32 v57, v2
	v_mov_b32_e32 v58, v2
	v_mov_b32_e32 v59, v2
	v_mov_b32_e32 v60, v2
	v_mov_b32_e32 v61, v2
	v_mov_b32_e32 v62, v2
	v_mov_b32_e32 v63, v2
	v_mov_b32_e32 v64, v2
	v_mov_b32_e32 v65, v2
	v_mov_b32_e32 v66, v2
	v_mov_b32_e32 v67, v2
	v_mov_b32_e32 v68, v2
	v_mov_b32_e32 v69, v2
	v_mov_b32_e32 v70, v2
	v_mov_b32_e32 v71, v2
	v_mov_b32_e32 v72, v2
	v_mov_b32_e32 v73, v2
	v_mov_b32_e32 v74, v2
	v_mov_b32_e32 v75, v2
	v_mov_b32_e32 v76, v2
	v_mov_b32_e32 v77, v2
	v_mov_b32_e32 v78, v2
	v_mov_b32_e32 v79, v2
	v_mov_b32_e32 v80, v2
	v_mov_b32_e32 v81, v2
	v_mov_b32_e32 v82, v2
	v_mov_b32_e32 v83, v2
	v_mov_b32_e32 v84, v2
	v_mov_b32_e32 v85, v2
	v_mov_b32_e32 v86, v2
	v_mov_b32_e32 v87, v2
	v_mov_b32_e32 v88, v2
	v_mov_b32_e32 v89, v2
	v_mov_b32_e32 v90, v2
	v_mov_b32_e32 v91, v2
	v_mov_b32_e32 v92, v2
	v_mov_b32_e32 v93, v2
	v_mov_b32_e32 v94, v2
	v_mov_b32_e32 v95, v2
	v_mov_b32_e32 v96, v2
	v_mov_b32_e32 v97, v2
	v_mov_b32_e32 v98, v2
	v_mov_b32_e32 v99, v2
	v_mov_b32_e32 v100, v2
	v_mov_b32_e32 v101, v2
	v_mov_b32_e32 v102, v2
	v_mov_b32_e32 v103, v2
	v_mov_b32_e32 v104, v2
	v_mov_b32_e32 v105, v2
	v_mov_b32_e32 v106, v2
	v_mov_b32_e32 v107, v2
	v_mov_b32_e32 v108, v2
	v_mov_b32_e32 v109, v2
	v_mov_b32_e32 v110, v2
	v_mov_b32_e32 v111, v2
	v_mov_b32_e32 v112, v2
	v_mov_b32_e32 v113, v2
	v_mov_b32_e32 v114, v2
	v_mov_b32_e32 v115, v2
	v_mov_b32_e32 v116, v2
	v_mov_b32_e32 v117, v2
	v_mov_b32_e32 v118, v2
	v_mov_b32_e32 v119, v2
	v_mov_b32_e32 v120, v2
	v_mov_b32_e32 v121, v2
	v_mov_b32_e32 v122, v2
	v_mov_b32_e32 v123, v2
	v_mov_b32_e32 v124, v2
	v_mov_b32_e32 v125, v2
	v_mov_b32_e32 v126, v2
	v_mov_b32_e32 v127, v2
	v_mov_b32_e32 v128, v2
	v_mov_b32_e32 v129, v2
	v_readfirstlane_b32 s40, v212
	s_nop 3
	s_cmp_lt_u32 s40, 0x100
	s_cbranch_scc0 .Lpb1_c_entry
; DI f32x4 mfma16(bf16x8 a, bf16x8 b, f32x4 c) { return __builtin_amdgcn_mfma_f32_16x16x32_bf16(a, b, c, 0, 0, 0); }
; template <int N> DI void wait_vm() { asm volatile("s_waitcnt vmcnt(%0)" ::"n"(N) : "memory"); }
; DI void raw_barrier() { asm volatile("" ::: "memory"); __builtin_amdgcn_s_barrier(); asm volatile("" ::: "memory"); }
;     ...
;     auto compute = [&](int cb, bool do_issue, int ikt, int ib) {
;         const char* base = lds + cb * BUF;
;         bf16x8 af[MT], bfr[NT];
; #pragma unroll
;         for (int nt = 0; nt < NT; ++nt) {
;             const int br = BM + (nt / NTS) * (BN / NSEG) + wc * (NTS * 16) + (nt % NTS) * 16;
;             bfr[nt] = *(const bf16x8*)(base + (br + l15) * 64 + rsw);
;         }
; #pragma unroll
;         for (int mt = 0; mt < MT; ++mt) af[mt] = *(const bf16x8*)(base + (wr * WM + mt * 16 + l15) * 64 + rsw);
;         constexpr int TOT = MT * NT, PER = (TOT + NIT - 1) / NIT;
; #pragma unroll
;         for (int part = 0; part < NIT; ++part) {
; #pragma unroll
;             for (int q = 0; q < PER; ++q) {
;                 const int idx = part * PER + q;
;                 if (idx < TOT) {
;                     const int mt = idx / NT, nt = idx % NT;
;                     acc[mt][nt] = SWAP ? mfma16(bfr[nt], af[mt], acc[mt][nt]) : mfma16(af[mt], bfr[nt], acc[mt][nt]);
;                 }
;             }
;             __builtin_amdgcn_sched_barrier(0);
;             if (do_issue) issue_one(ikt, ib, part);
;             __builtin_amdgcn_sched_barrier(0);
;         }
;     };
;     __syncthreads();
; #pragma unroll
;     for (int d = 0; d < D; ++d) issue(d, d);
;     int cb = 0, ib = D;
;     for (int kt = 0; kt < KT; ++kt) {
;         if (D > 1 && kt + D - 1 < KT) wait_vm<(D - 1) * NIT>(); else wait_vm<0>();
;         raw_barrier();
;         compute(cb, kt + D < KT, kt + D, ib);
;         cb = (cb + 1 == NST) ? 0 : cb + 1;
;         ib = (ib + 1 == NST) ? 0 : ib + 1;
;     }
	s_lshl_b32 s7, s40, 5
	s_lshl_b32 s40, s40, 4
	v_add_u32_e32 v227, s40, v0
	v_readfirstlane_b32 s8, v130
	v_readfirstlane_b32 s9, v131
	v_readfirstlane_b32 s40, v0
	s_nop 3
	s_sub_u32 vcc_lo, s8, s40
	s_subb_u32 vcc_hi, s9, 0
	s_mul_i32 s8, s1, 0xa000
	s_add_u32 s8, s8, s7
	s_mov_b32 m0, s8
	s_add_i32 s40, s59, s0
	s_and_b32 s40, s40, 62
	s_lshl_b32 s8, s40, 12
	s_add_u32 s8, vcc_lo, s8
	s_addc_u32 s9, vcc_hi, 0
	s_mul_i32 s40, s40, 0x14000
	global_load_lds_dwordx4 v227, s[8:9]
	global_load_lds_dwordx4 v227, s[8:9] offset:1024
	s_add_u32 s8, s48, s40
	s_addc_u32 s9, s49, 0
	s_add_u32 m0, m0, 0x2000
	s_nop 0
	global_load_lds_dwordx4 v227, s[8:9]
	global_load_lds_dwordx4 v227, s[8:9] offset:1024
	s_add_u32 s8, s8, 0x2000
	s_addc_u32 s9, s9, 0
	s_add_u32 m0, m0, 0x2000
	s_nop 0
	global_load_lds_dwordx4 v227, s[8:9]
	global_load_lds_dwordx4 v227, s[8:9] offset:1024
	s_add_u32 s8, s8, 0x2000
	s_addc_u32 s9, s9, 0
	s_add_u32 m0, m0, 0x2000
	s_nop 0
	global_load_lds_dwordx4 v227, s[8:9]
	global_load_lds_dwordx4 v227, s[8:9] offset:1024
	s_add_u32 s8, s8, 0x2000
	s_addc_u32 s9, s9, 0
	s_add_u32 m0, m0, 0x2000
	s_nop 0
	global_load_lds_dwordx4 v227, s[8:9]
	global_load_lds_dwordx4 v227, s[8:9] offset:1024
	s_add_i32 s0, s0, 2
	s_mov_b32 s1, 0
	s_mov_b32 s6, 1
	s_waitcnt vmcnt(15)
	s_barrier
	v_add_u32_e32 v225, v136, v138
	v_add_u32_e32 v224, v136, v137
	ds_read_b128 v[144:147], v224
	ds_read_b128 v[152:155], v224 offset:1024
	ds_read_b128 v[180:183], v224 offset:2048
	ds_read_b128 v[140:143], v225 offset:8192
	ds_read_b128 v[148:151], v225 offset:9216
	ds_read_b128 v[156:159], v225 offset:10240
	ds_read_b128 v[160:163], v225 offset:11264
	ds_read_b128 v[164:167], v225 offset:12288
	ds_read_b128 v[168:171], v225 offset:13312
	ds_read_b128 v[172:175], v225 offset:14336
	ds_read_b128 v[176:179], v225 offset:15360
	ds_read_b128 v[184:187], v224 offset:3072
.Lpb1_l_loop:
	s_mul_i32 s40, s6, 0xa000
	v_add_u32_e32 v226, s40, v136
	v_add_u32_e32 v225, v226, v138
	v_add_u32_e32 v224, v226, v137
	s_waitcnt lgkmcnt(8)
	v_mfma_f32_16x16x32_bf16 v[126:129], v[140:143], v[144:147], v[126:129]
	s_waitcnt lgkmcnt(7)
	v_mfma_f32_16x16x32_bf16 v[122:125], v[148:151], v[144:147], v[122:125]
	s_waitcnt lgkmcnt(6)
	v_mfma_f32_16x16x32_bf16 v[118:121], v[156:159], v[144:147], v[118:121]
	s_waitcnt lgkmcnt(5)
	v_mfma_f32_16x16x32_bf16 v[114:117], v[160:163], v[144:147], v[114:117]
	s_waitcnt lgkmcnt(4)
	v_mfma_f32_16x16x32_bf16 v[110:113], v[164:167], v[144:147], v[110:113]
	s_waitcnt lgkmcnt(3)
	v_mfma_f32_16x16x32_bf16 v[106:109], v[168:171], v[144:147], v[106:109]
	s_waitcnt lgkmcnt(2)
	v_mfma_f32_16x16x32_bf16 v[102:105], v[172:175], v[144:147], v[102:105]
	s_waitcnt lgkmcnt(1)
	v_mfma_f32_16x16x32_bf16 v[98:101], v[176:179], v[144:147], v[98:101]
	s_waitcnt vmcnt(10) lgkmcnt(0)
	s_barrier
	ds_read_b128 v[144:147], v224
	s_mul_i32 s8, s1, 0xa000
	s_add_u32 s8, s8, s7
	s_mov_b32 m0, s8
	s_add_i32 s40, s59, s0
	s_and_b32 s40, s40, 62
	s_lshl_b32 s8, s40, 12
	s_add_u32 s8, vcc_lo, s8
	s_addc_u32 s9, vcc_hi, 0
	s_mul_i32 s40, s40, 0x14000
	global_load_lds_dwordx4 v227, s[8:9]
	global_load_lds_dwordx4 v227, s[8:9] offset:1024
	v_mfma_f32_16x16x32_bf16 v[94:97], v[140:143], v[152:155], v[94:97]
	v_mfma_f32_16x16x32_bf16 v[90:93], v[148:151], v[152:155], v[90:93]
	v_mfma_f32_16x16x32_bf16 v[86:89], v[156:159], v[152:155], v[86:89]
	v_mfma_f32_16x16x32_bf16 v[82:85], v[160:163], v[152:155], v[82:85]
	v_mfma_f32_16x16x32_bf16 v[78:81], v[164:167], v[152:155], v[78:81]
	s_add_u32 s8, s48, s40
	s_addc_u32 s9, s49, 0
	s_add_u32 m0, m0, 0x2000
	s_nop 0
	global_load_lds_dwordx4 v227, s[8:9]
	global_load_lds_dwordx4 v227, s[8:9] offset:1024
	v_mfma_f32_16x16x32_bf16 v[74:77], v[168:171], v[152:155], v[74:77]
	v_mfma_f32_16x16x32_bf16 v[70:73], v[172:175], v[152:155], v[70:73]
	v_mfma_f32_16x16x32_bf16 v[66:69], v[176:179], v[152:155], v[66:69]
	ds_read_b128 v[152:155], v224 offset:1024
	v_mfma_f32_16x16x32_bf16 v[62:65], v[140:143], v[180:183], v[62:65]
	v_mfma_f32_16x16x32_bf16 v[58:61], v[148:151], v[180:183], v[58:61]
	s_add_u32 s8, s8, 0x2000
	s_addc_u32 s9, s9, 0
	s_add_u32 m0, m0, 0x2000
	s_nop 0
	global_load_lds_dwordx4 v227, s[8:9]
	global_load_lds_dwordx4 v227, s[8:9] offset:1024
	v_mfma_f32_16x16x32_bf16 v[54:57], v[156:159], v[180:183], v[54:57]
	v_mfma_f32_16x16x32_bf16 v[50:53], v[160:163], v[180:183], v[50:53]
	v_mfma_f32_16x16x32_bf16 v[46:49], v[164:167], v[180:183], v[46:49]
	v_mfma_f32_16x16x32_bf16 v[42:45], v[168:171], v[180:183], v[42:45]
	s_add_u32 s8, s8, 0x2000
	s_addc_u32 s9, s9, 0
	s_add_u32 m0, m0, 0x2000
	s_nop 0
	global_load_lds_dwordx4 v227, s[8:9]
	global_load_lds_dwordx4 v227, s[8:9] offset:1024
	v_mfma_f32_16x16x32_bf16 v[38:41], v[172:175], v[180:183], v[38:41]
	v_mfma_f32_16x16x32_bf16 v[34:37], v[176:179], v[180:183], v[34:37]
	ds_read_b128 v[180:183], v224 offset:2048
	v_mfma_f32_16x16x32_bf16 v[30:33], v[140:143], v[184:187], v[30:33]
	ds_read_b128 v[140:143], v225 offset:8192
	v_mfma_f32_16x16x32_bf16 v[26:29], v[148:151], v[184:187], v[26:29]
	ds_read_b128 v[148:151], v225 offset:9216
	v_mfma_f32_16x16x32_bf16 v[22:25], v[156:159], v[184:187], v[22:25]
	ds_read_b128 v[156:159], v225 offset:10240
	s_add_u32 s8, s8, 0x2000
	s_addc_u32 s9, s9, 0
	s_add_u32 m0, m0, 0x2000
	s_nop 0
	global_load_lds_dwordx4 v227, s[8:9]
	global_load_lds_dwordx4 v227, s[8:9] offset:1024
	v_mfma_f32_16x16x32_bf16 v[18:21], v[160:163], v[184:187], v[18:21]
	ds_read_b128 v[160:163], v225 offset:11264
	v_mfma_f32_16x16x32_bf16 v[14:17], v[164:167], v[184:187], v[14:17]
	ds_read_b128 v[164:167], v225 offset:12288
	v_mfma_f32_16x16x32_bf16 v[10:13], v[168:171], v[184:187], v[10:13]
	ds_read_b128 v[168:171], v225 offset:13312
	v_mfma_f32_16x16x32_bf16 v[6:9], v[172:175], v[184:187], v[6:9]
	ds_read_b128 v[172:175], v225 offset:14336
	v_mfma_f32_16x16x32_bf16 v[2:5], v[176:179], v[184:187], v[2:5]
	ds_read_b128 v[176:179], v225 offset:15360
	ds_read_b128 v[184:187], v224 offset:3072
	s_add_i32 s6, s6, 1
	s_cmp_lg_u32 s6, 3
	s_cselect_b32 s6, s6, 0
	s_add_i32 s1, s1, 1
	s_cmp_lg_u32 s1, 3
	s_cselect_b32 s1, s1, 0
	s_add_i32 s0, s0, 2
	s_cmp_lg_u32 s0, 64
	s_cbranch_scc1 .Lpb1_l_loop
; DI f32x4 mfma16(bf16x8 a, bf16x8 b, f32x4 c) { return __builtin_amdgcn_mfma_f32_16x16x32_bf16(a, b, c, 0, 0, 0); }
; template <int N> DI void wait_vm() { asm volatile("s_waitcnt vmcnt(%0)" ::"n"(N) : "memory"); }
; DI void raw_barrier() { asm volatile("" ::: "memory"); __builtin_amdgcn_s_barrier(); asm volatile("" ::: "memory"); }
;     ...
;     auto compute = [&](int cb, bool do_issue, int ikt, int ib) {
;         const char* base = lds + cb * BUF;
;         bf16x8 af[MT], bfr[NT];
; #pragma unroll
;         for (int nt = 0; nt < NT; ++nt) {
;             const int br = BM + (nt / NTS) * (BN / NSEG) + wc * (NTS * 16) + (nt % NTS) * 16;
;             bfr[nt] = *(const bf16x8*)(base + (br + l15) * 64 + rsw);
;         }
; #pragma unroll
;         for (int mt = 0; mt < MT; ++mt) af[mt] = *(const bf16x8*)(base + (wr * WM + mt * 16 + l15) * 64 + rsw);
;         constexpr int TOT = MT * NT, PER = (TOT + NIT - 1) / NIT;
; #pragma unroll
;         for (int part = 0; part < NIT; ++part) {
; #pragma unroll
;             for (int q = 0; q < PER; ++q) {
;                 const int idx = part * PER + q;
;                 if (idx < TOT) {
;                     const int mt = idx / NT, nt = idx % NT;
;                     acc[mt][nt] = SWAP ? mfma16(bfr[nt], af[mt], acc[mt][nt]) : mfma16(af[mt], bfr[nt], acc[mt][nt]);
;                 }
;             }
;             __builtin_amdgcn_sched_barrier(0);
;             if (do_issue) issue_one(ikt, ib, part);
;             __builtin_amdgcn_sched_barrier(0);
;         }
;     };
;     __syncthreads();
; #pragma unroll
;     for (int d = 0; d < D; ++d) issue(d, d);
;     int cb = 0, ib = D;
;     for (int kt = 0; kt < KT; ++kt) {
;         if (D > 1 && kt + D - 1 < KT) wait_vm<(D - 1) * NIT>(); else wait_vm<0>();
;         raw_barrier();
;         compute(cb, kt + D < KT, kt + D, ib);
;         cb = (cb + 1 == NST) ? 0 : cb + 1;
;         ib = (ib + 1 == NST) ? 0 : ib + 1;
;     }
	s_waitcnt lgkmcnt(8)
	v_mfma_f32_16x16x32_bf16 v[126:129], v[140:143], v[144:147], v[126:129]
	s_waitcnt lgkmcnt(7)
	v_mfma_f32_16x16x32_bf16 v[122:125], v[148:151], v[144:147], v[122:125]
	s_waitcnt lgkmcnt(6)
	v_mfma_f32_16x16x32_bf16 v[118:121], v[156:159], v[144:147], v[118:121]
	s_waitcnt lgkmcnt(5)
	v_mfma_f32_16x16x32_bf16 v[114:117], v[160:163], v[144:147], v[114:117]
	s_waitcnt lgkmcnt(4)
	v_mfma_f32_16x16x32_bf16 v[110:113], v[164:167], v[144:147], v[110:113]
	s_waitcnt lgkmcnt(3)
	v_mfma_f32_16x16x32_bf16 v[106:109], v[168:171], v[144:147], v[106:109]
	s_waitcnt lgkmcnt(2)
	v_mfma_f32_16x16x32_bf16 v[102:105], v[172:175], v[144:147], v[102:105]
	s_waitcnt lgkmcnt(1)
	v_mfma_f32_16x16x32_bf16 v[98:101], v[176:179], v[144:147], v[98:101]
	s_waitcnt lgkmcnt(0)
	v_mfma_f32_16x16x32_bf16 v[94:97], v[140:143], v[152:155], v[94:97]
	v_mfma_f32_16x16x32_bf16 v[90:93], v[148:151], v[152:155], v[90:93]
	v_mfma_f32_16x16x32_bf16 v[86:89], v[156:159], v[152:155], v[86:89]
	v_mfma_f32_16x16x32_bf16 v[82:85], v[160:163], v[152:155], v[82:85]
	v_mfma_f32_16x16x32_bf16 v[78:81], v[164:167], v[152:155], v[78:81]
	v_mfma_f32_16x16x32_bf16 v[74:77], v[168:171], v[152:155], v[74:77]
	v_mfma_f32_16x16x32_bf16 v[70:73], v[172:175], v[152:155], v[70:73]
	v_mfma_f32_16x16x32_bf16 v[66:69], v[176:179], v[152:155], v[66:69]
	v_mfma_f32_16x16x32_bf16 v[62:65], v[140:143], v[180:183], v[62:65]
	v_mfma_f32_16x16x32_bf16 v[58:61], v[148:151], v[180:183], v[58:61]
	v_mfma_f32_16x16x32_bf16 v[54:57], v[156:159], v[180:183], v[54:57]
	v_mfma_f32_16x16x32_bf16 v[50:53], v[160:163], v[180:183], v[50:53]
	v_mfma_f32_16x16x32_bf16 v[46:49], v[164:167], v[180:183], v[46:49]
	v_mfma_f32_16x16x32_bf16 v[42:45], v[168:171], v[180:183], v[42:45]
	v_mfma_f32_16x16x32_bf16 v[38:41], v[172:175], v[180:183], v[38:41]
	v_mfma_f32_16x16x32_bf16 v[34:37], v[176:179], v[180:183], v[34:37]
	v_mfma_f32_16x16x32_bf16 v[30:33], v[140:143], v[184:187], v[30:33]
	v_mfma_f32_16x16x32_bf16 v[26:29], v[148:151], v[184:187], v[26:29]
	v_mfma_f32_16x16x32_bf16 v[22:25], v[156:159], v[184:187], v[22:25]
	v_mfma_f32_16x16x32_bf16 v[18:21], v[160:163], v[184:187], v[18:21]
	v_mfma_f32_16x16x32_bf16 v[14:17], v[164:167], v[184:187], v[14:17]
	v_mfma_f32_16x16x32_bf16 v[10:13], v[168:171], v[184:187], v[10:13]
	v_mfma_f32_16x16x32_bf16 v[6:9], v[172:175], v[184:187], v[6:9]
	v_mfma_f32_16x16x32_bf16 v[2:5], v[176:179], v[184:187], v[2:5]
	s_branch .Lpb1_join
.Lpb1_c_entry:
	s_add_i32 s0, s0, 2
	s_mov_b32 s6, 1
	s_waitcnt vmcnt(5)
	s_barrier
	v_add_u32_e32 v225, v136, v138
	v_add_u32_e32 v224, v136, v137
	ds_read_b128 v[144:147], v224
	ds_read_b128 v[152:155], v224 offset:1024
	ds_read_b128 v[180:183], v224 offset:2048
	ds_read_b128 v[140:143], v225 offset:8192
	ds_read_b128 v[148:151], v225 offset:9216
	ds_read_b128 v[156:159], v225 offset:10240
	ds_read_b128 v[160:163], v225 offset:11264
	ds_read_b128 v[164:167], v225 offset:12288
	ds_read_b128 v[168:171], v225 offset:13312
	ds_read_b128 v[172:175], v225 offset:14336
	ds_read_b128 v[176:179], v225 offset:15360
	ds_read_b128 v[184:187], v224 offset:3072
.Lpb1_c_loop:
	s_mul_i32 s40, s6, 0xa000
	v_add_u32_e32 v226, s40, v136
	v_add_u32_e32 v225, v226, v138
	v_add_u32_e32 v224, v226, v137
	s_waitcnt lgkmcnt(8)
	v_mfma_f32_16x16x32_bf16 v[126:129], v[140:143], v[144:147], v[126:129]
	s_waitcnt lgkmcnt(7)
	v_mfma_f32_16x16x32_bf16 v[122:125], v[148:151], v[144:147], v[122:125]
	s_waitcnt lgkmcnt(6)
	v_mfma_f32_16x16x32_bf16 v[118:121], v[156:159], v[144:147], v[118:121]
	s_waitcnt lgkmcnt(5)
	v_mfma_f32_16x16x32_bf16 v[114:117], v[160:163], v[144:147], v[114:117]
	s_waitcnt lgkmcnt(4)
	v_mfma_f32_16x16x32_bf16 v[110:113], v[164:167], v[144:147], v[110:113]
	s_waitcnt lgkmcnt(3)
	v_mfma_f32_16x16x32_bf16 v[106:109], v[168:171], v[144:147], v[106:109]
	s_waitcnt lgkmcnt(2)
	v_mfma_f32_16x16x32_bf16 v[102:105], v[172:175], v[144:147], v[102:105]
	s_waitcnt lgkmcnt(1)
	v_mfma_f32_16x16x32_bf16 v[98:101], v[176:179], v[144:147], v[98:101]
	s_waitcnt vmcnt(0) lgkmcnt(0)
	s_barrier
	ds_read_b128 v[144:147], v224
	v_mfma_f32_16x16x32_bf16 v[94:97], v[140:143], v[152:155], v[94:97]
	v_mfma_f32_16x16x32_bf16 v[90:93], v[148:151], v[152:155], v[90:93]
	v_mfma_f32_16x16x32_bf16 v[86:89], v[156:159], v[152:155], v[86:89]
	v_mfma_f32_16x16x32_bf16 v[82:85], v[160:163], v[152:155], v[82:85]
	v_mfma_f32_16x16x32_bf16 v[78:81], v[164:167], v[152:155], v[78:81]
	v_mfma_f32_16x16x32_bf16 v[74:77], v[168:171], v[152:155], v[74:77]
	v_mfma_f32_16x16x32_bf16 v[70:73], v[172:175], v[152:155], v[70:73]
	v_mfma_f32_16x16x32_bf16 v[66:69], v[176:179], v[152:155], v[66:69]
	ds_read_b128 v[152:155], v224 offset:1024
	v_mfma_f32_16x16x32_bf16 v[62:65], v[140:143], v[180:183], v[62:65]
	v_mfma_f32_16x16x32_bf16 v[58:61], v[148:151], v[180:183], v[58:61]
	v_mfma_f32_16x16x32_bf16 v[54:57], v[156:159], v[180:183], v[54:57]
	v_mfma_f32_16x16x32_bf16 v[50:53], v[160:163], v[180:183], v[50:53]
	v_mfma_f32_16x16x32_bf16 v[46:49], v[164:167], v[180:183], v[46:49]
	v_mfma_f32_16x16x32_bf16 v[42:45], v[168:171], v[180:183], v[42:45]
	v_mfma_f32_16x16x32_bf16 v[38:41], v[172:175], v[180:183], v[38:41]
	v_mfma_f32_16x16x32_bf16 v[34:37], v[176:179], v[180:183], v[34:37]
	ds_read_b128 v[180:183], v224 offset:2048
	v_mfma_f32_16x16x32_bf16 v[30:33], v[140:143], v[184:187], v[30:33]
	ds_read_b128 v[140:143], v225 offset:8192
	v_mfma_f32_16x16x32_bf16 v[26:29], v[148:151], v[184:187], v[26:29]
	ds_read_b128 v[148:151], v225 offset:9216
	v_mfma_f32_16x16x32_bf16 v[22:25], v[156:159], v[184:187], v[22:25]
	ds_read_b128 v[156:159], v225 offset:10240
	v_mfma_f32_16x16x32_bf16 v[18:21], v[160:163], v[184:187], v[18:21]
	ds_read_b128 v[160:163], v225 offset:11264
	v_mfma_f32_16x16x32_bf16 v[14:17], v[164:167], v[184:187], v[14:17]
	ds_read_b128 v[164:167], v225 offset:12288
	v_mfma_f32_16x16x32_bf16 v[10:13], v[168:171], v[184:187], v[10:13]
	ds_read_b128 v[168:171], v225 offset:13312
	v_mfma_f32_16x16x32_bf16 v[6:9], v[172:175], v[184:187], v[6:9]
	ds_read_b128 v[172:175], v225 offset:14336
	v_mfma_f32_16x16x32_bf16 v[2:5], v[176:179], v[184:187], v[2:5]
	ds_read_b128 v[176:179], v225 offset:15360
	ds_read_b128 v[184:187], v224 offset:3072
	s_add_i32 s6, s6, 1
	s_cmp_lg_u32 s6, 3
	s_cselect_b32 s6, s6, 0
	s_add_i32 s0, s0, 2
	s_cmp_lg_u32 s0, 64
	s_cbranch_scc1 .Lpb1_c_loop
; DI f32x4 mfma16(bf16x8 a, bf16x8 b, f32x4 c) { return __builtin_amdgcn_mfma_f32_16x16x32_bf16(a, b, c, 0, 0, 0); }
;     ...
;     auto compute = [&](int cb, bool do_issue, int ikt, int ib) {
;         const char* base = lds + cb * BUF;
;         bf16x8 af[MT], bfr[NT];
; #pragma unroll
;         for (int nt = 0; nt < NT; ++nt) {
;             const int br = BM + (nt / NTS) * (BN / NSEG) + wc * (NTS * 16) + (nt % NTS) * 16;
;             bfr[nt] = *(const bf16x8*)(base + (br + l15) * 64 + rsw);
;         }
; #pragma unroll
;         for (int mt = 0; mt < MT; ++mt) af[mt] = *(const bf16x8*)(base + (wr * WM + mt * 16 + l15) * 64 + rsw);
;         constexpr int TOT = MT * NT, PER = (TOT + NIT - 1) / NIT;
; #pragma unroll
;         for (int part = 0; part < NIT; ++part) {
; #pragma unroll
;             for (int q = 0; q < PER; ++q) {
;                 const int idx = part * PER + q;
;                 if (idx < TOT) {
;                     const int mt = idx / NT, nt = idx % NT;
;                     acc[mt][nt] = SWAP ? mfma16(bfr[nt], af[mt], acc[mt][nt]) : mfma16(af[mt], bfr[nt], acc[mt][nt]);
;                 }
;             }
;             __builtin_amdgcn_sched_barrier(0);
;             if (do_issue) issue_one(ikt, ib, part);
;             __builtin_amdgcn_sched_barrier(0);
;         }
;     };
	s_waitcnt lgkmcnt(8)
	v_mfma_f32_16x16x32_bf16 v[126:129], v[140:143], v[144:147], v[126:129]
	s_waitcnt lgkmcnt(7)
	v_mfma_f32_16x16x32_bf16 v[122:125], v[148:151], v[144:147], v[122:125]
	s_waitcnt lgkmcnt(6)
	v_mfma_f32_16x16x32_bf16 v[118:121], v[156:159], v[144:147], v[118:121]
	s_waitcnt lgkmcnt(5)
	v_mfma_f32_16x16x32_bf16 v[114:117], v[160:163], v[144:147], v[114:117]
	s_waitcnt lgkmcnt(4)
	v_mfma_f32_16x16x32_bf16 v[110:113], v[164:167], v[144:147], v[110:113]
	s_waitcnt lgkmcnt(3)
	v_mfma_f32_16x16x32_bf16 v[106:109], v[168:171], v[144:147], v[106:109]
	s_waitcnt lgkmcnt(2)
	v_mfma_f32_16x16x32_bf16 v[102:105], v[172:175], v[144:147], v[102:105]
	s_waitcnt lgkmcnt(1)
	v_mfma_f32_16x16x32_bf16 v[98:101], v[176:179], v[144:147], v[98:101]
	s_waitcnt lgkmcnt(0)
	v_mfma_f32_16x16x32_bf16 v[94:97], v[140:143], v[152:155], v[94:97]
	v_mfma_f32_16x16x32_bf16 v[90:93], v[148:151], v[152:155], v[90:93]
	v_mfma_f32_16x16x32_bf16 v[86:89], v[156:159], v[152:155], v[86:89]
	v_mfma_f32_16x16x32_bf16 v[82:85], v[160:163], v[152:155], v[82:85]
	v_mfma_f32_16x16x32_bf16 v[78:81], v[164:167], v[152:155], v[78:81]
	v_mfma_f32_16x16x32_bf16 v[74:77], v[168:171], v[152:155], v[74:77]
	v_mfma_f32_16x16x32_bf16 v[70:73], v[172:175], v[152:155], v[70:73]
	v_mfma_f32_16x16x32_bf16 v[66:69], v[176:179], v[152:155], v[66:69]
	v_mfma_f32_16x16x32_bf16 v[62:65], v[140:143], v[180:183], v[62:65]
	v_mfma_f32_16x16x32_bf16 v[58:61], v[148:151], v[180:183], v[58:61]
	v_mfma_f32_16x16x32_bf16 v[54:57], v[156:159], v[180:183], v[54:57]
	v_mfma_f32_16x16x32_bf16 v[50:53], v[160:163], v[180:183], v[50:53]
	v_mfma_f32_16x16x32_bf16 v[46:49], v[164:167], v[180:183], v[46:49]
	v_mfma_f32_16x16x32_bf16 v[42:45], v[168:171], v[180:183], v[42:45]
	v_mfma_f32_16x16x32_bf16 v[38:41], v[172:175], v[180:183], v[38:41]
	v_mfma_f32_16x16x32_bf16 v[34:37], v[176:179], v[180:183], v[34:37]
	v_mfma_f32_16x16x32_bf16 v[30:33], v[140:143], v[184:187], v[30:33]
	v_mfma_f32_16x16x32_bf16 v[26:29], v[148:151], v[184:187], v[26:29]
	v_mfma_f32_16x16x32_bf16 v[22:25], v[156:159], v[184:187], v[22:25]
	v_mfma_f32_16x16x32_bf16 v[18:21], v[160:163], v[184:187], v[18:21]
	v_mfma_f32_16x16x32_bf16 v[14:17], v[164:167], v[184:187], v[14:17]
	v_mfma_f32_16x16x32_bf16 v[10:13], v[168:171], v[184:187], v[10:13]
	v_mfma_f32_16x16x32_bf16 v[6:9], v[172:175], v[184:187], v[6:9]
	v_mfma_f32_16x16x32_bf16 v[2:5], v[176:179], v[184:187], v[2:5]
; DI unsigned pk2(float lo, float hi) { const f32x2 v = {lo, hi}; const bf16x2_t b = __builtin_convertvector(v, bf16x2_t); return __builtin_bit_cast(unsigned, b); }
; DI float silu_f(float x) { return x * sigmoid_f(x); }
; template <int N> DI void wait_vm() { asm volatile("s_waitcnt vmcnt(%0)" ::"n"(N) : "memory"); }
; DI void raw_barrier() { asm volatile("" ::: "memory"); __builtin_amdgcn_s_barrier(); asm volatile("" ::: "memory"); }
;     ...
;     for (int kt = 0; kt < KT; ++kt) {
;         if (D > 1 && kt + D - 1 < KT) wait_vm<(D - 1) * NIT>(); else wait_vm<0>();
;         raw_barrier();
;         compute(cb, kt + D < KT, kt + D, ib);
;         cb = (cb + 1 == NST) ? 0 : cb + 1;
;         ib = (ib + 1 == NST) ? 0 : ib + 1;
;     }
; DI void unit_B1(const Params& p, char* lds, int l, int chunk) {
;     ...
;     bf16_t* sgd = WS_PTR(bf16_t, OFF_SG) + (size_t)chunk * 128 * 256;
;     bf16_t* xbd = WS_PTR(bf16_t, OFF_XBB) + (size_t)(chunk >> 4) * 16 * 2048 * 16;
; #pragma unroll
;     for (int mt = 0; mt < 4; ++mt) {
;         const int tok = wr * 64 + mt * 16 + l15;
; #pragma unroll
;         for (int nt = 0; nt < 8; ++nt) {
;             f32x4 v = acc[mt][nt];
;             if (wc >= 2) {
;                 v[0] = silu_f(v[0]); v[1] = silu_f(v[1]); v[2] = silu_f(v[2]); v[3] = silu_f(v[3]);
;                 const int col = (wc & 1) * 128 + nt * 16 + quad * 4;
;                 *(u32x2*)(sgd + (size_t)tok * 256 + col) = (u32x2){pk2(v[0], v[1]), pk2(v[2], v[3])};
;             } else {
;                 const int g = (wc & 1) * 8 + nt, tb = (chunk & 15) * 128 + tok;
;                 *(u32x2*)(xbd + ((size_t)g * 2048 + tb) * 16 + quad * 4) = (u32x2){pk2(v[0], v[1]), pk2(v[2], v[3])};
.Lpb1_join:
	s_waitcnt vmcnt(5)
	s_barrier
	v_add_u32_e32 v0, v136, v138
	v_add_u32_e32 v134, v136, v137
	ds_read_b128 v[130:133], v0 offset:8192
	ds_read_b128 v[136:139], v134
	ds_read_b128 v[140:143], v0 offset:9216
	ds_read_b128 v[144:147], v134 offset:1024
	ds_read_b128 v[148:151], v0 offset:10240
	ds_read_b128 v[152:155], v0 offset:11264
	ds_read_b128 v[156:159], v0 offset:12288
	ds_read_b128 v[160:163], v0 offset:13312
	ds_read_b128 v[164:167], v0 offset:14336
	ds_read_b128 v[168:171], v0 offset:15360
	ds_read_b128 v[172:175], v134 offset:2048
	ds_read_b128 v[176:179], v134 offset:3072
	s_waitcnt lgkmcnt(0)
	v_mfma_f32_16x16x32_bf16 v[126:129], v[130:133], v[136:139], v[126:129]
	v_bfe_u32 v180, v135, 6, 2
	v_mfma_f32_16x16x32_bf16 v[122:125], v[140:143], v[136:139], v[122:125]
	v_mfma_f32_16x16x32_bf16 v[118:121], v[148:151], v[136:139], v[118:121]
	v_mfma_f32_16x16x32_bf16 v[114:117], v[152:155], v[136:139], v[114:117]
	v_mfma_f32_16x16x32_bf16 v[110:113], v[156:159], v[136:139], v[110:113]
	v_mfma_f32_16x16x32_bf16 v[106:109], v[160:163], v[136:139], v[106:109]
	v_mfma_f32_16x16x32_bf16 v[102:105], v[164:167], v[136:139], v[102:105]
	v_mfma_f32_16x16x32_bf16 v[98:101], v[168:171], v[136:139], v[98:101]
	v_mfma_f32_16x16x32_bf16 v[94:97], v[130:133], v[144:147], v[94:97]
	v_mfma_f32_16x16x32_bf16 v[90:93], v[140:143], v[144:147], v[90:93]
	v_mfma_f32_16x16x32_bf16 v[86:89], v[148:151], v[144:147], v[86:89]
	v_mfma_f32_16x16x32_bf16 v[82:85], v[152:155], v[144:147], v[82:85]
	v_mfma_f32_16x16x32_bf16 v[78:81], v[156:159], v[144:147], v[78:81]
	v_mfma_f32_16x16x32_bf16 v[74:77], v[160:163], v[144:147], v[74:77]
	v_mfma_f32_16x16x32_bf16 v[70:73], v[164:167], v[144:147], v[70:73]
	v_mfma_f32_16x16x32_bf16 v[66:69], v[168:171], v[144:147], v[66:69]
	v_mfma_f32_16x16x32_bf16 v[62:65], v[130:133], v[172:175], v[62:65]
	v_mfma_f32_16x16x32_bf16 v[58:61], v[140:143], v[172:175], v[58:61]
	v_mfma_f32_16x16x32_bf16 v[54:57], v[148:151], v[172:175], v[54:57]
	v_mfma_f32_16x16x32_bf16 v[50:53], v[152:155], v[172:175], v[50:53]
	v_mfma_f32_16x16x32_bf16 v[46:49], v[156:159], v[172:175], v[46:49]
	v_mfma_f32_16x16x32_bf16 v[42:45], v[160:163], v[172:175], v[42:45]
	v_mfma_f32_16x16x32_bf16 v[38:41], v[164:167], v[172:175], v[38:41]
	v_mfma_f32_16x16x32_bf16 v[34:37], v[168:171], v[172:175], v[34:37]
	v_mfma_f32_16x16x32_bf16 v[30:33], v[130:133], v[176:179], v[30:33]
	v_mfma_f32_16x16x32_bf16 v[26:29], v[140:143], v[176:179], v[26:29]
	v_mfma_f32_16x16x32_bf16 v[22:25], v[148:151], v[176:179], v[22:25]
	v_mfma_f32_16x16x32_bf16 v[18:21], v[152:155], v[176:179], v[18:21]
	v_mfma_f32_16x16x32_bf16 v[14:17], v[156:159], v[176:179], v[14:17]
	v_mfma_f32_16x16x32_bf16 v[10:13], v[160:163], v[176:179], v[10:13]
	v_mfma_f32_16x16x32_bf16 v[6:9], v[164:167], v[176:179], v[6:9]
	v_mfma_f32_16x16x32_bf16 v[2:5], v[168:171], v[176:179], v[2:5]
	s_waitcnt vmcnt(0)
	s_barrier
	ds_read_b128 v[130:133], v0 offset:49152
	ds_read_b128 v[136:139], v134 offset:40960
	ds_read_b128 v[140:143], v0 offset:50176
	ds_read_b128 v[144:147], v134 offset:41984
	ds_read_b128 v[148:151], v0 offset:51200
	ds_read_b128 v[152:155], v0 offset:52224
	ds_read_b128 v[156:159], v0 offset:53248
	ds_read_b128 v[160:163], v0 offset:54272
	ds_read_b128 v[164:167], v0 offset:55296
	ds_read_b128 v[168:171], v0 offset:56320
	ds_read_b128 v[172:175], v134 offset:43008
	ds_read_b128 v[176:179], v134 offset:44032
	s_waitcnt lgkmcnt(0)
	v_mfma_f32_16x16x32_bf16 v[126:129], v[130:133], v[136:139], v[126:129]
	v_and_b32_e32 v181, 15, v135
	v_mfma_f32_16x16x32_bf16 v[122:125], v[140:143], v[136:139], v[122:125]
	v_mfma_f32_16x16x32_bf16 v[118:121], v[148:151], v[136:139], v[118:121]
	v_mfma_f32_16x16x32_bf16 v[114:117], v[152:155], v[136:139], v[114:117]
	v_mfma_f32_16x16x32_bf16 v[110:113], v[156:159], v[136:139], v[110:113]
	v_mfma_f32_16x16x32_bf16 v[106:109], v[160:163], v[136:139], v[106:109]
	v_mfma_f32_16x16x32_bf16 v[102:105], v[164:167], v[136:139], v[102:105]
	v_mfma_f32_16x16x32_bf16 v[98:101], v[168:171], v[136:139], v[98:101]
	v_mfma_f32_16x16x32_bf16 v[94:97], v[130:133], v[144:147], v[94:97]
	v_mfma_f32_16x16x32_bf16 v[90:93], v[140:143], v[144:147], v[90:93]
	v_mfma_f32_16x16x32_bf16 v[86:89], v[148:151], v[144:147], v[86:89]
	v_mfma_f32_16x16x32_bf16 v[82:85], v[152:155], v[144:147], v[82:85]
	v_mfma_f32_16x16x32_bf16 v[78:81], v[156:159], v[144:147], v[78:81]
	v_mfma_f32_16x16x32_bf16 v[74:77], v[160:163], v[144:147], v[74:77]
	v_mfma_f32_16x16x32_bf16 v[70:73], v[164:167], v[144:147], v[70:73]
	v_mfma_f32_16x16x32_bf16 v[66:69], v[168:171], v[144:147], v[66:69]
	v_mfma_f32_16x16x32_bf16 v[62:65], v[130:133], v[172:175], v[62:65]
	v_mfma_f32_16x16x32_bf16 v[58:61], v[140:143], v[172:175], v[58:61]
	v_mfma_f32_16x16x32_bf16 v[54:57], v[148:151], v[172:175], v[54:57]
	v_mfma_f32_16x16x32_bf16 v[50:53], v[152:155], v[172:175], v[50:53]
	v_mfma_f32_16x16x32_bf16 v[46:49], v[156:159], v[172:175], v[46:49]
	v_mfma_f32_16x16x32_bf16 v[42:45], v[160:163], v[172:175], v[42:45]
	v_mfma_f32_16x16x32_bf16 v[38:41], v[164:167], v[172:175], v[38:41]
	v_mfma_f32_16x16x32_bf16 v[34:37], v[168:171], v[172:175], v[34:37]
	v_mfma_f32_16x16x32_bf16 v[30:33], v[130:133], v[176:179], v[30:33]
	v_mfma_f32_16x16x32_bf16 v[26:29], v[140:143], v[176:179], v[26:29]
	v_mfma_f32_16x16x32_bf16 v[22:25], v[148:151], v[176:179], v[22:25]
	v_mfma_f32_16x16x32_bf16 v[18:21], v[152:155], v[176:179], v[18:21]
	v_mfma_f32_16x16x32_bf16 v[14:17], v[156:159], v[176:179], v[14:17]
	v_mfma_f32_16x16x32_bf16 v[10:13], v[160:163], v[176:179], v[10:13]
	v_mfma_f32_16x16x32_bf16 v[6:9], v[164:167], v[176:179], v[6:9]
	v_mfma_f32_16x16x32_bf16 v[2:5], v[168:171], v[176:179], v[2:5]
	s_lshl_b64 s[0:1], s[2:3], 16
	v_readlane_b32 s3, v244, 48
	s_add_u32 s8, s3, s0
	v_readlane_b32 s0, v244, 49
	s_addc_u32 s9, s0, s1
	s_ashr_i32 s6, s2, 4
	s_ashr_i32 s7, s6, 31
	s_lshl_b64 s[0:1], s[6:7], 20
	v_readlane_b32 s3, v243, 0
	s_add_u32 s10, s3, s0
	v_readlane_b32 s0, v243, 1
	s_addc_u32 s11, s0, s1
	v_ashrrev_i32_e32 v0, 2, v135
	s_movk_i32 s0, 0xffc0
	v_and_or_b32 v134, v0, s0, v181
	s_lshl_b32 s0, s2, 7
	v_lshrrev_b32_e32 v0, 2, v135
	s_and_b32 s0, s0, 0x780
	v_and_b32_e32 v136, 12, v0
	v_lshlrev_b32_e32 v0, 1, v136
	v_add_u32_e32 v138, s0, v134
	v_cmp_gt_u32_e32 vcc, 2, v180
	v_lshlrev_b32_e32 v132, 14, v180
	v_lshl_add_u64 v[130:131], s[10:11], 0, v[0:1]
	v_ashrrev_i32_e32 v139, 31, v138
	s_waitcnt vmcnt(0)
	s_barrier
	s_and_saveexec_b64 s[10:11], vcc
	s_xor_b64 s[10:11], exec, s[10:11]
	s_cbranch_execz .LBB0_897
	v_mov_b32_e32 v133, v1
	v_cvt_pk_bf16_f32 v126, v126, v127
	v_cvt_pk_bf16_f32 v127, v128, v129
	v_lshl_add_u64 v[128:129], v[138:139], 0, v[132:133]
	v_lshlrev_b64 v[128:129], 5, v[128:129]
	v_lshl_add_u64 v[128:129], v[130:131], 0, v[128:129]
	global_store_dwordx2 v[128:129], v[126:127], off
